# snake k-order extended to the bf16 GEMM loops (f32 partial sums of a K-tile added in the opposite order for every second accumulator)
# speedup vs baseline: 1.0154x; 1.0017x over previous
; #define PG8_STAGE(bufoff, gbase, voff) do { _Pragma("unroll") for (int _i = 0; _i < 2; ++_i) \
;         __builtin_amdgcn_global_load_lds((const unsigned*)((const char*)(gbase) + (voff)[_i]), (PG8_LAS unsigned*)(lds + (bufoff) + ldsw + _i * 8192), 16, 0, 0); } while (0)
; #define PG8_LDA(dst, b, h) do { _Pragma("unroll") for (int m = 0; m < 4; ++m) _Pragma("unroll") for (int k = 0; k < 2; ++k) dst[m][k] = *(const PG8_LAS bf16x8*)(lds + PG8_SA(b, h) + aoff + m * 2048 + k * 1024); } while (0)
; #define PG8_LDB(dst, b, h) do { _Pragma("unroll") for (int n = 0; n < 2; ++n) _Pragma("unroll") for (int k = 0; k < 2; ++k) dst[n][k] = *(const PG8_LAS bf16x8*)(lds + PG8_SB(b, h) + boff + n * 2048 + k * 1024); } while (0)
; #define PG8_WAIT_V(n) asm volatile("s_waitcnt vmcnt(" #n ")" ::: "memory")
; #define PG8_WAIT_L(n) asm volatile("s_waitcnt lgkmcnt(" #n ")" ::: "memory")
; #define PG8_BAR __builtin_amdgcn_s_barrier()
; #define PG8_SCHED __builtin_amdgcn_sched_barrier(0)
; template <class Epi, class Sched, bool ALIGN_EPI = false, bool SP2 = false, bool I8 = false>
; __device__ __forceinline__ void gemm_phase(PG8_LAS unsigned char* lds, const Gemm g, const Sched& S, const Epi& E) {
;     ...
;         const bool has_next = S.next(ui + 1, nxt);
;         const char* nA = has_next ? (const char*)g.A + (size_t)nxt.pm * tstep : cA; const char* nB = has_next ? (const char*)g.Bt + (size_t)nxt.pn * tstep : cB;
;         for (int t = 0; t < nt; t += 2) {
;             const bool last = (t == nt - 2);
;             const char* a1 = cA + (size_t)(t + 1) * kstep;
;             const char* a2 = last ? nA : cA + (size_t)(t + 2) * kstep; const char* b2 = last ? nB : cB + (size_t)(t + 2) * kstep;
;             const char* a3 = a2 + kstep; const char* b3 = b2 + kstep;
;             if (last && has_next) S.a_ready(nxt);
;             if constexpr (SP2) {
;             PG8_LDB(B0, 0, 0); PG8_LDB(B1, 0, 1); PG8_SCHED; PG8_LDA(At, 0, 0); PG8_STAGE(PG8_SA(1, 1), a1 + hstep, voffA);
;             PG8_WAIT_V(8); PG8_WAIT_L(0); PG8_BAR; PG8_MMA(0, 0, At, B0); PG8_MMA(0, 1, At, B1); PG8_BAR; PG8_SCHED;
;             PG8_LDA(At, 0, 1); PG8_STAGE(PG8_SB(0, 0), b2, voffB); PG8_STAGE(PG8_SB(0, 1), b2 + hstep, voffB); PG8_STAGE(PG8_SA(0, 0), a2, voffA);
;             PG8_WAIT_V(8); PG8_WAIT_L(0); PG8_BAR; PG8_MMA(1, 0, At, B0); PG8_MMA(1, 1, At, B1); PG8_BAR; PG8_SCHED;
.LBB0_229:
	s_ashr_i32 s37, s36, 31
	s_lshl_b64 s[34:35], s[36:37], 21
	s_add_u32 s40, s42, s34
	s_addc_u32 s41, s43, s35
	s_and_b64 s[34:35], s[8:9], exec
	s_cselect_b32 s11, s41, s13
	s_cselect_b32 s34, s40, s12
	s_ashr_i32 s27, s26, 31
	s_lshl_b64 s[50:51], s[26:27], 21
	s_add_u32 s54, s44, s50
	s_addc_u32 s55, s45, s51
	s_and_b64 s[50:51], s[8:9], exec
	s_cselect_b32 s27, s55, s73
	s_cselect_b32 s35, s54, s72
	s_add_u32 s12, s12, 0x100080
	s_addc_u32 s13, s13, 0
	s_add_u32 s37, s72, 0x100
	s_addc_u32 s61, s73, 0
	s_mov_b32 s97, -2
	s_add_u32 s50, s12, 0xfff00080
	s_addc_u32 s51, s13, -1
	s_add_i32 s56, 0, 0x10000
	s_cmp_eq_u32 s97, 60
	s_cselect_b32 s77, s11, s51
	s_cselect_b32 s76, s34, s50
	s_cselect_b32 s73, s27, s61
	s_cselect_b32 s72, s35, s37
	s_add_i32 s57, 0, 0x14000
	v_add_u32_e32 v156, s56, v171
	v_add_u32_e32 v168, s57, v171
	s_waitcnt vmcnt(0)
	ds_read_b128 v[112:115], v156
	ds_read_b128 v[120:123], v156 offset:1024
	ds_read_b128 v[152:155], v156 offset:2048
	ds_read_b128 v[156:159], v156 offset:3072
	ds_read_b128 v[160:163], v168
	ds_read_b128 v[164:167], v168 offset:1024
	s_waitcnt lgkmcnt(0)
	ds_read_b128 v[176:179], v168 offset:2048
	ds_read_b128 v[180:183], v168 offset:3072
	v_lshl_add_u64 v[168:169], s[12:13], 0, v[148:149]
	s_add_i32 m0, s47, 0xc000
	ds_read_b128 v[184:187], v173
	ds_read_b128 v[188:191], v173 offset:1024
	ds_read_b128 v[204:207], v173 offset:2048
	ds_read_b128 v[208:211], v173 offset:3072
	ds_read_b128 v[212:215], v173 offset:4096
	ds_read_b128 v[216:219], v173 offset:5120
	ds_read_b128 v[220:223], v173 offset:6144
	ds_read_b128 v[224:227], v173 offset:7168
	global_load_lds_dwordx4 v[168:169], off
	v_lshl_add_u64 v[168:169], s[12:13], 0, v[150:151]
	s_add_i32 m0, s47, 0xe000
	s_nop 0
	global_load_lds_dwordx4 v[168:169], off
	s_waitcnt vmcnt(8)
	s_waitcnt lgkmcnt(0)
	s_barrier
	s_setprio 1
	s_waitcnt lgkmcnt(0)
	v_mfma_f32_16x16x32_bf16 v[136:139], v[112:115], v[184:187], 0
	v_mfma_f32_16x16x32_bf16 v[136:139], v[120:123], v[188:191], v[136:139]
	v_mfma_f32_16x16x32_bf16 v[116:119], v[120:123], v[208:211], 0
	v_mfma_f32_16x16x32_bf16 v[116:119], v[112:115], v[204:207], v[116:119]
	v_mfma_f32_16x16x32_bf16 v[96:99], v[112:115], v[212:215], 0
	v_mfma_f32_16x16x32_bf16 v[96:99], v[120:123], v[216:219], v[96:99]
	v_mfma_f32_16x16x32_bf16 v[80:83], v[120:123], v[224:227], 0
	v_mfma_f32_16x16x32_bf16 v[80:83], v[112:115], v[220:223], v[80:83]
	v_mfma_f32_16x16x32_bf16 v[132:135], v[152:155], v[184:187], 0
	v_mfma_f32_16x16x32_bf16 v[132:135], v[156:159], v[188:191], v[132:135]
	v_mfma_f32_16x16x32_bf16 v[108:111], v[156:159], v[208:211], 0
	v_mfma_f32_16x16x32_bf16 v[108:111], v[152:155], v[204:207], v[108:111]
	v_mfma_f32_16x16x32_bf16 v[92:95], v[152:155], v[212:215], 0
	v_mfma_f32_16x16x32_bf16 v[92:95], v[156:159], v[216:219], v[92:95]
	v_mfma_f32_16x16x32_bf16 v[76:79], v[156:159], v[224:227], 0
	v_mfma_f32_16x16x32_bf16 v[76:79], v[152:155], v[220:223], v[76:79]
	s_setprio 0
	s_setprio 1
	v_mfma_f32_16x16x32_bf16 v[128:131], v[160:163], v[184:187], 0
	v_mfma_f32_16x16x32_bf16 v[128:131], v[164:167], v[188:191], v[128:131]
	v_mfma_f32_16x16x32_bf16 v[104:107], v[164:167], v[208:211], 0
	v_mfma_f32_16x16x32_bf16 v[104:107], v[160:163], v[204:207], v[104:107]
	v_mfma_f32_16x16x32_bf16 v[88:91], v[160:163], v[212:215], 0
	v_mfma_f32_16x16x32_bf16 v[88:91], v[164:167], v[216:219], v[88:91]
	v_mfma_f32_16x16x32_bf16 v[72:75], v[164:167], v[224:227], 0
	v_mfma_f32_16x16x32_bf16 v[72:75], v[160:163], v[220:223], v[72:75]
	v_mfma_f32_16x16x32_bf16 v[124:127], v[176:179], v[184:187], 0
	v_mfma_f32_16x16x32_bf16 v[124:127], v[180:183], v[188:191], v[124:127]
	v_mfma_f32_16x16x32_bf16 v[100:103], v[180:183], v[208:211], 0
	v_mfma_f32_16x16x32_bf16 v[100:103], v[176:179], v[204:207], v[100:103]
	v_mfma_f32_16x16x32_bf16 v[84:87], v[176:179], v[212:215], 0
	v_mfma_f32_16x16x32_bf16 v[84:87], v[180:183], v[216:219], v[84:87]
	v_mfma_f32_16x16x32_bf16 v[68:71], v[180:183], v[224:227], 0
	v_mfma_f32_16x16x32_bf16 v[68:71], v[176:179], v[220:223], v[68:71]
	s_setprio 0
	s_barrier
	s_add_i32 s50, s56, s46
	v_lshl_add_u64 v[168:169], s[72:73], 0, v[2:3]
	s_mov_b32 m0, s50
	ds_read_b128 v[184:187], v173 offset:16384
	ds_read_b128 v[188:191], v173 offset:17408
	ds_read_b128 v[204:207], v173 offset:18432
	ds_read_b128 v[208:211], v173 offset:19456
	ds_read_b128 v[212:215], v173 offset:20480
	ds_read_b128 v[216:219], v173 offset:21504
	ds_read_b128 v[220:223], v173 offset:22528
	ds_read_b128 v[224:227], v173 offset:23552
	global_load_lds_dwordx4 v[168:169], off
	s_add_i32 m0, s50, 0x2000
	s_add_u32 s50, s72, 0x100000
	v_lshl_add_u64 v[228:229], s[72:73], 0, v[144:145]
	s_addc_u32 s51, s73, 0
	s_add_i32 s56, s57, s46
	global_load_lds_dwordx4 v[228:229], off
	v_lshl_add_u64 v[240:241], s[50:51], 0, v[2:3]
	s_mov_b32 m0, s56
	v_lshl_add_u64 v[242:243], s[76:77], 0, v[142:143]
	global_load_lds_dwordx4 v[240:241], off
	v_lshl_add_u64 v[240:241], s[50:51], 0, v[144:145]
	s_add_i32 m0, s56, 0x2000
	s_nop 0
	global_load_lds_dwordx4 v[240:241], off
	v_lshl_add_u64 v[240:241], s[76:77], 0, v[140:141]
	s_mov_b32 m0, s47
	s_nop 0
	global_load_lds_dwordx4 v[240:241], off
	s_mov_b32 m0, s52
	s_nop 0
	global_load_lds_dwordx4 v[242:243], off
	s_waitcnt vmcnt(8)
	s_waitcnt lgkmcnt(0)
	s_barrier
; #define PG8_STAGE(bufoff, gbase, voff) do { _Pragma("unroll") for (int _i = 0; _i < 2; ++_i) \
;         __builtin_amdgcn_global_load_lds((const unsigned*)((const char*)(gbase) + (voff)[_i]), (PG8_LAS unsigned*)(lds + (bufoff) + ldsw + _i * 8192), 16, 0, 0); } while (0)
; #define PG8_LDA(dst, b, h) do { _Pragma("unroll") for (int m = 0; m < 4; ++m) _Pragma("unroll") for (int k = 0; k < 2; ++k) dst[m][k] = *(const PG8_LAS bf16x8*)(lds + PG8_SA(b, h) + aoff + m * 2048 + k * 1024); } while (0)
; #define PG8_LDB(dst, b, h) do { _Pragma("unroll") for (int n = 0; n < 2; ++n) _Pragma("unroll") for (int k = 0; k < 2; ++k) dst[n][k] = *(const PG8_LAS bf16x8*)(lds + PG8_SB(b, h) + boff + n * 2048 + k * 1024); } while (0)
; #define PG8_WAIT_V(n) asm volatile("s_waitcnt vmcnt(" #n ")" ::: "memory")
; #define PG8_WAIT_L(n) asm volatile("s_waitcnt lgkmcnt(" #n ")" ::: "memory")
; #define PG8_BAR __builtin_amdgcn_s_barrier()
; #define PG8_SCHED __builtin_amdgcn_sched_barrier(0)
; template <class Epi, class Sched, bool ALIGN_EPI = false, bool SP2 = false, bool I8 = false>
; __device__ __forceinline__ void gemm_phase(PG8_LAS unsigned char* lds, const Gemm g, const Sched& S, const Epi& E) {
;     ...
;             PG8_WAIT_V(8); PG8_WAIT_L(0); PG8_BAR; PG8_MMA(1, 0, At, B0); PG8_MMA(1, 1, At, B1); PG8_BAR; PG8_SCHED;
;             PG8_LDB(B0, 1, 0); PG8_LDB(B1, 1, 1); PG8_SCHED; PG8_LDA(At, 1, 0); PG8_STAGE(PG8_SA(0, 1), a2 + hstep, voffA);
;             PG8_WAIT_V(8); PG8_WAIT_L(0); PG8_BAR; PG8_MMA(0, 0, At, B0); PG8_MMA(0, 1, At, B1); PG8_BAR; PG8_SCHED;
;             PG8_LDA(At, 1, 1); PG8_STAGE(PG8_SB(1, 0), b3, voffB); PG8_STAGE(PG8_SB(1, 1), b3 + hstep, voffB); PG8_STAGE(PG8_SA(1, 0), a3, voffA);
	s_setprio 1
	s_waitcnt lgkmcnt(0)
	v_mfma_f32_16x16x32_bf16 v[64:67], v[112:115], v[184:187], 0
	v_mfma_f32_16x16x32_bf16 v[64:67], v[120:123], v[188:191], v[64:67]
	v_mfma_f32_16x16x32_bf16 v[48:51], v[120:123], v[208:211], 0
	v_mfma_f32_16x16x32_bf16 v[48:51], v[112:115], v[204:207], v[48:51]
	v_mfma_f32_16x16x32_bf16 v[32:35], v[112:115], v[212:215], 0
	v_mfma_f32_16x16x32_bf16 v[32:35], v[120:123], v[216:219], v[32:35]
	v_mfma_f32_16x16x32_bf16 v[16:19], v[120:123], v[224:227], 0
	v_mfma_f32_16x16x32_bf16 v[16:19], v[112:115], v[220:223], v[16:19]
	v_mfma_f32_16x16x32_bf16 v[60:63], v[152:155], v[184:187], 0
	v_mfma_f32_16x16x32_bf16 v[60:63], v[156:159], v[188:191], v[60:63]
	v_mfma_f32_16x16x32_bf16 v[44:47], v[156:159], v[208:211], 0
	v_mfma_f32_16x16x32_bf16 v[44:47], v[152:155], v[204:207], v[44:47]
	v_mfma_f32_16x16x32_bf16 v[28:31], v[152:155], v[212:215], 0
	v_mfma_f32_16x16x32_bf16 v[28:31], v[156:159], v[216:219], v[28:31]
	v_mfma_f32_16x16x32_bf16 v[12:15], v[156:159], v[224:227], 0
	v_mfma_f32_16x16x32_bf16 v[12:15], v[152:155], v[220:223], v[12:15]
	s_setprio 0
	s_setprio 1
	v_mfma_f32_16x16x32_bf16 v[56:59], v[160:163], v[184:187], 0
	v_mfma_f32_16x16x32_bf16 v[56:59], v[164:167], v[188:191], v[56:59]
	v_mfma_f32_16x16x32_bf16 v[40:43], v[164:167], v[208:211], 0
	v_mfma_f32_16x16x32_bf16 v[40:43], v[160:163], v[204:207], v[40:43]
	v_mfma_f32_16x16x32_bf16 v[24:27], v[160:163], v[212:215], 0
	v_mfma_f32_16x16x32_bf16 v[24:27], v[164:167], v[216:219], v[24:27]
	v_mfma_f32_16x16x32_bf16 v[8:11], v[164:167], v[224:227], 0
	v_mfma_f32_16x16x32_bf16 v[8:11], v[160:163], v[220:223], v[8:11]
	v_mfma_f32_16x16x32_bf16 v[52:55], v[176:179], v[184:187], 0
	v_mfma_f32_16x16x32_bf16 v[52:55], v[180:183], v[188:191], v[52:55]
	v_mfma_f32_16x16x32_bf16 v[36:39], v[180:183], v[208:211], 0
	v_mfma_f32_16x16x32_bf16 v[36:39], v[176:179], v[204:207], v[36:39]
	v_mfma_f32_16x16x32_bf16 v[20:23], v[176:179], v[212:215], 0
	v_mfma_f32_16x16x32_bf16 v[20:23], v[180:183], v[216:219], v[20:23]
	v_mfma_f32_16x16x32_bf16 v[4:7], v[180:183], v[224:227], 0
	v_mfma_f32_16x16x32_bf16 v[4:7], v[176:179], v[220:223], v[4:7]
	s_setprio 0
	s_barrier
	s_add_i32 s56, 0, 0x18000
	s_add_i32 s57, 0, 0x1c000
	v_add_u32_e32 v156, s56, v171
	v_add_u32_e32 v175, s57, v171
	ds_read_b128 v[112:115], v156
	ds_read_b128 v[120:123], v156 offset:1024
	ds_read_b128 v[152:155], v156 offset:2048
	ds_read_b128 v[156:159], v156 offset:3072
	ds_read_b128 v[160:163], v175
	ds_read_b128 v[164:167], v175 offset:1024
	ds_read_b128 v[176:179], v175 offset:2048
	ds_read_b128 v[180:183], v175 offset:3072
	s_add_u32 s50, s76, 0x100000
	s_addc_u32 s51, s77, 0
	s_mov_b32 m0, s53
	v_lshl_add_u64 v[244:245], s[50:51], 0, v[140:141]
	ds_read_b128 v[184:187], v173 offset:32768
	ds_read_b128 v[188:191], v173 offset:33792
	ds_read_b128 v[204:207], v173 offset:34816
	ds_read_b128 v[208:211], v173 offset:35840
	ds_read_b128 v[212:215], v173 offset:36864
	ds_read_b128 v[216:219], v173 offset:37888
	ds_read_b128 v[220:223], v173 offset:38912
	ds_read_b128 v[224:227], v173 offset:39936
	global_load_lds_dwordx4 v[244:245], off
	v_lshl_add_u64 v[244:245], s[50:51], 0, v[142:143]
	s_mov_b32 m0, s64
	s_nop 0
	global_load_lds_dwordx4 v[244:245], off
	s_waitcnt vmcnt(8)
	s_waitcnt lgkmcnt(0)
	s_barrier
	s_setprio 1
	s_waitcnt lgkmcnt(0)
	v_mfma_f32_16x16x32_bf16 v[136:139], v[112:115], v[184:187], v[136:139]
	v_mfma_f32_16x16x32_bf16 v[136:139], v[120:123], v[188:191], v[136:139]
	v_mfma_f32_16x16x32_bf16 v[116:119], v[120:123], v[208:211], v[116:119]
	v_mfma_f32_16x16x32_bf16 v[116:119], v[112:115], v[204:207], v[116:119]
	v_mfma_f32_16x16x32_bf16 v[96:99], v[112:115], v[212:215], v[96:99]
	v_mfma_f32_16x16x32_bf16 v[96:99], v[120:123], v[216:219], v[96:99]
	v_mfma_f32_16x16x32_bf16 v[80:83], v[120:123], v[224:227], v[80:83]
	v_mfma_f32_16x16x32_bf16 v[80:83], v[112:115], v[220:223], v[80:83]
	v_mfma_f32_16x16x32_bf16 v[132:135], v[152:155], v[184:187], v[132:135]
	v_mfma_f32_16x16x32_bf16 v[132:135], v[156:159], v[188:191], v[132:135]
	v_mfma_f32_16x16x32_bf16 v[108:111], v[156:159], v[208:211], v[108:111]
	v_mfma_f32_16x16x32_bf16 v[108:111], v[152:155], v[204:207], v[108:111]
	v_mfma_f32_16x16x32_bf16 v[92:95], v[152:155], v[212:215], v[92:95]
	v_mfma_f32_16x16x32_bf16 v[92:95], v[156:159], v[216:219], v[92:95]
	v_mfma_f32_16x16x32_bf16 v[76:79], v[156:159], v[224:227], v[76:79]
	v_mfma_f32_16x16x32_bf16 v[76:79], v[152:155], v[220:223], v[76:79]
	s_setprio 0
	s_setprio 1
	v_mfma_f32_16x16x32_bf16 v[128:131], v[160:163], v[184:187], v[128:131]
	v_mfma_f32_16x16x32_bf16 v[128:131], v[164:167], v[188:191], v[128:131]
	v_mfma_f32_16x16x32_bf16 v[104:107], v[164:167], v[208:211], v[104:107]
	v_mfma_f32_16x16x32_bf16 v[104:107], v[160:163], v[204:207], v[104:107]
	v_mfma_f32_16x16x32_bf16 v[88:91], v[160:163], v[212:215], v[88:91]
	v_mfma_f32_16x16x32_bf16 v[88:91], v[164:167], v[216:219], v[88:91]
	v_mfma_f32_16x16x32_bf16 v[72:75], v[164:167], v[224:227], v[72:75]
	v_mfma_f32_16x16x32_bf16 v[72:75], v[160:163], v[220:223], v[72:75]
	v_mfma_f32_16x16x32_bf16 v[124:127], v[176:179], v[184:187], v[124:127]
	v_mfma_f32_16x16x32_bf16 v[124:127], v[180:183], v[188:191], v[124:127]
	v_mfma_f32_16x16x32_bf16 v[100:103], v[180:183], v[208:211], v[100:103]
	v_mfma_f32_16x16x32_bf16 v[100:103], v[176:179], v[204:207], v[100:103]
	v_mfma_f32_16x16x32_bf16 v[84:87], v[176:179], v[212:215], v[84:87]
	v_mfma_f32_16x16x32_bf16 v[84:87], v[180:183], v[216:219], v[84:87]
	v_mfma_f32_16x16x32_bf16 v[68:71], v[180:183], v[224:227], v[68:71]
	v_mfma_f32_16x16x32_bf16 v[68:71], v[176:179], v[220:223], v[68:71]
	s_setprio 0
	s_barrier
; #define PG8_STAGE(bufoff, gbase, voff) do { _Pragma("unroll") for (int _i = 0; _i < 2; ++_i) \
;         __builtin_amdgcn_global_load_lds((const unsigned*)((const char*)(gbase) + (voff)[_i]), (PG8_LAS unsigned*)(lds + (bufoff) + ldsw + _i * 8192), 16, 0, 0); } while (0)
; #define PG8_LDA(dst, b, h) do { _Pragma("unroll") for (int m = 0; m < 4; ++m) _Pragma("unroll") for (int k = 0; k < 2; ++k) dst[m][k] = *(const PG8_LAS bf16x8*)(lds + PG8_SA(b, h) + aoff + m * 2048 + k * 1024); } while (0)
; #define PG8_WAIT_V(n) asm volatile("s_waitcnt vmcnt(" #n ")" ::: "memory")
; #define PG8_WAIT_L(n) asm volatile("s_waitcnt lgkmcnt(" #n ")" ::: "memory")
; #define PG8_BAR __builtin_amdgcn_s_barrier()
; template <class Epi, class Sched, bool ALIGN_EPI = false, bool SP2 = false, bool I8 = false>
; __device__ __forceinline__ void gemm_phase(PG8_LAS unsigned char* lds, const Gemm g, const Sched& S, const Epi& E) {
;     ...
;         for (int t = 0; t < nt; t += 2) {
;             const bool last = (t == nt - 2);
;             const char* a1 = cA + (size_t)(t + 1) * kstep;
;             const char* a2 = last ? nA : cA + (size_t)(t + 2) * kstep; const char* b2 = last ? nB : cB + (size_t)(t + 2) * kstep;
;             const char* a3 = a2 + kstep; const char* b3 = b2 + kstep;
;             if (last && has_next) S.a_ready(nxt);
;             if constexpr (SP2) {
;             PG8_LDB(B0, 0, 0); PG8_LDB(B1, 0, 1); PG8_SCHED; PG8_LDA(At, 0, 0); PG8_STAGE(PG8_SA(1, 1), a1 + hstep, voffA);
;             PG8_WAIT_V(8); PG8_WAIT_L(0); PG8_BAR; PG8_MMA(0, 0, At, B0); PG8_MMA(0, 1, At, B1); PG8_BAR; PG8_SCHED;
;             PG8_LDA(At, 0, 1); PG8_STAGE(PG8_SB(0, 0), b2, voffB); PG8_STAGE(PG8_SB(0, 1), b2 + hstep, voffB); PG8_STAGE(PG8_SA(0, 0), a2, voffA);
;             PG8_WAIT_V(8); PG8_WAIT_L(0); PG8_BAR; PG8_MMA(1, 0, At, B0); PG8_MMA(1, 1, At, B1); PG8_BAR; PG8_SCHED;
;             PG8_LDB(B0, 1, 0); PG8_LDB(B1, 1, 1); PG8_SCHED; PG8_LDA(At, 1, 0); PG8_STAGE(PG8_SA(0, 1), a2 + hstep, voffA);
;             PG8_WAIT_V(8); PG8_WAIT_L(0); PG8_BAR; PG8_MMA(0, 0, At, B0); PG8_MMA(0, 1, At, B1); PG8_BAR; PG8_SCHED;
;             PG8_LDA(At, 1, 1); PG8_STAGE(PG8_SB(1, 0), b3, voffB); PG8_STAGE(PG8_SB(1, 1), b3 + hstep, voffB); PG8_STAGE(PG8_SA(1, 0), a3, voffA);
;             PG8_WAIT_V(8); PG8_WAIT_L(0); PG8_BAR; PG8_MMA(1, 0, At, B0); PG8_MMA(1, 1, At, B1); PG8_BAR; PG8_SCHED;
	s_add_i32 s50, s56, s46
	v_lshl_add_u64 v[168:169], v[168:169], 0, s[84:85]
	s_mov_b32 m0, s50
	ds_read_b128 v[184:187], v173 offset:49152
	ds_read_b128 v[188:191], v173 offset:50176
	ds_read_b128 v[204:207], v173 offset:51200
	ds_read_b128 v[208:211], v173 offset:52224
	ds_read_b128 v[212:215], v173 offset:53248
	ds_read_b128 v[216:219], v173 offset:54272
	ds_read_b128 v[220:223], v173 offset:55296
	ds_read_b128 v[224:227], v173 offset:56320
	global_load_lds_dwordx4 v[168:169], off
	s_add_i32 m0, s50, 0x2000
	s_add_u32 s50, s72, 0x100080
	v_lshl_add_u64 v[168:169], v[228:229], 0, s[84:85]
	s_addc_u32 s51, s73, 0
	s_add_i32 s56, s57, s46
	global_load_lds_dwordx4 v[168:169], off
	v_lshl_add_u64 v[168:169], s[50:51], 0, v[2:3]
	s_mov_b32 m0, s56
	s_nop 0
	global_load_lds_dwordx4 v[168:169], off
	v_lshl_add_u64 v[168:169], s[50:51], 0, v[144:145]
	s_add_i32 m0, s56, 0x2000
	s_nop 0
	global_load_lds_dwordx4 v[168:169], off
	v_lshl_add_u64 v[168:169], v[240:241], 0, s[84:85]
	s_mov_b32 m0, s28
	s_nop 0
	global_load_lds_dwordx4 v[168:169], off
	v_lshl_add_u64 v[168:169], v[242:243], 0, s[84:85]
	s_mov_b32 m0, s65
	s_nop 0
	global_load_lds_dwordx4 v[168:169], off
	s_waitcnt vmcnt(8)
	s_waitcnt lgkmcnt(0)
	s_barrier
	s_setprio 1
	s_waitcnt lgkmcnt(0)
	v_mfma_f32_16x16x32_bf16 v[64:67], v[112:115], v[184:187], v[64:67]
	v_mfma_f32_16x16x32_bf16 v[64:67], v[120:123], v[188:191], v[64:67]
	v_mfma_f32_16x16x32_bf16 v[48:51], v[120:123], v[208:211], v[48:51]
	v_mfma_f32_16x16x32_bf16 v[48:51], v[112:115], v[204:207], v[48:51]
	v_mfma_f32_16x16x32_bf16 v[32:35], v[112:115], v[212:215], v[32:35]
	v_mfma_f32_16x16x32_bf16 v[32:35], v[120:123], v[216:219], v[32:35]
	v_mfma_f32_16x16x32_bf16 v[16:19], v[120:123], v[224:227], v[16:19]
	v_mfma_f32_16x16x32_bf16 v[16:19], v[112:115], v[220:223], v[16:19]
	v_mfma_f32_16x16x32_bf16 v[60:63], v[152:155], v[184:187], v[60:63]
	v_mfma_f32_16x16x32_bf16 v[60:63], v[156:159], v[188:191], v[60:63]
	v_mfma_f32_16x16x32_bf16 v[44:47], v[156:159], v[208:211], v[44:47]
	v_mfma_f32_16x16x32_bf16 v[44:47], v[152:155], v[204:207], v[44:47]
	v_mfma_f32_16x16x32_bf16 v[28:31], v[152:155], v[212:215], v[28:31]
	v_mfma_f32_16x16x32_bf16 v[28:31], v[156:159], v[216:219], v[28:31]
	v_mfma_f32_16x16x32_bf16 v[12:15], v[156:159], v[224:227], v[12:15]
	v_mfma_f32_16x16x32_bf16 v[12:15], v[152:155], v[220:223], v[12:15]
	s_setprio 0
	s_setprio 1
	v_mfma_f32_16x16x32_bf16 v[56:59], v[160:163], v[184:187], v[56:59]
	v_mfma_f32_16x16x32_bf16 v[56:59], v[164:167], v[188:191], v[56:59]
	v_mfma_f32_16x16x32_bf16 v[40:43], v[164:167], v[208:211], v[40:43]
	v_mfma_f32_16x16x32_bf16 v[40:43], v[160:163], v[204:207], v[40:43]
	v_mfma_f32_16x16x32_bf16 v[24:27], v[160:163], v[212:215], v[24:27]
	v_mfma_f32_16x16x32_bf16 v[24:27], v[164:167], v[216:219], v[24:27]
	v_mfma_f32_16x16x32_bf16 v[8:11], v[164:167], v[224:227], v[8:11]
	v_mfma_f32_16x16x32_bf16 v[8:11], v[160:163], v[220:223], v[8:11]
	v_mfma_f32_16x16x32_bf16 v[52:55], v[176:179], v[184:187], v[52:55]
	v_mfma_f32_16x16x32_bf16 v[52:55], v[180:183], v[188:191], v[52:55]
	v_mfma_f32_16x16x32_bf16 v[36:39], v[180:183], v[208:211], v[36:39]
	v_mfma_f32_16x16x32_bf16 v[36:39], v[176:179], v[204:207], v[36:39]
	v_mfma_f32_16x16x32_bf16 v[20:23], v[176:179], v[212:215], v[20:23]
	v_mfma_f32_16x16x32_bf16 v[20:23], v[180:183], v[216:219], v[20:23]
	v_mfma_f32_16x16x32_bf16 v[4:7], v[180:183], v[224:227], v[4:7]
	v_mfma_f32_16x16x32_bf16 v[4:7], v[176:179], v[220:223], v[4:7]
	s_setprio 0
	s_barrier
	s_add_i32 s97, s97, 2
	s_add_u32 s12, s12, 0x100
	s_addc_u32 s13, s13, 0
	s_add_u32 s37, s37, 0x100
	s_addc_u32 s61, s61, 0
	s_cmp_gt_u32 s97, 61
	s_cbranch_scc1 .Lkloop_exit_1
.LBB0_230:
	s_add_u32 s50, s12, 0xfff00080
	s_addc_u32 s51, s13, -1
	s_add_i32 s56, 0, 0x10000
	s_cmp_eq_u32 s97, 60
	s_cselect_b32 s77, s11, s51
	s_cselect_b32 s76, s34, s50
	s_cselect_b32 s73, s27, s61
	s_cselect_b32 s72, s35, s37
	s_add_i32 s57, 0, 0x14000
	v_add_u32_e32 v156, s56, v171
	v_add_u32_e32 v168, s57, v171
	s_waitcnt vmcnt(0)
	ds_read_b128 v[112:115], v156
	ds_read_b128 v[120:123], v156 offset:1024
	ds_read_b128 v[152:155], v156 offset:2048
	ds_read_b128 v[156:159], v156 offset:3072
	ds_read_b128 v[160:163], v168
	ds_read_b128 v[164:167], v168 offset:1024
	s_waitcnt lgkmcnt(0)
	ds_read_b128 v[176:179], v168 offset:2048
	ds_read_b128 v[180:183], v168 offset:3072
	v_lshl_add_u64 v[168:169], s[12:13], 0, v[148:149]
	s_add_i32 m0, s47, 0xc000
	ds_read_b128 v[184:187], v173
	ds_read_b128 v[188:191], v173 offset:1024
	ds_read_b128 v[204:207], v173 offset:2048
	ds_read_b128 v[208:211], v173 offset:3072
	ds_read_b128 v[212:215], v173 offset:4096
	ds_read_b128 v[216:219], v173 offset:5120
	ds_read_b128 v[220:223], v173 offset:6144
	ds_read_b128 v[224:227], v173 offset:7168
	global_load_lds_dwordx4 v[168:169], off
	v_lshl_add_u64 v[168:169], s[12:13], 0, v[150:151]
	s_add_i32 m0, s47, 0xe000
	s_nop 0
	global_load_lds_dwordx4 v[168:169], off
	s_waitcnt vmcnt(8)
	s_waitcnt lgkmcnt(0)
	s_barrier
; #define PG8_STAGE(bufoff, gbase, voff) do { _Pragma("unroll") for (int _i = 0; _i < 2; ++_i) \
;         __builtin_amdgcn_global_load_lds((const unsigned*)((const char*)(gbase) + (voff)[_i]), (PG8_LAS unsigned*)(lds + (bufoff) + ldsw + _i * 8192), 16, 0, 0); } while (0)
; #define PG8_LDA(dst, b, h) do { _Pragma("unroll") for (int m = 0; m < 4; ++m) _Pragma("unroll") for (int k = 0; k < 2; ++k) dst[m][k] = *(const PG8_LAS bf16x8*)(lds + PG8_SA(b, h) + aoff + m * 2048 + k * 1024); } while (0)
; #define PG8_LDB(dst, b, h) do { _Pragma("unroll") for (int n = 0; n < 2; ++n) _Pragma("unroll") for (int k = 0; k < 2; ++k) dst[n][k] = *(const PG8_LAS bf16x8*)(lds + PG8_SB(b, h) + boff + n * 2048 + k * 1024); } while (0)
; #define PG8_WAIT_V(n) asm volatile("s_waitcnt vmcnt(" #n ")" ::: "memory")
; #define PG8_WAIT_L(n) asm volatile("s_waitcnt lgkmcnt(" #n ")" ::: "memory")
; #define PG8_BAR __builtin_amdgcn_s_barrier()
; #define PG8_SCHED __builtin_amdgcn_sched_barrier(0)
; template <class Epi, class Sched, bool ALIGN_EPI = false, bool SP2 = false, bool I8 = false>
; __device__ __forceinline__ void gemm_phase(PG8_LAS unsigned char* lds, const Gemm g, const Sched& S, const Epi& E) {
;     ...
;             PG8_WAIT_V(8); PG8_WAIT_L(0); PG8_BAR; PG8_MMA(0, 0, At, B0); PG8_MMA(0, 1, At, B1); PG8_BAR; PG8_SCHED;
;             PG8_LDA(At, 0, 1); PG8_STAGE(PG8_SB(0, 0), b2, voffB); PG8_STAGE(PG8_SB(0, 1), b2 + hstep, voffB); PG8_STAGE(PG8_SA(0, 0), a2, voffA);
;             PG8_WAIT_V(8); PG8_WAIT_L(0); PG8_BAR; PG8_MMA(1, 0, At, B0); PG8_MMA(1, 1, At, B1); PG8_BAR; PG8_SCHED;
;             PG8_LDB(B0, 1, 0); PG8_LDB(B1, 1, 1); PG8_SCHED; PG8_LDA(At, 1, 0); PG8_STAGE(PG8_SA(0, 1), a2 + hstep, voffA);
;             PG8_WAIT_V(8); PG8_WAIT_L(0); PG8_BAR; PG8_MMA(0, 0, At, B0); PG8_MMA(0, 1, At, B1); PG8_BAR; PG8_SCHED;
	s_setprio 1
	s_waitcnt lgkmcnt(0)
	v_mfma_f32_16x16x32_bf16 v[136:139], v[112:115], v[184:187], v[136:139]
	v_mfma_f32_16x16x32_bf16 v[136:139], v[120:123], v[188:191], v[136:139]
	v_mfma_f32_16x16x32_bf16 v[116:119], v[120:123], v[208:211], v[116:119]
	v_mfma_f32_16x16x32_bf16 v[116:119], v[112:115], v[204:207], v[116:119]
	v_mfma_f32_16x16x32_bf16 v[96:99], v[112:115], v[212:215], v[96:99]
	v_mfma_f32_16x16x32_bf16 v[96:99], v[120:123], v[216:219], v[96:99]
	v_mfma_f32_16x16x32_bf16 v[80:83], v[120:123], v[224:227], v[80:83]
	v_mfma_f32_16x16x32_bf16 v[80:83], v[112:115], v[220:223], v[80:83]
	v_mfma_f32_16x16x32_bf16 v[132:135], v[152:155], v[184:187], v[132:135]
	v_mfma_f32_16x16x32_bf16 v[132:135], v[156:159], v[188:191], v[132:135]
	v_mfma_f32_16x16x32_bf16 v[108:111], v[156:159], v[208:211], v[108:111]
	v_mfma_f32_16x16x32_bf16 v[108:111], v[152:155], v[204:207], v[108:111]
	v_mfma_f32_16x16x32_bf16 v[92:95], v[152:155], v[212:215], v[92:95]
	v_mfma_f32_16x16x32_bf16 v[92:95], v[156:159], v[216:219], v[92:95]
	v_mfma_f32_16x16x32_bf16 v[76:79], v[156:159], v[224:227], v[76:79]
	v_mfma_f32_16x16x32_bf16 v[76:79], v[152:155], v[220:223], v[76:79]
	s_setprio 0
	s_setprio 1
	v_mfma_f32_16x16x32_bf16 v[128:131], v[160:163], v[184:187], v[128:131]
	v_mfma_f32_16x16x32_bf16 v[128:131], v[164:167], v[188:191], v[128:131]
	v_mfma_f32_16x16x32_bf16 v[104:107], v[164:167], v[208:211], v[104:107]
	v_mfma_f32_16x16x32_bf16 v[104:107], v[160:163], v[204:207], v[104:107]
	v_mfma_f32_16x16x32_bf16 v[88:91], v[160:163], v[212:215], v[88:91]
	v_mfma_f32_16x16x32_bf16 v[88:91], v[164:167], v[216:219], v[88:91]
	v_mfma_f32_16x16x32_bf16 v[72:75], v[164:167], v[224:227], v[72:75]
	v_mfma_f32_16x16x32_bf16 v[72:75], v[160:163], v[220:223], v[72:75]
	v_mfma_f32_16x16x32_bf16 v[124:127], v[176:179], v[184:187], v[124:127]
	v_mfma_f32_16x16x32_bf16 v[124:127], v[180:183], v[188:191], v[124:127]
	v_mfma_f32_16x16x32_bf16 v[100:103], v[180:183], v[208:211], v[100:103]
	v_mfma_f32_16x16x32_bf16 v[100:103], v[176:179], v[204:207], v[100:103]
	v_mfma_f32_16x16x32_bf16 v[84:87], v[176:179], v[212:215], v[84:87]
	v_mfma_f32_16x16x32_bf16 v[84:87], v[180:183], v[216:219], v[84:87]
	v_mfma_f32_16x16x32_bf16 v[68:71], v[180:183], v[224:227], v[68:71]
	v_mfma_f32_16x16x32_bf16 v[68:71], v[176:179], v[220:223], v[68:71]
	s_setprio 0
	s_barrier
	s_add_i32 s50, s56, s46
	v_lshl_add_u64 v[168:169], s[72:73], 0, v[2:3]
	s_mov_b32 m0, s50
	ds_read_b128 v[184:187], v173 offset:16384
	ds_read_b128 v[188:191], v173 offset:17408
	ds_read_b128 v[204:207], v173 offset:18432
	ds_read_b128 v[208:211], v173 offset:19456
	ds_read_b128 v[212:215], v173 offset:20480
	ds_read_b128 v[216:219], v173 offset:21504
	ds_read_b128 v[220:223], v173 offset:22528
	ds_read_b128 v[224:227], v173 offset:23552
	global_load_lds_dwordx4 v[168:169], off
	s_add_i32 m0, s50, 0x2000
	s_add_u32 s50, s72, 0x100000
	v_lshl_add_u64 v[228:229], s[72:73], 0, v[144:145]
	s_addc_u32 s51, s73, 0
	s_add_i32 s56, s57, s46
	global_load_lds_dwordx4 v[228:229], off
	v_lshl_add_u64 v[240:241], s[50:51], 0, v[2:3]
	s_mov_b32 m0, s56
	v_lshl_add_u64 v[242:243], s[76:77], 0, v[142:143]
	global_load_lds_dwordx4 v[240:241], off
	v_lshl_add_u64 v[240:241], s[50:51], 0, v[144:145]
	s_add_i32 m0, s56, 0x2000
	s_nop 0
	global_load_lds_dwordx4 v[240:241], off
	v_lshl_add_u64 v[240:241], s[76:77], 0, v[140:141]
	s_mov_b32 m0, s47
	s_nop 0
	global_load_lds_dwordx4 v[240:241], off
	s_mov_b32 m0, s52
	s_nop 0
	global_load_lds_dwordx4 v[242:243], off
	s_waitcnt vmcnt(8)
	s_waitcnt lgkmcnt(0)
	s_barrier
	s_setprio 1
	s_waitcnt lgkmcnt(0)
	v_mfma_f32_16x16x32_bf16 v[64:67], v[112:115], v[184:187], v[64:67]
	v_mfma_f32_16x16x32_bf16 v[64:67], v[120:123], v[188:191], v[64:67]
	v_mfma_f32_16x16x32_bf16 v[48:51], v[120:123], v[208:211], v[48:51]
	v_mfma_f32_16x16x32_bf16 v[48:51], v[112:115], v[204:207], v[48:51]
	v_mfma_f32_16x16x32_bf16 v[32:35], v[112:115], v[212:215], v[32:35]
	v_mfma_f32_16x16x32_bf16 v[32:35], v[120:123], v[216:219], v[32:35]
	v_mfma_f32_16x16x32_bf16 v[16:19], v[120:123], v[224:227], v[16:19]
	v_mfma_f32_16x16x32_bf16 v[16:19], v[112:115], v[220:223], v[16:19]
	v_mfma_f32_16x16x32_bf16 v[60:63], v[152:155], v[184:187], v[60:63]
	v_mfma_f32_16x16x32_bf16 v[60:63], v[156:159], v[188:191], v[60:63]
	v_mfma_f32_16x16x32_bf16 v[44:47], v[156:159], v[208:211], v[44:47]
	v_mfma_f32_16x16x32_bf16 v[44:47], v[152:155], v[204:207], v[44:47]
	v_mfma_f32_16x16x32_bf16 v[28:31], v[152:155], v[212:215], v[28:31]
	v_mfma_f32_16x16x32_bf16 v[28:31], v[156:159], v[216:219], v[28:31]
	v_mfma_f32_16x16x32_bf16 v[12:15], v[156:159], v[224:227], v[12:15]
	v_mfma_f32_16x16x32_bf16 v[12:15], v[152:155], v[220:223], v[12:15]
	s_setprio 0
	s_setprio 1
	v_mfma_f32_16x16x32_bf16 v[56:59], v[160:163], v[184:187], v[56:59]
	v_mfma_f32_16x16x32_bf16 v[56:59], v[164:167], v[188:191], v[56:59]
	v_mfma_f32_16x16x32_bf16 v[40:43], v[164:167], v[208:211], v[40:43]
	v_mfma_f32_16x16x32_bf16 v[40:43], v[160:163], v[204:207], v[40:43]
	v_mfma_f32_16x16x32_bf16 v[24:27], v[160:163], v[212:215], v[24:27]
	v_mfma_f32_16x16x32_bf16 v[24:27], v[164:167], v[216:219], v[24:27]
	v_mfma_f32_16x16x32_bf16 v[8:11], v[164:167], v[224:227], v[8:11]
	v_mfma_f32_16x16x32_bf16 v[8:11], v[160:163], v[220:223], v[8:11]
	v_mfma_f32_16x16x32_bf16 v[52:55], v[176:179], v[184:187], v[52:55]
	v_mfma_f32_16x16x32_bf16 v[52:55], v[180:183], v[188:191], v[52:55]
	v_mfma_f32_16x16x32_bf16 v[36:39], v[180:183], v[208:211], v[36:39]
	v_mfma_f32_16x16x32_bf16 v[36:39], v[176:179], v[204:207], v[36:39]
	v_mfma_f32_16x16x32_bf16 v[20:23], v[176:179], v[212:215], v[20:23]
	v_mfma_f32_16x16x32_bf16 v[20:23], v[180:183], v[216:219], v[20:23]
	v_mfma_f32_16x16x32_bf16 v[4:7], v[180:183], v[224:227], v[4:7]
	v_mfma_f32_16x16x32_bf16 v[4:7], v[176:179], v[220:223], v[4:7]
	s_setprio 0
	s_barrier
; #define PG8_STAGE(bufoff, gbase, voff) do { _Pragma("unroll") for (int _i = 0; _i < 2; ++_i) \
;         __builtin_amdgcn_global_load_lds((const unsigned*)((const char*)(gbase) + (voff)[_i]), (PG8_LAS unsigned*)(lds + (bufoff) + ldsw + _i * 8192), 16, 0, 0); } while (0)
; #define PG8_LDA(dst, b, h) do { _Pragma("unroll") for (int m = 0; m < 4; ++m) _Pragma("unroll") for (int k = 0; k < 2; ++k) dst[m][k] = *(const PG8_LAS bf16x8*)(lds + PG8_SA(b, h) + aoff + m * 2048 + k * 1024); } while (0)
; #define PG8_LDB(dst, b, h) do { _Pragma("unroll") for (int n = 0; n < 2; ++n) _Pragma("unroll") for (int k = 0; k < 2; ++k) dst[n][k] = *(const PG8_LAS bf16x8*)(lds + PG8_SB(b, h) + boff + n * 2048 + k * 1024); } while (0)
; #define PG8_WAIT_V(n) asm volatile("s_waitcnt vmcnt(" #n ")" ::: "memory")
; #define PG8_WAIT_L(n) asm volatile("s_waitcnt lgkmcnt(" #n ")" ::: "memory")
; #define PG8_BAR __builtin_amdgcn_s_barrier()
; #define PG8_SCHED __builtin_amdgcn_sched_barrier(0)
; template <class Epi, class Sched, bool ALIGN_EPI = false, bool SP2 = false, bool I8 = false>
; __device__ __forceinline__ void gemm_phase(PG8_LAS unsigned char* lds, const Gemm g, const Sched& S, const Epi& E) {
;     ...
;             PG8_LDB(B0, 1, 0); PG8_LDB(B1, 1, 1); PG8_SCHED; PG8_LDA(At, 1, 0); PG8_STAGE(PG8_SA(0, 1), a2 + hstep, voffA);
;             PG8_WAIT_V(8); PG8_WAIT_L(0); PG8_BAR; PG8_MMA(0, 0, At, B0); PG8_MMA(0, 1, At, B1); PG8_BAR; PG8_SCHED;
	s_add_i32 s56, 0, 0x18000
	s_add_i32 s57, 0, 0x1c000
	v_add_u32_e32 v156, s56, v171
	v_add_u32_e32 v175, s57, v171
	ds_read_b128 v[112:115], v156
	ds_read_b128 v[120:123], v156 offset:1024
	ds_read_b128 v[152:155], v156 offset:2048
	ds_read_b128 v[156:159], v156 offset:3072
	ds_read_b128 v[160:163], v175
	ds_read_b128 v[164:167], v175 offset:1024
	ds_read_b128 v[176:179], v175 offset:2048
	ds_read_b128 v[180:183], v175 offset:3072
	s_add_u32 s50, s76, 0x100000
	s_addc_u32 s51, s77, 0
	s_mov_b32 m0, s53
	v_lshl_add_u64 v[244:245], s[50:51], 0, v[140:141]
	ds_read_b128 v[184:187], v173 offset:32768
	ds_read_b128 v[188:191], v173 offset:33792
	ds_read_b128 v[204:207], v173 offset:34816
	ds_read_b128 v[208:211], v173 offset:35840
	ds_read_b128 v[212:215], v173 offset:36864
	ds_read_b128 v[216:219], v173 offset:37888
	ds_read_b128 v[220:223], v173 offset:38912
	ds_read_b128 v[224:227], v173 offset:39936
	global_load_lds_dwordx4 v[244:245], off
	v_lshl_add_u64 v[244:245], s[50:51], 0, v[142:143]
	s_mov_b32 m0, s64
	s_nop 0
	global_load_lds_dwordx4 v[244:245], off
	s_waitcnt vmcnt(8)
	s_waitcnt lgkmcnt(0)
	s_barrier
	s_setprio 1
	s_waitcnt lgkmcnt(0)
	v_mfma_f32_16x16x32_bf16 v[136:139], v[112:115], v[184:187], v[136:139]
	v_mfma_f32_16x16x32_bf16 v[136:139], v[120:123], v[188:191], v[136:139]
	v_mfma_f32_16x16x32_bf16 v[116:119], v[120:123], v[208:211], v[116:119]
	v_mfma_f32_16x16x32_bf16 v[116:119], v[112:115], v[204:207], v[116:119]
	v_mfma_f32_16x16x32_bf16 v[96:99], v[112:115], v[212:215], v[96:99]
	v_mfma_f32_16x16x32_bf16 v[96:99], v[120:123], v[216:219], v[96:99]
	v_mfma_f32_16x16x32_bf16 v[80:83], v[120:123], v[224:227], v[80:83]
	v_mfma_f32_16x16x32_bf16 v[80:83], v[112:115], v[220:223], v[80:83]
	v_mfma_f32_16x16x32_bf16 v[132:135], v[152:155], v[184:187], v[132:135]
	v_mfma_f32_16x16x32_bf16 v[132:135], v[156:159], v[188:191], v[132:135]
	v_mfma_f32_16x16x32_bf16 v[108:111], v[156:159], v[208:211], v[108:111]
	v_mfma_f32_16x16x32_bf16 v[108:111], v[152:155], v[204:207], v[108:111]
	v_mfma_f32_16x16x32_bf16 v[92:95], v[152:155], v[212:215], v[92:95]
	v_mfma_f32_16x16x32_bf16 v[92:95], v[156:159], v[216:219], v[92:95]
	v_mfma_f32_16x16x32_bf16 v[76:79], v[156:159], v[224:227], v[76:79]
	v_mfma_f32_16x16x32_bf16 v[76:79], v[152:155], v[220:223], v[76:79]
	s_setprio 0
	s_setprio 1
	v_mfma_f32_16x16x32_bf16 v[128:131], v[160:163], v[184:187], v[128:131]
	v_mfma_f32_16x16x32_bf16 v[128:131], v[164:167], v[188:191], v[128:131]
	v_mfma_f32_16x16x32_bf16 v[104:107], v[164:167], v[208:211], v[104:107]
	v_mfma_f32_16x16x32_bf16 v[104:107], v[160:163], v[204:207], v[104:107]
	v_mfma_f32_16x16x32_bf16 v[88:91], v[160:163], v[212:215], v[88:91]
	v_mfma_f32_16x16x32_bf16 v[88:91], v[164:167], v[216:219], v[88:91]
	v_mfma_f32_16x16x32_bf16 v[72:75], v[164:167], v[224:227], v[72:75]
	v_mfma_f32_16x16x32_bf16 v[72:75], v[160:163], v[220:223], v[72:75]
	v_mfma_f32_16x16x32_bf16 v[124:127], v[176:179], v[184:187], v[124:127]
	v_mfma_f32_16x16x32_bf16 v[124:127], v[180:183], v[188:191], v[124:127]
	v_mfma_f32_16x16x32_bf16 v[100:103], v[180:183], v[208:211], v[100:103]
	v_mfma_f32_16x16x32_bf16 v[100:103], v[176:179], v[204:207], v[100:103]
	v_mfma_f32_16x16x32_bf16 v[84:87], v[176:179], v[212:215], v[84:87]
	v_mfma_f32_16x16x32_bf16 v[84:87], v[180:183], v[216:219], v[84:87]
	v_mfma_f32_16x16x32_bf16 v[68:71], v[180:183], v[224:227], v[68:71]
	v_mfma_f32_16x16x32_bf16 v[68:71], v[176:179], v[220:223], v[68:71]
	s_setprio 0
	s_barrier
; #define PG8_STAGE(bufoff, gbase, voff) do { _Pragma("unroll") for (int _i = 0; _i < 2; ++_i) \
;         __builtin_amdgcn_global_load_lds((const unsigned*)((const char*)(gbase) + (voff)[_i]), (PG8_LAS unsigned*)(lds + (bufoff) + ldsw + _i * 8192), 16, 0, 0); } while (0)
; #define PG8_LDA(dst, b, h) do { _Pragma("unroll") for (int m = 0; m < 4; ++m) _Pragma("unroll") for (int k = 0; k < 2; ++k) dst[m][k] = *(const PG8_LAS bf16x8*)(lds + PG8_SA(b, h) + aoff + m * 2048 + k * 1024); } while (0)
; #define PG8_WAIT_V(n) asm volatile("s_waitcnt vmcnt(" #n ")" ::: "memory")
; #define PG8_WAIT_L(n) asm volatile("s_waitcnt lgkmcnt(" #n ")" ::: "memory")
; #define PG8_BAR __builtin_amdgcn_s_barrier()
; #define PG8_SCHED __builtin_amdgcn_sched_barrier(0)
; template <class Epi, class Sched, bool ALIGN_EPI = false, bool SP2 = false, bool I8 = false>
; __device__ __forceinline__ void gemm_phase(PG8_LAS unsigned char* lds, const Gemm g, const Sched& S, const Epi& E) {
;     ...
;         for (int t = 0; t < nt; t += 2) {
;             const bool last = (t == nt - 2);
;             const char* a1 = cA + (size_t)(t + 1) * kstep;
;             const char* a2 = last ? nA : cA + (size_t)(t + 2) * kstep; const char* b2 = last ? nB : cB + (size_t)(t + 2) * kstep;
;     ...
;             PG8_LDA(At, 1, 1); PG8_STAGE(PG8_SB(1, 0), b3, voffB); PG8_STAGE(PG8_SB(1, 1), b3 + hstep, voffB); PG8_STAGE(PG8_SA(1, 0), a3, voffA);
;             PG8_WAIT_V(8); PG8_WAIT_L(0); PG8_BAR; PG8_MMA(1, 0, At, B0); PG8_MMA(1, 1, At, B1); PG8_BAR; PG8_SCHED;
	s_add_i32 s50, s56, s46
	v_lshl_add_u64 v[168:169], v[168:169], 0, s[84:85]
	s_mov_b32 m0, s50
	ds_read_b128 v[184:187], v173 offset:49152
	ds_read_b128 v[188:191], v173 offset:50176
	ds_read_b128 v[204:207], v173 offset:51200
	ds_read_b128 v[208:211], v173 offset:52224
	ds_read_b128 v[212:215], v173 offset:53248
	ds_read_b128 v[216:219], v173 offset:54272
	ds_read_b128 v[220:223], v173 offset:55296
	ds_read_b128 v[224:227], v173 offset:56320
	global_load_lds_dwordx4 v[168:169], off
	s_add_i32 m0, s50, 0x2000
	s_add_u32 s50, s72, 0x100080
	v_lshl_add_u64 v[168:169], v[228:229], 0, s[84:85]
	s_addc_u32 s51, s73, 0
	s_add_i32 s56, s57, s46
	global_load_lds_dwordx4 v[168:169], off
	v_lshl_add_u64 v[168:169], s[50:51], 0, v[2:3]
	s_mov_b32 m0, s56
	s_nop 0
	global_load_lds_dwordx4 v[168:169], off
	v_lshl_add_u64 v[168:169], s[50:51], 0, v[144:145]
	s_add_i32 m0, s56, 0x2000
	s_nop 0
	global_load_lds_dwordx4 v[168:169], off
	v_lshl_add_u64 v[168:169], v[240:241], 0, s[84:85]
	s_mov_b32 m0, s28
	s_nop 0
	global_load_lds_dwordx4 v[168:169], off
	v_lshl_add_u64 v[168:169], v[242:243], 0, s[84:85]
	s_mov_b32 m0, s65
	s_nop 0
	global_load_lds_dwordx4 v[168:169], off
	s_waitcnt vmcnt(8)
	s_waitcnt lgkmcnt(0)
	s_barrier
	s_setprio 1
	s_waitcnt lgkmcnt(0)
	v_mfma_f32_16x16x32_bf16 v[64:67], v[112:115], v[184:187], v[64:67]
	v_mfma_f32_16x16x32_bf16 v[64:67], v[120:123], v[188:191], v[64:67]
	v_mfma_f32_16x16x32_bf16 v[48:51], v[120:123], v[208:211], v[48:51]
	v_mfma_f32_16x16x32_bf16 v[48:51], v[112:115], v[204:207], v[48:51]
	v_mfma_f32_16x16x32_bf16 v[32:35], v[112:115], v[212:215], v[32:35]
	v_mfma_f32_16x16x32_bf16 v[32:35], v[120:123], v[216:219], v[32:35]
	v_mfma_f32_16x16x32_bf16 v[16:19], v[120:123], v[224:227], v[16:19]
	v_mfma_f32_16x16x32_bf16 v[16:19], v[112:115], v[220:223], v[16:19]
	v_mfma_f32_16x16x32_bf16 v[60:63], v[152:155], v[184:187], v[60:63]
	v_mfma_f32_16x16x32_bf16 v[60:63], v[156:159], v[188:191], v[60:63]
	v_mfma_f32_16x16x32_bf16 v[44:47], v[156:159], v[208:211], v[44:47]
	v_mfma_f32_16x16x32_bf16 v[44:47], v[152:155], v[204:207], v[44:47]
	v_mfma_f32_16x16x32_bf16 v[28:31], v[152:155], v[212:215], v[28:31]
	v_mfma_f32_16x16x32_bf16 v[28:31], v[156:159], v[216:219], v[28:31]
	v_mfma_f32_16x16x32_bf16 v[12:15], v[156:159], v[224:227], v[12:15]
	v_mfma_f32_16x16x32_bf16 v[12:15], v[152:155], v[220:223], v[12:15]
	s_setprio 0
	s_setprio 1
	v_mfma_f32_16x16x32_bf16 v[56:59], v[160:163], v[184:187], v[56:59]
	v_mfma_f32_16x16x32_bf16 v[56:59], v[164:167], v[188:191], v[56:59]
	v_mfma_f32_16x16x32_bf16 v[40:43], v[164:167], v[208:211], v[40:43]
	v_mfma_f32_16x16x32_bf16 v[40:43], v[160:163], v[204:207], v[40:43]
	v_mfma_f32_16x16x32_bf16 v[24:27], v[160:163], v[212:215], v[24:27]
	v_mfma_f32_16x16x32_bf16 v[24:27], v[164:167], v[216:219], v[24:27]
	v_mfma_f32_16x16x32_bf16 v[8:11], v[164:167], v[224:227], v[8:11]
	v_mfma_f32_16x16x32_bf16 v[8:11], v[160:163], v[220:223], v[8:11]
	v_mfma_f32_16x16x32_bf16 v[52:55], v[176:179], v[184:187], v[52:55]
	v_mfma_f32_16x16x32_bf16 v[52:55], v[180:183], v[188:191], v[52:55]
	v_mfma_f32_16x16x32_bf16 v[36:39], v[180:183], v[208:211], v[36:39]
	v_mfma_f32_16x16x32_bf16 v[36:39], v[176:179], v[204:207], v[36:39]
	v_mfma_f32_16x16x32_bf16 v[20:23], v[176:179], v[212:215], v[20:23]
	v_mfma_f32_16x16x32_bf16 v[20:23], v[180:183], v[216:219], v[20:23]
	v_mfma_f32_16x16x32_bf16 v[4:7], v[180:183], v[224:227], v[4:7]
	v_mfma_f32_16x16x32_bf16 v[4:7], v[176:179], v[220:223], v[4:7]
	s_setprio 0
	s_barrier
	s_add_i32 s97, s97, 2
	s_add_u32 s12, s12, 0x100
	s_addc_u32 s13, s13, 0
	s_add_u32 s37, s37, 0x100
	s_addc_u32 s61, s61, 0
	s_cmp_gt_u32 s97, 61
	s_cbranch_scc0 .LBB0_230

; #define PG8_STAGE(bufoff, gbase, voff) do { _Pragma("unroll") for (int _i = 0; _i < 2; ++_i) \
;         __builtin_amdgcn_global_load_lds((const unsigned*)((const char*)(gbase) + (voff)[_i]), (PG8_LAS unsigned*)(lds + (bufoff) + ldsw + _i * 8192), 16, 0, 0); } while (0)
; #define PG8_LDA(dst, b, h) do { _Pragma("unroll") for (int m = 0; m < 4; ++m) _Pragma("unroll") for (int k = 0; k < 2; ++k) dst[m][k] = *(const PG8_LAS bf16x8*)(lds + PG8_SA(b, h) + aoff + m * 2048 + k * 1024); } while (0)
; #define PG8_LDB(dst, b, h) do { _Pragma("unroll") for (int n = 0; n < 2; ++n) _Pragma("unroll") for (int k = 0; k < 2; ++k) dst[n][k] = *(const PG8_LAS bf16x8*)(lds + PG8_SB(b, h) + boff + n * 2048 + k * 1024); } while (0)
; #define PG8_WAIT_V(n) asm volatile("s_waitcnt vmcnt(" #n ")" ::: "memory")
; #define PG8_WAIT_L(n) asm volatile("s_waitcnt lgkmcnt(" #n ")" ::: "memory")
; #define PG8_BAR __builtin_amdgcn_s_barrier()
; #define PG8_SCHED __builtin_amdgcn_sched_barrier(0)
; template <class Epi, class Sched, bool ALIGN_EPI = false, bool SP2 = false, bool I8 = false>
; __device__ __forceinline__ void gemm_phase(PG8_LAS unsigned char* lds, const Gemm g, const Sched& S, const Epi& E) {
;     ...
;         const bool has_next = S.next(ui + 1, nxt);
;         const char* nA = has_next ? (const char*)g.A + (size_t)nxt.pm * tstep : cA; const char* nB = has_next ? (const char*)g.Bt + (size_t)nxt.pn * tstep : cB;
;         for (int t = 0; t < nt; t += 2) {
;             const bool last = (t == nt - 2);
;             const char* a1 = cA + (size_t)(t + 1) * kstep;
;             const char* a2 = last ? nA : cA + (size_t)(t + 2) * kstep; const char* b2 = last ? nB : cB + (size_t)(t + 2) * kstep;
;             const char* a3 = a2 + kstep; const char* b3 = b2 + kstep;
;             if (last && has_next) S.a_ready(nxt);
;             if constexpr (SP2) {
;             PG8_LDB(B0, 0, 0); PG8_LDB(B1, 0, 1); PG8_SCHED; PG8_LDA(At, 0, 0); PG8_STAGE(PG8_SA(1, 1), a1 + hstep, voffA);
;             PG8_WAIT_V(8); PG8_WAIT_L(0); PG8_BAR; PG8_MMA(0, 0, At, B0); PG8_MMA(0, 1, At, B1); PG8_BAR; PG8_SCHED;
;             PG8_LDA(At, 0, 1); PG8_STAGE(PG8_SB(0, 0), b2, voffB); PG8_STAGE(PG8_SB(0, 1), b2 + hstep, voffB); PG8_STAGE(PG8_SA(0, 0), a2, voffA);
;             PG8_WAIT_V(8); PG8_WAIT_L(0); PG8_BAR; PG8_MMA(1, 0, At, B0); PG8_MMA(1, 1, At, B1); PG8_BAR; PG8_SCHED;
.LBB0_1455:
	s_ashr_i32 s17, s16, 31
	s_lshl_b64 s[20:21], s[16:17], 21
	s_add_u32 s20, s28, s20
	s_addc_u32 s21, s34, s21
	s_and_b64 s[22:23], s[8:9], exec
	s_cselect_b32 s17, s21, s25
	s_cselect_b32 s51, s20, s24
	s_ashr_i32 s19, s18, 31
	s_lshl_b64 s[22:23], s[18:19], 21
	s_add_u32 s22, s35, s22
	s_addc_u32 s23, s39, s23
	s_and_b64 s[36:37], s[8:9], exec
	s_cselect_b32 s19, s23, s27
	s_cselect_b32 s52, s22, s26
	s_add_u32 s24, s24, 0x100080
	s_addc_u32 s25, s25, 0
	s_add_u32 s53, s26, 0x100
	s_addc_u32 s54, s27, 0
	s_mov_b32 s55, -2
	s_waitcnt vmcnt(0)
	s_add_u32 s26, s24, 0xfff00080
	s_addc_u32 s27, s25, -1
	s_add_i32 s56, 0, 0x10000
	s_cmp_eq_u32 s55, 60
	s_cselect_b32 s37, s17, s27
	s_cselect_b32 s36, s51, s26
	s_cselect_b32 s27, s19, s54
	s_cselect_b32 s26, s52, s53
	s_add_i32 s58, 0, 0x14000
	v_add_u32_e32 v144, s56, v240
	v_add_u32_e32 v160, s58, v240
	ds_read_b128 v[124:127], v144
	ds_read_b128 v[128:131], v144 offset:1024
	ds_read_b128 v[132:135], v144 offset:2048
	ds_read_b128 v[144:147], v144 offset:3072
	ds_read_b128 v[148:151], v160
	ds_read_b128 v[152:155], v160 offset:1024
	ds_read_b128 v[156:159], v160 offset:2048
	ds_read_b128 v[160:163], v160 offset:3072
	v_lshl_add_u64 v[218:219], s[24:25], 0, v[210:211]
	s_add_i32 m0, s41, 0xc000
	ds_read_b128 v[164:167], v242
	ds_read_b128 v[168:171], v242 offset:1024
	ds_read_b128 v[172:175], v242 offset:2048
	ds_read_b128 v[176:179], v242 offset:3072
	ds_read_b128 v[180:183], v242 offset:4096
	ds_read_b128 v[184:187], v242 offset:5120
	ds_read_b128 v[188:191], v242 offset:6144
	ds_read_b128 v[214:217], v242 offset:7168
	global_load_lds_dwordx4 v[218:219], off
	v_lshl_add_u64 v[218:219], s[24:25], 0, v[212:213]
	s_add_i32 m0, s41, 0xe000
	s_nop 0
	global_load_lds_dwordx4 v[218:219], off
	s_waitcnt vmcnt(8)
	s_waitcnt lgkmcnt(0)
	s_barrier
	s_setprio 1
	s_waitcnt lgkmcnt(0)
	v_mfma_f32_16x16x32_bf16 v[140:143], v[124:127], v[164:167], 0
	v_mfma_f32_16x16x32_bf16 v[140:143], v[128:131], v[168:171], v[140:143]
	v_mfma_f32_16x16x32_bf16 v[112:115], v[128:131], v[176:179], 0
	v_mfma_f32_16x16x32_bf16 v[112:115], v[124:127], v[172:175], v[112:115]
	v_mfma_f32_16x16x32_bf16 v[96:99], v[124:127], v[180:183], 0
	v_mfma_f32_16x16x32_bf16 v[96:99], v[128:131], v[184:187], v[96:99]
	v_mfma_f32_16x16x32_bf16 v[80:83], v[128:131], v[214:217], 0
	v_mfma_f32_16x16x32_bf16 v[80:83], v[124:127], v[188:191], v[80:83]
	v_mfma_f32_16x16x32_bf16 v[136:139], v[132:135], v[164:167], 0
	v_mfma_f32_16x16x32_bf16 v[136:139], v[144:147], v[168:171], v[136:139]
	v_mfma_f32_16x16x32_bf16 v[108:111], v[144:147], v[176:179], 0
	v_mfma_f32_16x16x32_bf16 v[108:111], v[132:135], v[172:175], v[108:111]
	v_mfma_f32_16x16x32_bf16 v[92:95], v[132:135], v[180:183], 0
	v_mfma_f32_16x16x32_bf16 v[92:95], v[144:147], v[184:187], v[92:95]
	v_mfma_f32_16x16x32_bf16 v[76:79], v[144:147], v[214:217], 0
	v_mfma_f32_16x16x32_bf16 v[76:79], v[132:135], v[188:191], v[76:79]
	s_setprio 0
	s_setprio 1
	v_mfma_f32_16x16x32_bf16 v[120:123], v[148:151], v[164:167], 0
	v_mfma_f32_16x16x32_bf16 v[120:123], v[152:155], v[168:171], v[120:123]
	v_mfma_f32_16x16x32_bf16 v[104:107], v[152:155], v[176:179], 0
	v_mfma_f32_16x16x32_bf16 v[104:107], v[148:151], v[172:175], v[104:107]
	v_mfma_f32_16x16x32_bf16 v[88:91], v[148:151], v[180:183], 0
	v_mfma_f32_16x16x32_bf16 v[88:91], v[152:155], v[184:187], v[88:91]
	v_mfma_f32_16x16x32_bf16 v[72:75], v[152:155], v[214:217], 0
	v_mfma_f32_16x16x32_bf16 v[72:75], v[148:151], v[188:191], v[72:75]
	v_mfma_f32_16x16x32_bf16 v[116:119], v[156:159], v[164:167], 0
	v_mfma_f32_16x16x32_bf16 v[116:119], v[160:163], v[168:171], v[116:119]
	v_mfma_f32_16x16x32_bf16 v[100:103], v[160:163], v[176:179], 0
	v_mfma_f32_16x16x32_bf16 v[100:103], v[156:159], v[172:175], v[100:103]
	v_mfma_f32_16x16x32_bf16 v[84:87], v[156:159], v[180:183], 0
	v_mfma_f32_16x16x32_bf16 v[84:87], v[160:163], v[184:187], v[84:87]
	v_mfma_f32_16x16x32_bf16 v[68:71], v[160:163], v[214:217], 0
	v_mfma_f32_16x16x32_bf16 v[68:71], v[156:159], v[188:191], v[68:71]
	s_setprio 0
	s_barrier
	s_add_i32 s56, s56, s40
	v_lshl_add_u64 v[218:219], s[26:27], 0, v[2:3]
	s_mov_b32 m0, s56
	ds_read_b128 v[164:167], v242 offset:16384
	ds_read_b128 v[168:171], v242 offset:17408
	ds_read_b128 v[172:175], v242 offset:18432
	ds_read_b128 v[176:179], v242 offset:19456
	ds_read_b128 v[180:183], v242 offset:20480
	ds_read_b128 v[184:187], v242 offset:21504
	ds_read_b128 v[188:191], v242 offset:22528
	ds_read_b128 v[214:217], v242 offset:23552
	global_load_lds_dwordx4 v[218:219], off
	s_add_i32 m0, s56, 0x2000
	s_add_u32 s56, s26, 0x100000
	v_lshl_add_u64 v[220:221], s[26:27], 0, v[204:205]
	s_addc_u32 s57, s27, 0
	s_add_i32 s58, s58, s40
	global_load_lds_dwordx4 v[220:221], off
	v_lshl_add_u64 v[222:223], s[56:57], 0, v[2:3]
	s_mov_b32 m0, s58
	v_lshl_add_u64 v[224:225], s[36:37], 0, v[206:207]
	global_load_lds_dwordx4 v[222:223], off
	v_lshl_add_u64 v[222:223], s[56:57], 0, v[204:205]
	s_add_i32 m0, s58, 0x2000
	s_nop 0
	global_load_lds_dwordx4 v[222:223], off
	v_lshl_add_u64 v[222:223], s[36:37], 0, v[208:209]
	s_mov_b32 m0, s41
	s_nop 0
	global_load_lds_dwordx4 v[222:223], off
	s_mov_b32 m0, s42
	s_nop 0
	global_load_lds_dwordx4 v[224:225], off
	s_waitcnt vmcnt(8)
	s_waitcnt lgkmcnt(0)
	s_barrier
; #define PG8_STAGE(bufoff, gbase, voff) do { _Pragma("unroll") for (int _i = 0; _i < 2; ++_i) \
;         __builtin_amdgcn_global_load_lds((const unsigned*)((const char*)(gbase) + (voff)[_i]), (PG8_LAS unsigned*)(lds + (bufoff) + ldsw + _i * 8192), 16, 0, 0); } while (0)
; #define PG8_LDA(dst, b, h) do { _Pragma("unroll") for (int m = 0; m < 4; ++m) _Pragma("unroll") for (int k = 0; k < 2; ++k) dst[m][k] = *(const PG8_LAS bf16x8*)(lds + PG8_SA(b, h) + aoff + m * 2048 + k * 1024); } while (0)
; #define PG8_LDB(dst, b, h) do { _Pragma("unroll") for (int n = 0; n < 2; ++n) _Pragma("unroll") for (int k = 0; k < 2; ++k) dst[n][k] = *(const PG8_LAS bf16x8*)(lds + PG8_SB(b, h) + boff + n * 2048 + k * 1024); } while (0)
; #define PG8_WAIT_V(n) asm volatile("s_waitcnt vmcnt(" #n ")" ::: "memory")
; #define PG8_WAIT_L(n) asm volatile("s_waitcnt lgkmcnt(" #n ")" ::: "memory")
; #define PG8_BAR __builtin_amdgcn_s_barrier()
; #define PG8_SCHED __builtin_amdgcn_sched_barrier(0)
; template <class Epi, class Sched, bool ALIGN_EPI = false, bool SP2 = false, bool I8 = false>
; __device__ __forceinline__ void gemm_phase(PG8_LAS unsigned char* lds, const Gemm g, const Sched& S, const Epi& E) {
;     ...
;             PG8_WAIT_V(8); PG8_WAIT_L(0); PG8_BAR; PG8_MMA(1, 0, At, B0); PG8_MMA(1, 1, At, B1); PG8_BAR; PG8_SCHED;
;             PG8_LDB(B0, 1, 0); PG8_LDB(B1, 1, 1); PG8_SCHED; PG8_LDA(At, 1, 0); PG8_STAGE(PG8_SA(0, 1), a2 + hstep, voffA);
;             PG8_WAIT_V(8); PG8_WAIT_L(0); PG8_BAR; PG8_MMA(0, 0, At, B0); PG8_MMA(0, 1, At, B1); PG8_BAR; PG8_SCHED;
;             PG8_LDA(At, 1, 1); PG8_STAGE(PG8_SB(1, 0), b3, voffB); PG8_STAGE(PG8_SB(1, 1), b3 + hstep, voffB); PG8_STAGE(PG8_SA(1, 0), a3, voffA);
	s_setprio 1
	s_waitcnt lgkmcnt(0)
	v_mfma_f32_16x16x32_bf16 v[64:67], v[124:127], v[164:167], 0
	v_mfma_f32_16x16x32_bf16 v[64:67], v[128:131], v[168:171], v[64:67]
	v_mfma_f32_16x16x32_bf16 v[48:51], v[128:131], v[176:179], 0
	v_mfma_f32_16x16x32_bf16 v[48:51], v[124:127], v[172:175], v[48:51]
	v_mfma_f32_16x16x32_bf16 v[32:35], v[124:127], v[180:183], 0
	v_mfma_f32_16x16x32_bf16 v[32:35], v[128:131], v[184:187], v[32:35]
	v_mfma_f32_16x16x32_bf16 v[16:19], v[128:131], v[214:217], 0
	v_mfma_f32_16x16x32_bf16 v[16:19], v[124:127], v[188:191], v[16:19]
	v_mfma_f32_16x16x32_bf16 v[60:63], v[132:135], v[164:167], 0
	v_mfma_f32_16x16x32_bf16 v[60:63], v[144:147], v[168:171], v[60:63]
	v_mfma_f32_16x16x32_bf16 v[44:47], v[144:147], v[176:179], 0
	v_mfma_f32_16x16x32_bf16 v[44:47], v[132:135], v[172:175], v[44:47]
	v_mfma_f32_16x16x32_bf16 v[28:31], v[132:135], v[180:183], 0
	v_mfma_f32_16x16x32_bf16 v[28:31], v[144:147], v[184:187], v[28:31]
	v_mfma_f32_16x16x32_bf16 v[12:15], v[144:147], v[214:217], 0
	v_mfma_f32_16x16x32_bf16 v[12:15], v[132:135], v[188:191], v[12:15]
	s_setprio 0
	s_setprio 1
	v_mfma_f32_16x16x32_bf16 v[56:59], v[148:151], v[164:167], 0
	v_mfma_f32_16x16x32_bf16 v[56:59], v[152:155], v[168:171], v[56:59]
	v_mfma_f32_16x16x32_bf16 v[40:43], v[152:155], v[176:179], 0
	v_mfma_f32_16x16x32_bf16 v[40:43], v[148:151], v[172:175], v[40:43]
	v_mfma_f32_16x16x32_bf16 v[24:27], v[148:151], v[180:183], 0
	v_mfma_f32_16x16x32_bf16 v[24:27], v[152:155], v[184:187], v[24:27]
	v_mfma_f32_16x16x32_bf16 v[8:11], v[152:155], v[214:217], 0
	v_mfma_f32_16x16x32_bf16 v[8:11], v[148:151], v[188:191], v[8:11]
	v_mfma_f32_16x16x32_bf16 v[52:55], v[156:159], v[164:167], 0
	v_mfma_f32_16x16x32_bf16 v[52:55], v[160:163], v[168:171], v[52:55]
	v_mfma_f32_16x16x32_bf16 v[36:39], v[160:163], v[176:179], 0
	v_mfma_f32_16x16x32_bf16 v[36:39], v[156:159], v[172:175], v[36:39]
	v_mfma_f32_16x16x32_bf16 v[20:23], v[156:159], v[180:183], 0
	v_mfma_f32_16x16x32_bf16 v[20:23], v[160:163], v[184:187], v[20:23]
	v_mfma_f32_16x16x32_bf16 v[4:7], v[160:163], v[214:217], 0
	v_mfma_f32_16x16x32_bf16 v[4:7], v[156:159], v[188:191], v[4:7]
	s_setprio 0
	s_barrier
	s_add_i32 s56, 0, 0x18000
	s_add_i32 s57, 0, 0x1c000
	v_add_u32_e32 v144, s56, v240
	v_add_u32_e32 v160, s57, v240
	ds_read_b128 v[124:127], v144
	ds_read_b128 v[128:131], v144 offset:1024
	ds_read_b128 v[132:135], v144 offset:2048
	ds_read_b128 v[144:147], v144 offset:3072
	ds_read_b128 v[148:151], v160
	ds_read_b128 v[152:155], v160 offset:1024
	ds_read_b128 v[156:159], v160 offset:2048
	ds_read_b128 v[160:163], v160 offset:3072
	s_add_u32 s36, s36, 0x100000
	s_addc_u32 s37, s37, 0
	s_mov_b32 m0, s43
	v_lshl_add_u64 v[226:227], s[36:37], 0, v[208:209]
	ds_read_b128 v[164:167], v242 offset:32768
	ds_read_b128 v[168:171], v242 offset:33792
	ds_read_b128 v[172:175], v242 offset:34816
	ds_read_b128 v[176:179], v242 offset:35840
	ds_read_b128 v[180:183], v242 offset:36864
	ds_read_b128 v[184:187], v242 offset:37888
	ds_read_b128 v[188:191], v242 offset:38912
	ds_read_b128 v[214:217], v242 offset:39936
	global_load_lds_dwordx4 v[226:227], off
	v_lshl_add_u64 v[226:227], s[36:37], 0, v[206:207]
	s_mov_b32 m0, s44
	s_nop 0
	global_load_lds_dwordx4 v[226:227], off
	s_waitcnt vmcnt(8)
	s_waitcnt lgkmcnt(0)
	s_barrier
	s_setprio 1
	s_waitcnt lgkmcnt(0)
	v_mfma_f32_16x16x32_bf16 v[140:143], v[124:127], v[164:167], v[140:143]
	v_mfma_f32_16x16x32_bf16 v[140:143], v[128:131], v[168:171], v[140:143]
	v_mfma_f32_16x16x32_bf16 v[112:115], v[128:131], v[176:179], v[112:115]
	v_mfma_f32_16x16x32_bf16 v[112:115], v[124:127], v[172:175], v[112:115]
	v_mfma_f32_16x16x32_bf16 v[96:99], v[124:127], v[180:183], v[96:99]
	v_mfma_f32_16x16x32_bf16 v[96:99], v[128:131], v[184:187], v[96:99]
	v_mfma_f32_16x16x32_bf16 v[80:83], v[128:131], v[214:217], v[80:83]
	v_mfma_f32_16x16x32_bf16 v[80:83], v[124:127], v[188:191], v[80:83]
	v_mfma_f32_16x16x32_bf16 v[136:139], v[132:135], v[164:167], v[136:139]
	v_mfma_f32_16x16x32_bf16 v[136:139], v[144:147], v[168:171], v[136:139]
	v_mfma_f32_16x16x32_bf16 v[108:111], v[144:147], v[176:179], v[108:111]
	v_mfma_f32_16x16x32_bf16 v[108:111], v[132:135], v[172:175], v[108:111]
	v_mfma_f32_16x16x32_bf16 v[92:95], v[132:135], v[180:183], v[92:95]
	v_mfma_f32_16x16x32_bf16 v[92:95], v[144:147], v[184:187], v[92:95]
	v_mfma_f32_16x16x32_bf16 v[76:79], v[144:147], v[214:217], v[76:79]
	v_mfma_f32_16x16x32_bf16 v[76:79], v[132:135], v[188:191], v[76:79]
	s_setprio 0
	s_setprio 1
	v_mfma_f32_16x16x32_bf16 v[120:123], v[148:151], v[164:167], v[120:123]
	v_mfma_f32_16x16x32_bf16 v[120:123], v[152:155], v[168:171], v[120:123]
	v_mfma_f32_16x16x32_bf16 v[104:107], v[152:155], v[176:179], v[104:107]
	v_mfma_f32_16x16x32_bf16 v[104:107], v[148:151], v[172:175], v[104:107]
	v_mfma_f32_16x16x32_bf16 v[88:91], v[148:151], v[180:183], v[88:91]
	v_mfma_f32_16x16x32_bf16 v[88:91], v[152:155], v[184:187], v[88:91]
	v_mfma_f32_16x16x32_bf16 v[72:75], v[152:155], v[214:217], v[72:75]
	v_mfma_f32_16x16x32_bf16 v[72:75], v[148:151], v[188:191], v[72:75]
	v_mfma_f32_16x16x32_bf16 v[116:119], v[156:159], v[164:167], v[116:119]
	v_mfma_f32_16x16x32_bf16 v[116:119], v[160:163], v[168:171], v[116:119]
	v_mfma_f32_16x16x32_bf16 v[100:103], v[160:163], v[176:179], v[100:103]
	v_mfma_f32_16x16x32_bf16 v[100:103], v[156:159], v[172:175], v[100:103]
	v_mfma_f32_16x16x32_bf16 v[84:87], v[156:159], v[180:183], v[84:87]
	v_mfma_f32_16x16x32_bf16 v[84:87], v[160:163], v[184:187], v[84:87]
	v_mfma_f32_16x16x32_bf16 v[68:71], v[160:163], v[214:217], v[68:71]
	v_mfma_f32_16x16x32_bf16 v[68:71], v[156:159], v[188:191], v[68:71]
	s_setprio 0
	s_barrier
; #define PG8_STAGE(bufoff, gbase, voff) do { _Pragma("unroll") for (int _i = 0; _i < 2; ++_i) \
;         __builtin_amdgcn_global_load_lds((const unsigned*)((const char*)(gbase) + (voff)[_i]), (PG8_LAS unsigned*)(lds + (bufoff) + ldsw + _i * 8192), 16, 0, 0); } while (0)
; #define PG8_LDA(dst, b, h) do { _Pragma("unroll") for (int m = 0; m < 4; ++m) _Pragma("unroll") for (int k = 0; k < 2; ++k) dst[m][k] = *(const PG8_LAS bf16x8*)(lds + PG8_SA(b, h) + aoff + m * 2048 + k * 1024); } while (0)
; #define PG8_WAIT_V(n) asm volatile("s_waitcnt vmcnt(" #n ")" ::: "memory")
; #define PG8_WAIT_L(n) asm volatile("s_waitcnt lgkmcnt(" #n ")" ::: "memory")
; #define PG8_BAR __builtin_amdgcn_s_barrier()
; template <class Epi, class Sched, bool ALIGN_EPI = false, bool SP2 = false, bool I8 = false>
; __device__ __forceinline__ void gemm_phase(PG8_LAS unsigned char* lds, const Gemm g, const Sched& S, const Epi& E) {
;     ...
;         for (int t = 0; t < nt; t += 2) {
;             const bool last = (t == nt - 2);
;             const char* a1 = cA + (size_t)(t + 1) * kstep;
;             const char* a2 = last ? nA : cA + (size_t)(t + 2) * kstep; const char* b2 = last ? nB : cB + (size_t)(t + 2) * kstep;
;             const char* a3 = a2 + kstep; const char* b3 = b2 + kstep;
;             if (last && has_next) S.a_ready(nxt);
;             if constexpr (SP2) {
;             PG8_LDB(B0, 0, 0); PG8_LDB(B1, 0, 1); PG8_SCHED; PG8_LDA(At, 0, 0); PG8_STAGE(PG8_SA(1, 1), a1 + hstep, voffA);
;             PG8_WAIT_V(8); PG8_WAIT_L(0); PG8_BAR; PG8_MMA(0, 0, At, B0); PG8_MMA(0, 1, At, B1); PG8_BAR; PG8_SCHED;
;             PG8_LDA(At, 0, 1); PG8_STAGE(PG8_SB(0, 0), b2, voffB); PG8_STAGE(PG8_SB(0, 1), b2 + hstep, voffB); PG8_STAGE(PG8_SA(0, 0), a2, voffA);
;             PG8_WAIT_V(8); PG8_WAIT_L(0); PG8_BAR; PG8_MMA(1, 0, At, B0); PG8_MMA(1, 1, At, B1); PG8_BAR; PG8_SCHED;
;             PG8_LDB(B0, 1, 0); PG8_LDB(B1, 1, 1); PG8_SCHED; PG8_LDA(At, 1, 0); PG8_STAGE(PG8_SA(0, 1), a2 + hstep, voffA);
;             PG8_WAIT_V(8); PG8_WAIT_L(0); PG8_BAR; PG8_MMA(0, 0, At, B0); PG8_MMA(0, 1, At, B1); PG8_BAR; PG8_SCHED;
;             PG8_LDA(At, 1, 1); PG8_STAGE(PG8_SB(1, 0), b3, voffB); PG8_STAGE(PG8_SB(1, 1), b3 + hstep, voffB); PG8_STAGE(PG8_SA(1, 0), a3, voffA);
;             PG8_WAIT_V(8); PG8_WAIT_L(0); PG8_BAR; PG8_MMA(1, 0, At, B0); PG8_MMA(1, 1, At, B1); PG8_BAR; PG8_SCHED;
	s_add_i32 s36, s56, s40
	v_lshl_add_u64 v[218:219], v[218:219], 0, s[84:85]
	s_mov_b32 m0, s36
	ds_read_b128 v[164:167], v242 offset:49152
	ds_read_b128 v[168:171], v242 offset:50176
	ds_read_b128 v[172:175], v242 offset:51200
	ds_read_b128 v[176:179], v242 offset:52224
	ds_read_b128 v[180:183], v242 offset:53248
	ds_read_b128 v[184:187], v242 offset:54272
	ds_read_b128 v[188:191], v242 offset:55296
	ds_read_b128 v[214:217], v242 offset:56320
	global_load_lds_dwordx4 v[218:219], off
	s_add_i32 m0, s36, 0x2000
	s_add_u32 s26, s26, 0x100080
	v_lshl_add_u64 v[218:219], v[220:221], 0, s[84:85]
	s_addc_u32 s27, s27, 0
	s_add_i32 s36, s57, s40
	global_load_lds_dwordx4 v[218:219], off
	v_lshl_add_u64 v[218:219], s[26:27], 0, v[2:3]
	s_mov_b32 m0, s36
	s_nop 0
	global_load_lds_dwordx4 v[218:219], off
	v_lshl_add_u64 v[218:219], s[26:27], 0, v[204:205]
	s_add_i32 m0, s36, 0x2000
	s_nop 0
	global_load_lds_dwordx4 v[218:219], off
	v_lshl_add_u64 v[218:219], v[222:223], 0, s[84:85]
	s_mov_b32 m0, s45
	s_nop 0
	global_load_lds_dwordx4 v[218:219], off
	v_lshl_add_u64 v[218:219], v[224:225], 0, s[84:85]
	s_mov_b32 m0, s46
	s_nop 0
	global_load_lds_dwordx4 v[218:219], off
	s_waitcnt vmcnt(8)
	s_waitcnt lgkmcnt(0)
	s_barrier
	s_setprio 1
	s_waitcnt lgkmcnt(0)
	v_mfma_f32_16x16x32_bf16 v[64:67], v[124:127], v[164:167], v[64:67]
	v_mfma_f32_16x16x32_bf16 v[64:67], v[128:131], v[168:171], v[64:67]
	v_mfma_f32_16x16x32_bf16 v[48:51], v[128:131], v[176:179], v[48:51]
	v_mfma_f32_16x16x32_bf16 v[48:51], v[124:127], v[172:175], v[48:51]
	v_mfma_f32_16x16x32_bf16 v[32:35], v[124:127], v[180:183], v[32:35]
	v_mfma_f32_16x16x32_bf16 v[32:35], v[128:131], v[184:187], v[32:35]
	v_mfma_f32_16x16x32_bf16 v[16:19], v[128:131], v[214:217], v[16:19]
	v_mfma_f32_16x16x32_bf16 v[16:19], v[124:127], v[188:191], v[16:19]
	v_mfma_f32_16x16x32_bf16 v[60:63], v[132:135], v[164:167], v[60:63]
	v_mfma_f32_16x16x32_bf16 v[60:63], v[144:147], v[168:171], v[60:63]
	v_mfma_f32_16x16x32_bf16 v[44:47], v[144:147], v[176:179], v[44:47]
	v_mfma_f32_16x16x32_bf16 v[44:47], v[132:135], v[172:175], v[44:47]
	v_mfma_f32_16x16x32_bf16 v[28:31], v[132:135], v[180:183], v[28:31]
	v_mfma_f32_16x16x32_bf16 v[28:31], v[144:147], v[184:187], v[28:31]
	v_mfma_f32_16x16x32_bf16 v[12:15], v[144:147], v[214:217], v[12:15]
	v_mfma_f32_16x16x32_bf16 v[12:15], v[132:135], v[188:191], v[12:15]
	s_setprio 0
	s_setprio 1
	v_mfma_f32_16x16x32_bf16 v[56:59], v[148:151], v[164:167], v[56:59]
	v_mfma_f32_16x16x32_bf16 v[56:59], v[152:155], v[168:171], v[56:59]
	v_mfma_f32_16x16x32_bf16 v[40:43], v[152:155], v[176:179], v[40:43]
	v_mfma_f32_16x16x32_bf16 v[40:43], v[148:151], v[172:175], v[40:43]
	v_mfma_f32_16x16x32_bf16 v[24:27], v[148:151], v[180:183], v[24:27]
	v_mfma_f32_16x16x32_bf16 v[24:27], v[152:155], v[184:187], v[24:27]
	v_mfma_f32_16x16x32_bf16 v[8:11], v[152:155], v[214:217], v[8:11]
	v_mfma_f32_16x16x32_bf16 v[8:11], v[148:151], v[188:191], v[8:11]
	v_mfma_f32_16x16x32_bf16 v[52:55], v[156:159], v[164:167], v[52:55]
	v_mfma_f32_16x16x32_bf16 v[52:55], v[160:163], v[168:171], v[52:55]
	v_mfma_f32_16x16x32_bf16 v[36:39], v[160:163], v[176:179], v[36:39]
	v_mfma_f32_16x16x32_bf16 v[36:39], v[156:159], v[172:175], v[36:39]
	v_mfma_f32_16x16x32_bf16 v[20:23], v[156:159], v[180:183], v[20:23]
	v_mfma_f32_16x16x32_bf16 v[20:23], v[160:163], v[184:187], v[20:23]
	v_mfma_f32_16x16x32_bf16 v[4:7], v[160:163], v[214:217], v[4:7]
	v_mfma_f32_16x16x32_bf16 v[4:7], v[156:159], v[188:191], v[4:7]
	s_setprio 0
	s_barrier
	s_add_i32 s55, s55, 2
	s_add_u32 s24, s24, 0x100
	s_addc_u32 s25, s25, 0
	s_add_u32 s53, s53, 0x100
	s_addc_u32 s54, s54, 0
	s_cmp_gt_u32 s55, 61
	s_cbranch_scc1 .Lkloop_exit_2
.LBB0_1456:
	s_add_u32 s26, s24, 0xfff00080
	s_addc_u32 s27, s25, -1
	s_add_i32 s56, 0, 0x10000
	s_cmp_eq_u32 s55, 60
	s_cselect_b32 s37, s17, s27
	s_cselect_b32 s36, s51, s26
	s_cselect_b32 s27, s19, s54
	s_cselect_b32 s26, s52, s53
	s_add_i32 s58, 0, 0x14000
	v_add_u32_e32 v144, s56, v240
	v_add_u32_e32 v160, s58, v240
	ds_read_b128 v[124:127], v144
	ds_read_b128 v[128:131], v144 offset:1024
	ds_read_b128 v[132:135], v144 offset:2048
	ds_read_b128 v[144:147], v144 offset:3072
	ds_read_b128 v[148:151], v160
	ds_read_b128 v[152:155], v160 offset:1024
	ds_read_b128 v[156:159], v160 offset:2048
	ds_read_b128 v[160:163], v160 offset:3072
	v_lshl_add_u64 v[218:219], s[24:25], 0, v[210:211]
	s_add_i32 m0, s41, 0xc000
	ds_read_b128 v[164:167], v242
	ds_read_b128 v[168:171], v242 offset:1024
	ds_read_b128 v[172:175], v242 offset:2048
	ds_read_b128 v[176:179], v242 offset:3072
	ds_read_b128 v[180:183], v242 offset:4096
	ds_read_b128 v[184:187], v242 offset:5120
	ds_read_b128 v[188:191], v242 offset:6144
	ds_read_b128 v[214:217], v242 offset:7168
	global_load_lds_dwordx4 v[218:219], off
	v_lshl_add_u64 v[218:219], s[24:25], 0, v[212:213]
	s_add_i32 m0, s41, 0xe000
	s_nop 0
	global_load_lds_dwordx4 v[218:219], off
	s_waitcnt vmcnt(8)
	s_waitcnt lgkmcnt(0)
	s_barrier
; #define PG8_STAGE(bufoff, gbase, voff) do { _Pragma("unroll") for (int _i = 0; _i < 2; ++_i) \
;         __builtin_amdgcn_global_load_lds((const unsigned*)((const char*)(gbase) + (voff)[_i]), (PG8_LAS unsigned*)(lds + (bufoff) + ldsw + _i * 8192), 16, 0, 0); } while (0)
; #define PG8_LDA(dst, b, h) do { _Pragma("unroll") for (int m = 0; m < 4; ++m) _Pragma("unroll") for (int k = 0; k < 2; ++k) dst[m][k] = *(const PG8_LAS bf16x8*)(lds + PG8_SA(b, h) + aoff + m * 2048 + k * 1024); } while (0)
; #define PG8_LDB(dst, b, h) do { _Pragma("unroll") for (int n = 0; n < 2; ++n) _Pragma("unroll") for (int k = 0; k < 2; ++k) dst[n][k] = *(const PG8_LAS bf16x8*)(lds + PG8_SB(b, h) + boff + n * 2048 + k * 1024); } while (0)
; #define PG8_WAIT_V(n) asm volatile("s_waitcnt vmcnt(" #n ")" ::: "memory")
; #define PG8_WAIT_L(n) asm volatile("s_waitcnt lgkmcnt(" #n ")" ::: "memory")
; #define PG8_BAR __builtin_amdgcn_s_barrier()
; #define PG8_SCHED __builtin_amdgcn_sched_barrier(0)
; template <class Epi, class Sched, bool ALIGN_EPI = false, bool SP2 = false, bool I8 = false>
; __device__ __forceinline__ void gemm_phase(PG8_LAS unsigned char* lds, const Gemm g, const Sched& S, const Epi& E) {
;     ...
;             PG8_WAIT_V(8); PG8_WAIT_L(0); PG8_BAR; PG8_MMA(0, 0, At, B0); PG8_MMA(0, 1, At, B1); PG8_BAR; PG8_SCHED;
;             PG8_LDA(At, 0, 1); PG8_STAGE(PG8_SB(0, 0), b2, voffB); PG8_STAGE(PG8_SB(0, 1), b2 + hstep, voffB); PG8_STAGE(PG8_SA(0, 0), a2, voffA);
;             PG8_WAIT_V(8); PG8_WAIT_L(0); PG8_BAR; PG8_MMA(1, 0, At, B0); PG8_MMA(1, 1, At, B1); PG8_BAR; PG8_SCHED;
;             PG8_LDB(B0, 1, 0); PG8_LDB(B1, 1, 1); PG8_SCHED; PG8_LDA(At, 1, 0); PG8_STAGE(PG8_SA(0, 1), a2 + hstep, voffA);
;             PG8_WAIT_V(8); PG8_WAIT_L(0); PG8_BAR; PG8_MMA(0, 0, At, B0); PG8_MMA(0, 1, At, B1); PG8_BAR; PG8_SCHED;
	s_setprio 1
	s_waitcnt lgkmcnt(0)
	v_mfma_f32_16x16x32_bf16 v[140:143], v[124:127], v[164:167], v[140:143]
	v_mfma_f32_16x16x32_bf16 v[140:143], v[128:131], v[168:171], v[140:143]
	v_mfma_f32_16x16x32_bf16 v[112:115], v[128:131], v[176:179], v[112:115]
	v_mfma_f32_16x16x32_bf16 v[112:115], v[124:127], v[172:175], v[112:115]
	v_mfma_f32_16x16x32_bf16 v[96:99], v[124:127], v[180:183], v[96:99]
	v_mfma_f32_16x16x32_bf16 v[96:99], v[128:131], v[184:187], v[96:99]
	v_mfma_f32_16x16x32_bf16 v[80:83], v[128:131], v[214:217], v[80:83]
	v_mfma_f32_16x16x32_bf16 v[80:83], v[124:127], v[188:191], v[80:83]
	v_mfma_f32_16x16x32_bf16 v[136:139], v[132:135], v[164:167], v[136:139]
	v_mfma_f32_16x16x32_bf16 v[136:139], v[144:147], v[168:171], v[136:139]
	v_mfma_f32_16x16x32_bf16 v[108:111], v[144:147], v[176:179], v[108:111]
	v_mfma_f32_16x16x32_bf16 v[108:111], v[132:135], v[172:175], v[108:111]
	v_mfma_f32_16x16x32_bf16 v[92:95], v[132:135], v[180:183], v[92:95]
	v_mfma_f32_16x16x32_bf16 v[92:95], v[144:147], v[184:187], v[92:95]
	v_mfma_f32_16x16x32_bf16 v[76:79], v[144:147], v[214:217], v[76:79]
	v_mfma_f32_16x16x32_bf16 v[76:79], v[132:135], v[188:191], v[76:79]
	s_setprio 0
	s_setprio 1
	v_mfma_f32_16x16x32_bf16 v[120:123], v[148:151], v[164:167], v[120:123]
	v_mfma_f32_16x16x32_bf16 v[120:123], v[152:155], v[168:171], v[120:123]
	v_mfma_f32_16x16x32_bf16 v[104:107], v[152:155], v[176:179], v[104:107]
	v_mfma_f32_16x16x32_bf16 v[104:107], v[148:151], v[172:175], v[104:107]
	v_mfma_f32_16x16x32_bf16 v[88:91], v[148:151], v[180:183], v[88:91]
	v_mfma_f32_16x16x32_bf16 v[88:91], v[152:155], v[184:187], v[88:91]
	v_mfma_f32_16x16x32_bf16 v[72:75], v[152:155], v[214:217], v[72:75]
	v_mfma_f32_16x16x32_bf16 v[72:75], v[148:151], v[188:191], v[72:75]
	v_mfma_f32_16x16x32_bf16 v[116:119], v[156:159], v[164:167], v[116:119]
	v_mfma_f32_16x16x32_bf16 v[116:119], v[160:163], v[168:171], v[116:119]
	v_mfma_f32_16x16x32_bf16 v[100:103], v[160:163], v[176:179], v[100:103]
	v_mfma_f32_16x16x32_bf16 v[100:103], v[156:159], v[172:175], v[100:103]
	v_mfma_f32_16x16x32_bf16 v[84:87], v[156:159], v[180:183], v[84:87]
	v_mfma_f32_16x16x32_bf16 v[84:87], v[160:163], v[184:187], v[84:87]
	v_mfma_f32_16x16x32_bf16 v[68:71], v[160:163], v[214:217], v[68:71]
	v_mfma_f32_16x16x32_bf16 v[68:71], v[156:159], v[188:191], v[68:71]
	s_setprio 0
	s_barrier
	s_add_i32 s56, s56, s40
	v_lshl_add_u64 v[218:219], s[26:27], 0, v[2:3]
	s_mov_b32 m0, s56
	ds_read_b128 v[164:167], v242 offset:16384
	ds_read_b128 v[168:171], v242 offset:17408
	ds_read_b128 v[172:175], v242 offset:18432
	ds_read_b128 v[176:179], v242 offset:19456
	ds_read_b128 v[180:183], v242 offset:20480
	ds_read_b128 v[184:187], v242 offset:21504
	ds_read_b128 v[188:191], v242 offset:22528
	ds_read_b128 v[214:217], v242 offset:23552
	global_load_lds_dwordx4 v[218:219], off
	s_add_i32 m0, s56, 0x2000
	s_add_u32 s56, s26, 0x100000
	v_lshl_add_u64 v[220:221], s[26:27], 0, v[204:205]
	s_addc_u32 s57, s27, 0
	s_add_i32 s58, s58, s40
	global_load_lds_dwordx4 v[220:221], off
	v_lshl_add_u64 v[222:223], s[56:57], 0, v[2:3]
	s_mov_b32 m0, s58
	v_lshl_add_u64 v[224:225], s[36:37], 0, v[206:207]
	global_load_lds_dwordx4 v[222:223], off
	v_lshl_add_u64 v[222:223], s[56:57], 0, v[204:205]
	s_add_i32 m0, s58, 0x2000
	s_nop 0
	global_load_lds_dwordx4 v[222:223], off
	v_lshl_add_u64 v[222:223], s[36:37], 0, v[208:209]
	s_mov_b32 m0, s41
	s_nop 0
	global_load_lds_dwordx4 v[222:223], off
	s_mov_b32 m0, s42
	s_nop 0
	global_load_lds_dwordx4 v[224:225], off
	s_waitcnt vmcnt(8)
	s_waitcnt lgkmcnt(0)
	s_barrier
	s_setprio 1
	s_waitcnt lgkmcnt(0)
	v_mfma_f32_16x16x32_bf16 v[64:67], v[124:127], v[164:167], v[64:67]
	v_mfma_f32_16x16x32_bf16 v[64:67], v[128:131], v[168:171], v[64:67]
	v_mfma_f32_16x16x32_bf16 v[48:51], v[128:131], v[176:179], v[48:51]
	v_mfma_f32_16x16x32_bf16 v[48:51], v[124:127], v[172:175], v[48:51]
	v_mfma_f32_16x16x32_bf16 v[32:35], v[124:127], v[180:183], v[32:35]
	v_mfma_f32_16x16x32_bf16 v[32:35], v[128:131], v[184:187], v[32:35]
	v_mfma_f32_16x16x32_bf16 v[16:19], v[128:131], v[214:217], v[16:19]
	v_mfma_f32_16x16x32_bf16 v[16:19], v[124:127], v[188:191], v[16:19]
	v_mfma_f32_16x16x32_bf16 v[60:63], v[132:135], v[164:167], v[60:63]
	v_mfma_f32_16x16x32_bf16 v[60:63], v[144:147], v[168:171], v[60:63]
	v_mfma_f32_16x16x32_bf16 v[44:47], v[144:147], v[176:179], v[44:47]
	v_mfma_f32_16x16x32_bf16 v[44:47], v[132:135], v[172:175], v[44:47]
	v_mfma_f32_16x16x32_bf16 v[28:31], v[132:135], v[180:183], v[28:31]
	v_mfma_f32_16x16x32_bf16 v[28:31], v[144:147], v[184:187], v[28:31]
	v_mfma_f32_16x16x32_bf16 v[12:15], v[144:147], v[214:217], v[12:15]
	v_mfma_f32_16x16x32_bf16 v[12:15], v[132:135], v[188:191], v[12:15]
	s_setprio 0
	s_setprio 1
	v_mfma_f32_16x16x32_bf16 v[56:59], v[148:151], v[164:167], v[56:59]
	v_mfma_f32_16x16x32_bf16 v[56:59], v[152:155], v[168:171], v[56:59]
	v_mfma_f32_16x16x32_bf16 v[40:43], v[152:155], v[176:179], v[40:43]
	v_mfma_f32_16x16x32_bf16 v[40:43], v[148:151], v[172:175], v[40:43]
	v_mfma_f32_16x16x32_bf16 v[24:27], v[148:151], v[180:183], v[24:27]
	v_mfma_f32_16x16x32_bf16 v[24:27], v[152:155], v[184:187], v[24:27]
	v_mfma_f32_16x16x32_bf16 v[8:11], v[152:155], v[214:217], v[8:11]
	v_mfma_f32_16x16x32_bf16 v[8:11], v[148:151], v[188:191], v[8:11]
	v_mfma_f32_16x16x32_bf16 v[52:55], v[156:159], v[164:167], v[52:55]
	v_mfma_f32_16x16x32_bf16 v[52:55], v[160:163], v[168:171], v[52:55]
	v_mfma_f32_16x16x32_bf16 v[36:39], v[160:163], v[176:179], v[36:39]
	v_mfma_f32_16x16x32_bf16 v[36:39], v[156:159], v[172:175], v[36:39]
	v_mfma_f32_16x16x32_bf16 v[20:23], v[156:159], v[180:183], v[20:23]
	v_mfma_f32_16x16x32_bf16 v[20:23], v[160:163], v[184:187], v[20:23]
	v_mfma_f32_16x16x32_bf16 v[4:7], v[160:163], v[214:217], v[4:7]
	v_mfma_f32_16x16x32_bf16 v[4:7], v[156:159], v[188:191], v[4:7]
	s_setprio 0
	s_barrier
; #define PG8_STAGE(bufoff, gbase, voff) do { _Pragma("unroll") for (int _i = 0; _i < 2; ++_i) \
;         __builtin_amdgcn_global_load_lds((const unsigned*)((const char*)(gbase) + (voff)[_i]), (PG8_LAS unsigned*)(lds + (bufoff) + ldsw + _i * 8192), 16, 0, 0); } while (0)
; #define PG8_LDA(dst, b, h) do { _Pragma("unroll") for (int m = 0; m < 4; ++m) _Pragma("unroll") for (int k = 0; k < 2; ++k) dst[m][k] = *(const PG8_LAS bf16x8*)(lds + PG8_SA(b, h) + aoff + m * 2048 + k * 1024); } while (0)
; #define PG8_LDB(dst, b, h) do { _Pragma("unroll") for (int n = 0; n < 2; ++n) _Pragma("unroll") for (int k = 0; k < 2; ++k) dst[n][k] = *(const PG8_LAS bf16x8*)(lds + PG8_SB(b, h) + boff + n * 2048 + k * 1024); } while (0)
; #define PG8_WAIT_V(n) asm volatile("s_waitcnt vmcnt(" #n ")" ::: "memory")
; #define PG8_WAIT_L(n) asm volatile("s_waitcnt lgkmcnt(" #n ")" ::: "memory")
; #define PG8_BAR __builtin_amdgcn_s_barrier()
; #define PG8_SCHED __builtin_amdgcn_sched_barrier(0)
; template <class Epi, class Sched, bool ALIGN_EPI = false, bool SP2 = false, bool I8 = false>
; __device__ __forceinline__ void gemm_phase(PG8_LAS unsigned char* lds, const Gemm g, const Sched& S, const Epi& E) {
;     ...
;             PG8_LDB(B0, 1, 0); PG8_LDB(B1, 1, 1); PG8_SCHED; PG8_LDA(At, 1, 0); PG8_STAGE(PG8_SA(0, 1), a2 + hstep, voffA);
;             PG8_WAIT_V(8); PG8_WAIT_L(0); PG8_BAR; PG8_MMA(0, 0, At, B0); PG8_MMA(0, 1, At, B1); PG8_BAR; PG8_SCHED;
	s_add_i32 s56, 0, 0x18000
	s_add_i32 s57, 0, 0x1c000
	v_add_u32_e32 v144, s56, v240
	v_add_u32_e32 v160, s57, v240
	ds_read_b128 v[124:127], v144
	ds_read_b128 v[128:131], v144 offset:1024
	ds_read_b128 v[132:135], v144 offset:2048
	ds_read_b128 v[144:147], v144 offset:3072
	ds_read_b128 v[148:151], v160
	ds_read_b128 v[152:155], v160 offset:1024
	ds_read_b128 v[156:159], v160 offset:2048
	ds_read_b128 v[160:163], v160 offset:3072
	s_add_u32 s36, s36, 0x100000
	s_addc_u32 s37, s37, 0
	s_mov_b32 m0, s43
	v_lshl_add_u64 v[226:227], s[36:37], 0, v[208:209]
	ds_read_b128 v[164:167], v242 offset:32768
	ds_read_b128 v[168:171], v242 offset:33792
	ds_read_b128 v[172:175], v242 offset:34816
	ds_read_b128 v[176:179], v242 offset:35840
	ds_read_b128 v[180:183], v242 offset:36864
	ds_read_b128 v[184:187], v242 offset:37888
	ds_read_b128 v[188:191], v242 offset:38912
	ds_read_b128 v[214:217], v242 offset:39936
	global_load_lds_dwordx4 v[226:227], off
	v_lshl_add_u64 v[226:227], s[36:37], 0, v[206:207]
	s_mov_b32 m0, s44
	s_nop 0
	global_load_lds_dwordx4 v[226:227], off
	s_waitcnt vmcnt(8)
	s_waitcnt lgkmcnt(0)
	s_barrier
	s_setprio 1
	s_waitcnt lgkmcnt(0)
	v_mfma_f32_16x16x32_bf16 v[140:143], v[124:127], v[164:167], v[140:143]
	v_mfma_f32_16x16x32_bf16 v[140:143], v[128:131], v[168:171], v[140:143]
	v_mfma_f32_16x16x32_bf16 v[112:115], v[128:131], v[176:179], v[112:115]
	v_mfma_f32_16x16x32_bf16 v[112:115], v[124:127], v[172:175], v[112:115]
	v_mfma_f32_16x16x32_bf16 v[96:99], v[124:127], v[180:183], v[96:99]
	v_mfma_f32_16x16x32_bf16 v[96:99], v[128:131], v[184:187], v[96:99]
	v_mfma_f32_16x16x32_bf16 v[80:83], v[128:131], v[214:217], v[80:83]
	v_mfma_f32_16x16x32_bf16 v[80:83], v[124:127], v[188:191], v[80:83]
	v_mfma_f32_16x16x32_bf16 v[136:139], v[132:135], v[164:167], v[136:139]
	v_mfma_f32_16x16x32_bf16 v[136:139], v[144:147], v[168:171], v[136:139]
	v_mfma_f32_16x16x32_bf16 v[108:111], v[144:147], v[176:179], v[108:111]
	v_mfma_f32_16x16x32_bf16 v[108:111], v[132:135], v[172:175], v[108:111]
	v_mfma_f32_16x16x32_bf16 v[92:95], v[132:135], v[180:183], v[92:95]
	v_mfma_f32_16x16x32_bf16 v[92:95], v[144:147], v[184:187], v[92:95]
	v_mfma_f32_16x16x32_bf16 v[76:79], v[144:147], v[214:217], v[76:79]
	v_mfma_f32_16x16x32_bf16 v[76:79], v[132:135], v[188:191], v[76:79]
	s_setprio 0
	s_setprio 1
	v_mfma_f32_16x16x32_bf16 v[120:123], v[148:151], v[164:167], v[120:123]
	v_mfma_f32_16x16x32_bf16 v[120:123], v[152:155], v[168:171], v[120:123]
	v_mfma_f32_16x16x32_bf16 v[104:107], v[152:155], v[176:179], v[104:107]
	v_mfma_f32_16x16x32_bf16 v[104:107], v[148:151], v[172:175], v[104:107]
	v_mfma_f32_16x16x32_bf16 v[88:91], v[148:151], v[180:183], v[88:91]
	v_mfma_f32_16x16x32_bf16 v[88:91], v[152:155], v[184:187], v[88:91]
	v_mfma_f32_16x16x32_bf16 v[72:75], v[152:155], v[214:217], v[72:75]
	v_mfma_f32_16x16x32_bf16 v[72:75], v[148:151], v[188:191], v[72:75]
	v_mfma_f32_16x16x32_bf16 v[116:119], v[156:159], v[164:167], v[116:119]
	v_mfma_f32_16x16x32_bf16 v[116:119], v[160:163], v[168:171], v[116:119]
	v_mfma_f32_16x16x32_bf16 v[100:103], v[160:163], v[176:179], v[100:103]
	v_mfma_f32_16x16x32_bf16 v[100:103], v[156:159], v[172:175], v[100:103]
	v_mfma_f32_16x16x32_bf16 v[84:87], v[156:159], v[180:183], v[84:87]
	v_mfma_f32_16x16x32_bf16 v[84:87], v[160:163], v[184:187], v[84:87]
	v_mfma_f32_16x16x32_bf16 v[68:71], v[160:163], v[214:217], v[68:71]
	v_mfma_f32_16x16x32_bf16 v[68:71], v[156:159], v[188:191], v[68:71]
	s_setprio 0
	s_barrier
; #define PG8_STAGE(bufoff, gbase, voff) do { _Pragma("unroll") for (int _i = 0; _i < 2; ++_i) \
;         __builtin_amdgcn_global_load_lds((const unsigned*)((const char*)(gbase) + (voff)[_i]), (PG8_LAS unsigned*)(lds + (bufoff) + ldsw + _i * 8192), 16, 0, 0); } while (0)
; #define PG8_LDA(dst, b, h) do { _Pragma("unroll") for (int m = 0; m < 4; ++m) _Pragma("unroll") for (int k = 0; k < 2; ++k) dst[m][k] = *(const PG8_LAS bf16x8*)(lds + PG8_SA(b, h) + aoff + m * 2048 + k * 1024); } while (0)
; #define PG8_WAIT_V(n) asm volatile("s_waitcnt vmcnt(" #n ")" ::: "memory")
; #define PG8_WAIT_L(n) asm volatile("s_waitcnt lgkmcnt(" #n ")" ::: "memory")
; #define PG8_BAR __builtin_amdgcn_s_barrier()
; #define PG8_SCHED __builtin_amdgcn_sched_barrier(0)
; template <class Epi, class Sched, bool ALIGN_EPI = false, bool SP2 = false, bool I8 = false>
; __device__ __forceinline__ void gemm_phase(PG8_LAS unsigned char* lds, const Gemm g, const Sched& S, const Epi& E) {
;     ...
;         for (int t = 0; t < nt; t += 2) {
;             const bool last = (t == nt - 2);
;             const char* a1 = cA + (size_t)(t + 1) * kstep;
;             const char* a2 = last ? nA : cA + (size_t)(t + 2) * kstep; const char* b2 = last ? nB : cB + (size_t)(t + 2) * kstep;
;     ...
;             PG8_LDA(At, 1, 1); PG8_STAGE(PG8_SB(1, 0), b3, voffB); PG8_STAGE(PG8_SB(1, 1), b3 + hstep, voffB); PG8_STAGE(PG8_SA(1, 0), a3, voffA);
;             PG8_WAIT_V(8); PG8_WAIT_L(0); PG8_BAR; PG8_MMA(1, 0, At, B0); PG8_MMA(1, 1, At, B1); PG8_BAR; PG8_SCHED;
	s_add_i32 s36, s56, s40
	v_lshl_add_u64 v[218:219], v[218:219], 0, s[84:85]
	s_mov_b32 m0, s36
	ds_read_b128 v[164:167], v242 offset:49152
	ds_read_b128 v[168:171], v242 offset:50176
	ds_read_b128 v[172:175], v242 offset:51200
	ds_read_b128 v[176:179], v242 offset:52224
	ds_read_b128 v[180:183], v242 offset:53248
	ds_read_b128 v[184:187], v242 offset:54272
	ds_read_b128 v[188:191], v242 offset:55296
	ds_read_b128 v[214:217], v242 offset:56320
	global_load_lds_dwordx4 v[218:219], off
	s_add_i32 m0, s36, 0x2000
	s_add_u32 s26, s26, 0x100080
	v_lshl_add_u64 v[218:219], v[220:221], 0, s[84:85]
	s_addc_u32 s27, s27, 0
	s_add_i32 s36, s57, s40
	global_load_lds_dwordx4 v[218:219], off
	v_lshl_add_u64 v[218:219], s[26:27], 0, v[2:3]
	s_mov_b32 m0, s36
	s_nop 0
	global_load_lds_dwordx4 v[218:219], off
	v_lshl_add_u64 v[218:219], s[26:27], 0, v[204:205]
	s_add_i32 m0, s36, 0x2000
	s_nop 0
	global_load_lds_dwordx4 v[218:219], off
	v_lshl_add_u64 v[218:219], v[222:223], 0, s[84:85]
	s_mov_b32 m0, s45
	s_nop 0
	global_load_lds_dwordx4 v[218:219], off
	v_lshl_add_u64 v[218:219], v[224:225], 0, s[84:85]
	s_mov_b32 m0, s46
	s_nop 0
	global_load_lds_dwordx4 v[218:219], off
	s_waitcnt vmcnt(8)
	s_waitcnt lgkmcnt(0)
	s_barrier
	s_setprio 1
	s_waitcnt lgkmcnt(0)
	v_mfma_f32_16x16x32_bf16 v[64:67], v[124:127], v[164:167], v[64:67]
	v_mfma_f32_16x16x32_bf16 v[64:67], v[128:131], v[168:171], v[64:67]
	v_mfma_f32_16x16x32_bf16 v[48:51], v[128:131], v[176:179], v[48:51]
	v_mfma_f32_16x16x32_bf16 v[48:51], v[124:127], v[172:175], v[48:51]
	v_mfma_f32_16x16x32_bf16 v[32:35], v[124:127], v[180:183], v[32:35]
	v_mfma_f32_16x16x32_bf16 v[32:35], v[128:131], v[184:187], v[32:35]
	v_mfma_f32_16x16x32_bf16 v[16:19], v[128:131], v[214:217], v[16:19]
	v_mfma_f32_16x16x32_bf16 v[16:19], v[124:127], v[188:191], v[16:19]
	v_mfma_f32_16x16x32_bf16 v[60:63], v[132:135], v[164:167], v[60:63]
	v_mfma_f32_16x16x32_bf16 v[60:63], v[144:147], v[168:171], v[60:63]
	v_mfma_f32_16x16x32_bf16 v[44:47], v[144:147], v[176:179], v[44:47]
	v_mfma_f32_16x16x32_bf16 v[44:47], v[132:135], v[172:175], v[44:47]
	v_mfma_f32_16x16x32_bf16 v[28:31], v[132:135], v[180:183], v[28:31]
	v_mfma_f32_16x16x32_bf16 v[28:31], v[144:147], v[184:187], v[28:31]
	v_mfma_f32_16x16x32_bf16 v[12:15], v[144:147], v[214:217], v[12:15]
	v_mfma_f32_16x16x32_bf16 v[12:15], v[132:135], v[188:191], v[12:15]
	s_setprio 0
	s_setprio 1
	v_mfma_f32_16x16x32_bf16 v[56:59], v[148:151], v[164:167], v[56:59]
	v_mfma_f32_16x16x32_bf16 v[56:59], v[152:155], v[168:171], v[56:59]
	v_mfma_f32_16x16x32_bf16 v[40:43], v[152:155], v[176:179], v[40:43]
	v_mfma_f32_16x16x32_bf16 v[40:43], v[148:151], v[172:175], v[40:43]
	v_mfma_f32_16x16x32_bf16 v[24:27], v[148:151], v[180:183], v[24:27]
	v_mfma_f32_16x16x32_bf16 v[24:27], v[152:155], v[184:187], v[24:27]
	v_mfma_f32_16x16x32_bf16 v[8:11], v[152:155], v[214:217], v[8:11]
	v_mfma_f32_16x16x32_bf16 v[8:11], v[148:151], v[188:191], v[8:11]
	v_mfma_f32_16x16x32_bf16 v[52:55], v[156:159], v[164:167], v[52:55]
	v_mfma_f32_16x16x32_bf16 v[52:55], v[160:163], v[168:171], v[52:55]
	v_mfma_f32_16x16x32_bf16 v[36:39], v[160:163], v[176:179], v[36:39]
	v_mfma_f32_16x16x32_bf16 v[36:39], v[156:159], v[172:175], v[36:39]
	v_mfma_f32_16x16x32_bf16 v[20:23], v[156:159], v[180:183], v[20:23]
	v_mfma_f32_16x16x32_bf16 v[20:23], v[160:163], v[184:187], v[20:23]
	v_mfma_f32_16x16x32_bf16 v[4:7], v[160:163], v[214:217], v[4:7]
	v_mfma_f32_16x16x32_bf16 v[4:7], v[156:159], v[188:191], v[4:7]
	s_setprio 0
	s_barrier
	s_add_i32 s55, s55, 2
	s_add_u32 s24, s24, 0x100
	s_addc_u32 s25, s25, 0
	s_add_u32 s53, s53, 0x100
	s_addc_u32 s54, s54, 0
	s_cmp_gt_u32 s55, 61
	s_cbranch_scc0 .LBB0_1456

; #define PG8_STAGE(bufoff, gbase, voff) do { _Pragma("unroll") for (int _i = 0; _i < 2; ++_i) \
;         __builtin_amdgcn_global_load_lds((const unsigned*)((const char*)(gbase) + (voff)[_i]), (PG8_LAS unsigned*)(lds + (bufoff) + ldsw + _i * 8192), 16, 0, 0); } while (0)
; #define PG8_LDA(dst, b, h) do { _Pragma("unroll") for (int m = 0; m < 4; ++m) _Pragma("unroll") for (int k = 0; k < 2; ++k) dst[m][k] = *(const PG8_LAS bf16x8*)(lds + PG8_SA(b, h) + aoff + m * 2048 + k * 1024); } while (0)
; #define PG8_LDB(dst, b, h) do { _Pragma("unroll") for (int n = 0; n < 2; ++n) _Pragma("unroll") for (int k = 0; k < 2; ++k) dst[n][k] = *(const PG8_LAS bf16x8*)(lds + PG8_SB(b, h) + boff + n * 2048 + k * 1024); } while (0)
; #define PG8_WAIT_V(n) asm volatile("s_waitcnt vmcnt(" #n ")" ::: "memory")
; #define PG8_WAIT_L(n) asm volatile("s_waitcnt lgkmcnt(" #n ")" ::: "memory")
; #define PG8_BAR __builtin_amdgcn_s_barrier()
; #define PG8_SCHED __builtin_amdgcn_sched_barrier(0)
; template <class Epi, class Sched, bool ALIGN_EPI = false, bool SP2 = false, bool I8 = false>
; __device__ __forceinline__ void gemm_phase(PG8_LAS unsigned char* lds, const Gemm g, const Sched& S, const Epi& E) {
;     ...
;         const bool has_next = S.next(ui + 1, nxt);
;         const char* nA = has_next ? (const char*)g.A + (size_t)nxt.pm * tstep : cA; const char* nB = has_next ? (const char*)g.Bt + (size_t)nxt.pn * tstep : cB;
;         for (int t = 0; t < nt; t += 2) {
;             const bool last = (t == nt - 2);
;             const char* a1 = cA + (size_t)(t + 1) * kstep;
;             const char* a2 = last ? nA : cA + (size_t)(t + 2) * kstep; const char* b2 = last ? nB : cB + (size_t)(t + 2) * kstep;
;             const char* a3 = a2 + kstep; const char* b3 = b2 + kstep;
;             if (last && has_next) S.a_ready(nxt);
;             if constexpr (SP2) {
;             PG8_LDB(B0, 0, 0); PG8_LDB(B1, 0, 1); PG8_SCHED; PG8_LDA(At, 0, 0); PG8_STAGE(PG8_SA(1, 1), a1 + hstep, voffA);
;             PG8_WAIT_V(8); PG8_WAIT_L(0); PG8_BAR; PG8_MMA(0, 0, At, B0); PG8_MMA(0, 1, At, B1); PG8_BAR; PG8_SCHED;
;     ...
;         for (int a = 0; a < 2; ++a)
; #pragma unroll
;             for (int b = 0; b < 2; ++b)
; #pragma unroll
;                 for (int m = 0; m < 4; ++m)
; #pragma unroll
;                     for (int n = 0; n < 2; ++n) acc[a][b][m][n] = (acc_t){0, 0, 0, 0};
.LBB0_1621:
	v_mov_b32_e32 v127, 0
	s_andn2_b64 vcc, exec, s[26:27]
	v_mov_b32_e32 v126, v127
	v_mov_b32_e32 v125, v127
	v_mov_b32_e32 v124, v127
	v_mov_b32_e32 v131, v127
	v_mov_b32_e32 v130, v127
	v_mov_b32_e32 v129, v127
	v_mov_b32_e32 v128, v127
	v_mov_b32_e32 v115, v127
	v_mov_b32_e32 v114, v127
	v_mov_b32_e32 v113, v127
	v_mov_b32_e32 v112, v127
	v_mov_b32_e32 v111, v127
	v_mov_b32_e32 v110, v127
	v_mov_b32_e32 v109, v127
	v_mov_b32_e32 v108, v127
	v_mov_b32_e32 v99, v127
	v_mov_b32_e32 v98, v127
	v_mov_b32_e32 v97, v127
	v_mov_b32_e32 v96, v127
	v_mov_b32_e32 v95, v127
	v_mov_b32_e32 v94, v127
	v_mov_b32_e32 v93, v127
	v_mov_b32_e32 v92, v127
	v_mov_b32_e32 v83, v127
	v_mov_b32_e32 v82, v127
	v_mov_b32_e32 v81, v127
	v_mov_b32_e32 v80, v127
	v_mov_b32_e32 v79, v127
	v_mov_b32_e32 v78, v127
	v_mov_b32_e32 v77, v127
	v_mov_b32_e32 v76, v127
	v_mov_b32_e32 v123, v127
	v_mov_b32_e32 v122, v127
	v_mov_b32_e32 v121, v127
	v_mov_b32_e32 v120, v127
	v_mov_b32_e32 v119, v127
	v_mov_b32_e32 v118, v127
	v_mov_b32_e32 v117, v127
	v_mov_b32_e32 v116, v127
	v_mov_b32_e32 v107, v127
	v_mov_b32_e32 v106, v127
	v_mov_b32_e32 v105, v127
	v_mov_b32_e32 v104, v127
	v_mov_b32_e32 v103, v127
	v_mov_b32_e32 v102, v127
	v_mov_b32_e32 v101, v127
	v_mov_b32_e32 v100, v127
	v_mov_b32_e32 v91, v127
	v_mov_b32_e32 v90, v127
	v_mov_b32_e32 v89, v127
	v_mov_b32_e32 v88, v127
	v_mov_b32_e32 v87, v127
	v_mov_b32_e32 v86, v127
	v_mov_b32_e32 v85, v127
	v_mov_b32_e32 v84, v127
	v_mov_b32_e32 v75, v127
	v_mov_b32_e32 v74, v127
	v_mov_b32_e32 v73, v127
	v_mov_b32_e32 v72, v127
	v_mov_b32_e32 v71, v127
	v_mov_b32_e32 v70, v127
	v_mov_b32_e32 v69, v127
	v_mov_b32_e32 v68, v127
	v_mov_b32_e32 v67, v127
	v_mov_b32_e32 v66, v127
	v_mov_b32_e32 v65, v127
	v_mov_b32_e32 v64, v127
	v_mov_b32_e32 v63, v127
	v_mov_b32_e32 v62, v127
	v_mov_b32_e32 v61, v127
	v_mov_b32_e32 v60, v127
	v_mov_b32_e32 v51, v127
	v_mov_b32_e32 v50, v127
	v_mov_b32_e32 v49, v127
	v_mov_b32_e32 v48, v127
	v_mov_b32_e32 v47, v127
	v_mov_b32_e32 v46, v127
	v_mov_b32_e32 v45, v127
	v_mov_b32_e32 v44, v127
	v_mov_b32_e32 v35, v127
	v_mov_b32_e32 v34, v127
	v_mov_b32_e32 v33, v127
	v_mov_b32_e32 v32, v127
	v_mov_b32_e32 v31, v127
	v_mov_b32_e32 v30, v127
	v_mov_b32_e32 v29, v127
	v_mov_b32_e32 v28, v127
	v_mov_b32_e32 v19, v127
	v_mov_b32_e32 v18, v127
	v_mov_b32_e32 v17, v127
	v_mov_b32_e32 v16, v127
	v_mov_b32_e32 v15, v127
	v_mov_b32_e32 v14, v127
	v_mov_b32_e32 v13, v127
	v_mov_b32_e32 v12, v127
	v_mov_b32_e32 v59, v127
	v_mov_b32_e32 v58, v127
	v_mov_b32_e32 v57, v127
	v_mov_b32_e32 v56, v127
	v_mov_b32_e32 v55, v127
	v_mov_b32_e32 v54, v127
	v_mov_b32_e32 v53, v127
	v_mov_b32_e32 v52, v127
	v_mov_b32_e32 v43, v127
	v_mov_b32_e32 v42, v127
	v_mov_b32_e32 v41, v127
	v_mov_b32_e32 v40, v127
	v_mov_b32_e32 v39, v127
	v_mov_b32_e32 v38, v127
	v_mov_b32_e32 v37, v127
	v_mov_b32_e32 v36, v127
	v_mov_b32_e32 v27, v127
	v_mov_b32_e32 v26, v127
	v_mov_b32_e32 v25, v127
	v_mov_b32_e32 v24, v127
	v_mov_b32_e32 v23, v127
	v_mov_b32_e32 v22, v127
	v_mov_b32_e32 v21, v127
	v_mov_b32_e32 v20, v127
	v_mov_b32_e32 v11, v127
	v_mov_b32_e32 v10, v127
	v_mov_b32_e32 v9, v127
	v_mov_b32_e32 v8, v127
	v_mov_b32_e32 v7, v127
	v_mov_b32_e32 v6, v127
	v_mov_b32_e32 v5, v127
	v_mov_b32_e32 v4, v127
	s_cbranch_vccnz .LBB0_1625
	s_add_u32 s44, s44, 0x80
	s_addc_u32 s45, s45, 0
	s_add_u32 s65, s48, 0x100
	s_addc_u32 s67, s49, 0
	s_mov_b32 s48, 0
	s_add_i32 s72, s48, 2
	s_add_u32 s73, s44, 0x80
	s_addc_u32 s49, s45, 0
	s_add_i32 s86, 0, 0x10000
	s_cmp_eq_u32 s57, s48
	s_cselect_b32 s49, s13, s49
	s_cselect_b32 s48, s12, s73
	s_cselect_b32 s77, s41, s67
	s_cselect_b32 s76, s40, s65
	s_add_i32 s73, 0, 0x14000
	v_add_u32_e32 v158, s86, v143
	v_add_u32_e32 v174, s73, v143
	ds_read_b128 v[146:149], v158
	ds_read_b128 v[150:153], v158 offset:1024
	ds_read_b128 v[154:157], v158 offset:2048
	ds_read_b128 v[158:161], v158 offset:3072
	ds_read_b128 v[162:165], v174
	ds_read_b128 v[166:169], v174 offset:1024
	ds_read_b128 v[170:173], v174 offset:2048
	ds_read_b128 v[174:177], v174 offset:3072
	v_lshl_add_u64 v[190:191], s[44:45], 0, v[138:139]
	s_add_i32 m0, s47, 0xc000
	ds_read_b128 v[178:181], v145
	ds_read_b128 v[182:185], v145 offset:1024
	ds_read_b128 v[186:189], v145 offset:2048
	ds_read_b128 v[204:207], v145 offset:3072
	ds_read_b128 v[208:211], v145 offset:4096
	ds_read_b128 v[212:215], v145 offset:5120
	ds_read_b128 v[216:219], v145 offset:6144
	ds_read_b128 v[220:223], v145 offset:7168
	global_load_lds_dwordx4 v[190:191], off
	v_lshl_add_u64 v[190:191], s[44:45], 0, v[140:141]
	s_add_i32 m0, s47, 0xe000
	s_nop 0
	global_load_lds_dwordx4 v[190:191], off
	s_waitcnt vmcnt(8)
	s_waitcnt lgkmcnt(0)
	s_barrier
; #define PG8_STAGE(bufoff, gbase, voff) do { _Pragma("unroll") for (int _i = 0; _i < 2; ++_i) \
;         __builtin_amdgcn_global_load_lds((const unsigned*)((const char*)(gbase) + (voff)[_i]), (PG8_LAS unsigned*)(lds + (bufoff) + ldsw + _i * 8192), 16, 0, 0); } while (0)
; #define PG8_LDA(dst, b, h) do { _Pragma("unroll") for (int m = 0; m < 4; ++m) _Pragma("unroll") for (int k = 0; k < 2; ++k) dst[m][k] = *(const PG8_LAS bf16x8*)(lds + PG8_SA(b, h) + aoff + m * 2048 + k * 1024); } while (0)
; #define PG8_LDB(dst, b, h) do { _Pragma("unroll") for (int n = 0; n < 2; ++n) _Pragma("unroll") for (int k = 0; k < 2; ++k) dst[n][k] = *(const PG8_LAS bf16x8*)(lds + PG8_SB(b, h) + boff + n * 2048 + k * 1024); } while (0)
; #define PG8_WAIT_V(n) asm volatile("s_waitcnt vmcnt(" #n ")" ::: "memory")
; #define PG8_WAIT_L(n) asm volatile("s_waitcnt lgkmcnt(" #n ")" ::: "memory")
; #define PG8_BAR __builtin_amdgcn_s_barrier()
; #define PG8_SCHED __builtin_amdgcn_sched_barrier(0)
; template <class Epi, class Sched, bool ALIGN_EPI = false, bool SP2 = false, bool I8 = false>
; __device__ __forceinline__ void gemm_phase(PG8_LAS unsigned char* lds, const Gemm g, const Sched& S, const Epi& E) {
;     ...
;             PG8_WAIT_V(8); PG8_WAIT_L(0); PG8_BAR; PG8_MMA(1, 0, At, B0); PG8_MMA(1, 1, At, B1); PG8_BAR; PG8_SCHED;
;             PG8_LDB(B0, 1, 0); PG8_LDB(B1, 1, 1); PG8_SCHED; PG8_LDA(At, 1, 0); PG8_STAGE(PG8_SA(0, 1), a2 + hstep, voffA);
;             PG8_WAIT_V(8); PG8_WAIT_L(0); PG8_BAR; PG8_MMA(0, 0, At, B0); PG8_MMA(0, 1, At, B1); PG8_BAR; PG8_SCHED;
;             PG8_LDA(At, 1, 1); PG8_STAGE(PG8_SB(1, 0), b3, voffB); PG8_STAGE(PG8_SB(1, 1), b3 + hstep, voffB); PG8_STAGE(PG8_SA(1, 0), a3, voffA);
	s_setprio 1
	s_waitcnt lgkmcnt(0)
	v_mfma_f32_16x16x32_bf16 v[124:127], v[146:149], v[178:181], 0
	v_mfma_f32_16x16x32_bf16 v[124:127], v[150:153], v[182:185], v[124:127]
	v_mfma_f32_16x16x32_bf16 v[112:115], v[150:153], v[204:207], 0
	v_mfma_f32_16x16x32_bf16 v[112:115], v[146:149], v[186:189], v[112:115]
	v_mfma_f32_16x16x32_bf16 v[96:99], v[146:149], v[208:211], 0
	v_mfma_f32_16x16x32_bf16 v[96:99], v[150:153], v[212:215], v[96:99]
	v_mfma_f32_16x16x32_bf16 v[80:83], v[150:153], v[220:223], 0
	v_mfma_f32_16x16x32_bf16 v[80:83], v[146:149], v[216:219], v[80:83]
	v_mfma_f32_16x16x32_bf16 v[128:131], v[154:157], v[178:181], 0
	v_mfma_f32_16x16x32_bf16 v[128:131], v[158:161], v[182:185], v[128:131]
	v_mfma_f32_16x16x32_bf16 v[108:111], v[158:161], v[204:207], 0
	v_mfma_f32_16x16x32_bf16 v[108:111], v[154:157], v[186:189], v[108:111]
	v_mfma_f32_16x16x32_bf16 v[92:95], v[154:157], v[208:211], 0
	v_mfma_f32_16x16x32_bf16 v[92:95], v[158:161], v[212:215], v[92:95]
	v_mfma_f32_16x16x32_bf16 v[76:79], v[158:161], v[220:223], 0
	v_mfma_f32_16x16x32_bf16 v[76:79], v[154:157], v[216:219], v[76:79]
	s_setprio 0
	s_setprio 1
	v_mfma_f32_16x16x32_bf16 v[120:123], v[162:165], v[178:181], 0
	v_mfma_f32_16x16x32_bf16 v[120:123], v[166:169], v[182:185], v[120:123]
	v_mfma_f32_16x16x32_bf16 v[104:107], v[166:169], v[204:207], 0
	v_mfma_f32_16x16x32_bf16 v[104:107], v[162:165], v[186:189], v[104:107]
	v_mfma_f32_16x16x32_bf16 v[88:91], v[162:165], v[208:211], 0
	v_mfma_f32_16x16x32_bf16 v[88:91], v[166:169], v[212:215], v[88:91]
	v_mfma_f32_16x16x32_bf16 v[72:75], v[166:169], v[220:223], 0
	v_mfma_f32_16x16x32_bf16 v[72:75], v[162:165], v[216:219], v[72:75]
	v_mfma_f32_16x16x32_bf16 v[116:119], v[170:173], v[178:181], 0
	v_mfma_f32_16x16x32_bf16 v[116:119], v[174:177], v[182:185], v[116:119]
	v_mfma_f32_16x16x32_bf16 v[100:103], v[174:177], v[204:207], 0
	v_mfma_f32_16x16x32_bf16 v[100:103], v[170:173], v[186:189], v[100:103]
	v_mfma_f32_16x16x32_bf16 v[84:87], v[170:173], v[208:211], 0
	v_mfma_f32_16x16x32_bf16 v[84:87], v[174:177], v[212:215], v[84:87]
	v_mfma_f32_16x16x32_bf16 v[68:71], v[174:177], v[220:223], 0
	v_mfma_f32_16x16x32_bf16 v[68:71], v[170:173], v[216:219], v[68:71]
	s_setprio 0
	s_barrier
	s_add_i32 s86, s86, s28
	v_lshl_add_u64 v[190:191], s[76:77], 0, v[2:3]
	s_mov_b32 m0, s86
	ds_read_b128 v[178:181], v145 offset:16384
	ds_read_b128 v[182:185], v145 offset:17408
	ds_read_b128 v[186:189], v145 offset:18432
	ds_read_b128 v[204:207], v145 offset:19456
	ds_read_b128 v[208:211], v145 offset:20480
	ds_read_b128 v[212:215], v145 offset:21504
	ds_read_b128 v[216:219], v145 offset:22528
	ds_read_b128 v[220:223], v145 offset:23552
	global_load_lds_dwordx4 v[190:191], off
	s_add_i32 m0, s86, 0x2000
	v_lshl_add_u64 v[224:225], s[76:77], 0, v[136:137]
	s_add_u32 s76, s76, s18
	s_addc_u32 s77, s77, s19
	s_add_i32 s73, s73, s28
	global_load_lds_dwordx4 v[224:225], off
	v_lshl_add_u64 v[226:227], s[76:77], 0, v[2:3]
	s_mov_b32 m0, s73
	v_lshl_add_u64 v[228:229], s[76:77], 0, v[136:137]
	global_load_lds_dwordx4 v[226:227], off
	s_add_i32 m0, s73, 0x2000
	v_lshl_add_u64 v[240:241], s[48:49], 0, v[132:133]
	global_load_lds_dwordx4 v[228:229], off
	s_mov_b32 m0, s47
	v_lshl_add_u64 v[242:243], s[48:49], 0, v[134:135]
	global_load_lds_dwordx4 v[240:241], off
	s_mov_b32 m0, s50
	s_nop 0
	global_load_lds_dwordx4 v[242:243], off
	s_waitcnt vmcnt(8)
	s_waitcnt lgkmcnt(0)
	s_barrier
	s_setprio 1
	s_waitcnt lgkmcnt(0)
	v_mfma_f32_16x16x32_bf16 v[64:67], v[146:149], v[178:181], 0
	v_mfma_f32_16x16x32_bf16 v[64:67], v[150:153], v[182:185], v[64:67]
	v_mfma_f32_16x16x32_bf16 v[48:51], v[150:153], v[204:207], 0
	v_mfma_f32_16x16x32_bf16 v[48:51], v[146:149], v[186:189], v[48:51]
	v_mfma_f32_16x16x32_bf16 v[32:35], v[146:149], v[208:211], 0
	v_mfma_f32_16x16x32_bf16 v[32:35], v[150:153], v[212:215], v[32:35]
	v_mfma_f32_16x16x32_bf16 v[16:19], v[150:153], v[220:223], 0
	v_mfma_f32_16x16x32_bf16 v[16:19], v[146:149], v[216:219], v[16:19]
	v_mfma_f32_16x16x32_bf16 v[60:63], v[154:157], v[178:181], 0
	v_mfma_f32_16x16x32_bf16 v[60:63], v[158:161], v[182:185], v[60:63]
	v_mfma_f32_16x16x32_bf16 v[44:47], v[158:161], v[204:207], 0
	v_mfma_f32_16x16x32_bf16 v[44:47], v[154:157], v[186:189], v[44:47]
	v_mfma_f32_16x16x32_bf16 v[28:31], v[154:157], v[208:211], 0
	v_mfma_f32_16x16x32_bf16 v[28:31], v[158:161], v[212:215], v[28:31]
	v_mfma_f32_16x16x32_bf16 v[12:15], v[158:161], v[220:223], 0
	v_mfma_f32_16x16x32_bf16 v[12:15], v[154:157], v[216:219], v[12:15]
	s_setprio 0
	s_setprio 1
	v_mfma_f32_16x16x32_bf16 v[56:59], v[162:165], v[178:181], 0
	v_mfma_f32_16x16x32_bf16 v[56:59], v[166:169], v[182:185], v[56:59]
	v_mfma_f32_16x16x32_bf16 v[40:43], v[166:169], v[204:207], 0
	v_mfma_f32_16x16x32_bf16 v[40:43], v[162:165], v[186:189], v[40:43]
	v_mfma_f32_16x16x32_bf16 v[24:27], v[162:165], v[208:211], 0
	v_mfma_f32_16x16x32_bf16 v[24:27], v[166:169], v[212:215], v[24:27]
	v_mfma_f32_16x16x32_bf16 v[8:11], v[166:169], v[220:223], 0
	v_mfma_f32_16x16x32_bf16 v[8:11], v[162:165], v[216:219], v[8:11]
	v_mfma_f32_16x16x32_bf16 v[52:55], v[170:173], v[178:181], 0
	v_mfma_f32_16x16x32_bf16 v[52:55], v[174:177], v[182:185], v[52:55]
	v_mfma_f32_16x16x32_bf16 v[36:39], v[174:177], v[204:207], 0
	v_mfma_f32_16x16x32_bf16 v[36:39], v[170:173], v[186:189], v[36:39]
	v_mfma_f32_16x16x32_bf16 v[20:23], v[170:173], v[208:211], 0
	v_mfma_f32_16x16x32_bf16 v[20:23], v[174:177], v[212:215], v[20:23]
	v_mfma_f32_16x16x32_bf16 v[4:7], v[174:177], v[220:223], 0
	v_mfma_f32_16x16x32_bf16 v[4:7], v[170:173], v[216:219], v[4:7]
	s_setprio 0
	s_barrier
; #define PG8_STAGE(bufoff, gbase, voff) do { _Pragma("unroll") for (int _i = 0; _i < 2; ++_i) \
;         __builtin_amdgcn_global_load_lds((const unsigned*)((const char*)(gbase) + (voff)[_i]), (PG8_LAS unsigned*)(lds + (bufoff) + ldsw + _i * 8192), 16, 0, 0); } while (0)
; #define PG8_LDA(dst, b, h) do { _Pragma("unroll") for (int m = 0; m < 4; ++m) _Pragma("unroll") for (int k = 0; k < 2; ++k) dst[m][k] = *(const PG8_LAS bf16x8*)(lds + PG8_SA(b, h) + aoff + m * 2048 + k * 1024); } while (0)
; #define PG8_LDB(dst, b, h) do { _Pragma("unroll") for (int n = 0; n < 2; ++n) _Pragma("unroll") for (int k = 0; k < 2; ++k) dst[n][k] = *(const PG8_LAS bf16x8*)(lds + PG8_SB(b, h) + boff + n * 2048 + k * 1024); } while (0)
; #define PG8_WAIT_V(n) asm volatile("s_waitcnt vmcnt(" #n ")" ::: "memory")
; #define PG8_WAIT_L(n) asm volatile("s_waitcnt lgkmcnt(" #n ")" ::: "memory")
; #define PG8_BAR __builtin_amdgcn_s_barrier()
; #define PG8_SCHED __builtin_amdgcn_sched_barrier(0)
; template <class Epi, class Sched, bool ALIGN_EPI = false, bool SP2 = false, bool I8 = false>
; __device__ __forceinline__ void gemm_phase(PG8_LAS unsigned char* lds, const Gemm g, const Sched& S, const Epi& E) {
;     ...
;             PG8_LDB(B0, 1, 0); PG8_LDB(B1, 1, 1); PG8_SCHED; PG8_LDA(At, 1, 0); PG8_STAGE(PG8_SA(0, 1), a2 + hstep, voffA);
;             PG8_WAIT_V(8); PG8_WAIT_L(0); PG8_BAR; PG8_MMA(0, 0, At, B0); PG8_MMA(0, 1, At, B1); PG8_BAR; PG8_SCHED;
;             PG8_LDA(At, 1, 1); PG8_STAGE(PG8_SB(1, 0), b3, voffB); PG8_STAGE(PG8_SB(1, 1), b3 + hstep, voffB); PG8_STAGE(PG8_SA(1, 0), a3, voffA);
	s_add_i32 s73, 0, 0x18000
	s_add_i32 s76, 0, 0x1c000
	v_add_u32_e32 v158, s73, v143
	v_add_u32_e32 v174, s76, v143
	ds_read_b128 v[146:149], v158
	ds_read_b128 v[150:153], v158 offset:1024
	ds_read_b128 v[154:157], v158 offset:2048
	ds_read_b128 v[158:161], v158 offset:3072
	ds_read_b128 v[162:165], v174
	ds_read_b128 v[166:169], v174 offset:1024
	ds_read_b128 v[170:173], v174 offset:2048
	ds_read_b128 v[174:177], v174 offset:3072
	s_add_u32 s48, s48, s18
	s_addc_u32 s49, s49, s19
	s_mov_b32 m0, s51
	v_lshl_add_u64 v[244:245], s[48:49], 0, v[132:133]
	ds_read_b128 v[178:181], v145 offset:32768
	ds_read_b128 v[182:185], v145 offset:33792
	ds_read_b128 v[186:189], v145 offset:34816
	ds_read_b128 v[204:207], v145 offset:35840
	ds_read_b128 v[208:211], v145 offset:36864
	ds_read_b128 v[212:215], v145 offset:37888
	ds_read_b128 v[216:219], v145 offset:38912
	ds_read_b128 v[220:223], v145 offset:39936
	global_load_lds_dwordx4 v[244:245], off
	v_lshl_add_u64 v[244:245], s[48:49], 0, v[134:135]
	s_mov_b32 m0, s52
	s_nop 0
	global_load_lds_dwordx4 v[244:245], off
	s_waitcnt vmcnt(8)
	s_waitcnt lgkmcnt(0)
	s_barrier
	s_setprio 1
	s_waitcnt lgkmcnt(0)
	v_mfma_f32_16x16x32_bf16 v[124:127], v[146:149], v[178:181], v[124:127]
	v_mfma_f32_16x16x32_bf16 v[124:127], v[150:153], v[182:185], v[124:127]
	v_mfma_f32_16x16x32_bf16 v[112:115], v[150:153], v[204:207], v[112:115]
	v_mfma_f32_16x16x32_bf16 v[112:115], v[146:149], v[186:189], v[112:115]
	v_mfma_f32_16x16x32_bf16 v[96:99], v[146:149], v[208:211], v[96:99]
	v_mfma_f32_16x16x32_bf16 v[96:99], v[150:153], v[212:215], v[96:99]
	v_mfma_f32_16x16x32_bf16 v[80:83], v[150:153], v[220:223], v[80:83]
	v_mfma_f32_16x16x32_bf16 v[80:83], v[146:149], v[216:219], v[80:83]
	v_mfma_f32_16x16x32_bf16 v[128:131], v[154:157], v[178:181], v[128:131]
	v_mfma_f32_16x16x32_bf16 v[128:131], v[158:161], v[182:185], v[128:131]
	v_mfma_f32_16x16x32_bf16 v[108:111], v[158:161], v[204:207], v[108:111]
	v_mfma_f32_16x16x32_bf16 v[108:111], v[154:157], v[186:189], v[108:111]
	v_mfma_f32_16x16x32_bf16 v[92:95], v[154:157], v[208:211], v[92:95]
	v_mfma_f32_16x16x32_bf16 v[92:95], v[158:161], v[212:215], v[92:95]
	v_mfma_f32_16x16x32_bf16 v[76:79], v[158:161], v[220:223], v[76:79]
	v_mfma_f32_16x16x32_bf16 v[76:79], v[154:157], v[216:219], v[76:79]
	s_setprio 0
	s_setprio 1
	v_mfma_f32_16x16x32_bf16 v[120:123], v[162:165], v[178:181], v[120:123]
	v_mfma_f32_16x16x32_bf16 v[120:123], v[166:169], v[182:185], v[120:123]
	v_mfma_f32_16x16x32_bf16 v[104:107], v[166:169], v[204:207], v[104:107]
	v_mfma_f32_16x16x32_bf16 v[104:107], v[162:165], v[186:189], v[104:107]
	v_mfma_f32_16x16x32_bf16 v[88:91], v[162:165], v[208:211], v[88:91]
	v_mfma_f32_16x16x32_bf16 v[88:91], v[166:169], v[212:215], v[88:91]
	v_mfma_f32_16x16x32_bf16 v[72:75], v[166:169], v[220:223], v[72:75]
	v_mfma_f32_16x16x32_bf16 v[72:75], v[162:165], v[216:219], v[72:75]
	v_mfma_f32_16x16x32_bf16 v[116:119], v[170:173], v[178:181], v[116:119]
	v_mfma_f32_16x16x32_bf16 v[116:119], v[174:177], v[182:185], v[116:119]
	v_mfma_f32_16x16x32_bf16 v[100:103], v[174:177], v[204:207], v[100:103]
	v_mfma_f32_16x16x32_bf16 v[100:103], v[170:173], v[186:189], v[100:103]
	v_mfma_f32_16x16x32_bf16 v[84:87], v[170:173], v[208:211], v[84:87]
	v_mfma_f32_16x16x32_bf16 v[84:87], v[174:177], v[212:215], v[84:87]
	v_mfma_f32_16x16x32_bf16 v[68:71], v[174:177], v[220:223], v[68:71]
	v_mfma_f32_16x16x32_bf16 v[68:71], v[170:173], v[216:219], v[68:71]
	s_setprio 0
	s_barrier
	s_add_i32 s48, s73, s28
	v_lshl_add_u64 v[190:191], v[190:191], 0, s[84:85]
	s_mov_b32 m0, s48
	ds_read_b128 v[178:181], v145 offset:49152
	ds_read_b128 v[182:185], v145 offset:50176
	ds_read_b128 v[186:189], v145 offset:51200
	ds_read_b128 v[204:207], v145 offset:52224
	ds_read_b128 v[208:211], v145 offset:53248
	ds_read_b128 v[212:215], v145 offset:54272
	ds_read_b128 v[216:219], v145 offset:55296
	ds_read_b128 v[220:223], v145 offset:56320
	global_load_lds_dwordx4 v[190:191], off
	v_lshl_add_u64 v[190:191], v[224:225], 0, s[84:85]
	s_add_i32 m0, s48, 0x2000
	s_add_i32 s48, s76, s28
	global_load_lds_dwordx4 v[190:191], off
	v_lshl_add_u64 v[190:191], v[226:227], 0, s[84:85]
	s_mov_b32 m0, s48
	s_nop 0
	global_load_lds_dwordx4 v[190:191], off
	v_lshl_add_u64 v[190:191], v[228:229], 0, s[84:85]
	s_add_i32 m0, s48, 0x2000
	s_nop 0
	global_load_lds_dwordx4 v[190:191], off
	v_lshl_add_u64 v[190:191], v[240:241], 0, s[84:85]
	s_mov_b32 m0, s55
	s_nop 0
	global_load_lds_dwordx4 v[190:191], off
	v_lshl_add_u64 v[190:191], v[242:243], 0, s[84:85]
	s_mov_b32 m0, s56
	s_nop 0
	global_load_lds_dwordx4 v[190:191], off
	s_waitcnt vmcnt(8)
	s_waitcnt lgkmcnt(0)
	s_barrier
; #define PG8_STAGE(bufoff, gbase, voff) do { _Pragma("unroll") for (int _i = 0; _i < 2; ++_i) \
;         __builtin_amdgcn_global_load_lds((const unsigned*)((const char*)(gbase) + (voff)[_i]), (PG8_LAS unsigned*)(lds + (bufoff) + ldsw + _i * 8192), 16, 0, 0); } while (0)
; #define PG8_LDA(dst, b, h) do { _Pragma("unroll") for (int m = 0; m < 4; ++m) _Pragma("unroll") for (int k = 0; k < 2; ++k) dst[m][k] = *(const PG8_LAS bf16x8*)(lds + PG8_SA(b, h) + aoff + m * 2048 + k * 1024); } while (0)
; #define PG8_WAIT_V(n) asm volatile("s_waitcnt vmcnt(" #n ")" ::: "memory")
; #define PG8_WAIT_L(n) asm volatile("s_waitcnt lgkmcnt(" #n ")" ::: "memory")
; #define PG8_BAR __builtin_amdgcn_s_barrier()
; template <class Epi, class Sched, bool ALIGN_EPI = false, bool SP2 = false, bool I8 = false>
; __device__ __forceinline__ void gemm_phase(PG8_LAS unsigned char* lds, const Gemm g, const Sched& S, const Epi& E) {
;     ...
;         for (int t = 0; t < nt; t += 2) {
;             const bool last = (t == nt - 2);
;             const char* a1 = cA + (size_t)(t + 1) * kstep;
;             const char* a2 = last ? nA : cA + (size_t)(t + 2) * kstep; const char* b2 = last ? nB : cB + (size_t)(t + 2) * kstep;
;             const char* a3 = a2 + kstep; const char* b3 = b2 + kstep;
;             if (last && has_next) S.a_ready(nxt);
;             if constexpr (SP2) {
;             PG8_LDB(B0, 0, 0); PG8_LDB(B1, 0, 1); PG8_SCHED; PG8_LDA(At, 0, 0); PG8_STAGE(PG8_SA(1, 1), a1 + hstep, voffA);
;             PG8_WAIT_V(8); PG8_WAIT_L(0); PG8_BAR; PG8_MMA(0, 0, At, B0); PG8_MMA(0, 1, At, B1); PG8_BAR; PG8_SCHED;
;             PG8_LDA(At, 0, 1); PG8_STAGE(PG8_SB(0, 0), b2, voffB); PG8_STAGE(PG8_SB(0, 1), b2 + hstep, voffB); PG8_STAGE(PG8_SA(0, 0), a2, voffA);
;             PG8_WAIT_V(8); PG8_WAIT_L(0); PG8_BAR; PG8_MMA(1, 0, At, B0); PG8_MMA(1, 1, At, B1); PG8_BAR; PG8_SCHED;
;             PG8_LDB(B0, 1, 0); PG8_LDB(B1, 1, 1); PG8_SCHED; PG8_LDA(At, 1, 0); PG8_STAGE(PG8_SA(0, 1), a2 + hstep, voffA);
;             PG8_WAIT_V(8); PG8_WAIT_L(0); PG8_BAR; PG8_MMA(0, 0, At, B0); PG8_MMA(0, 1, At, B1); PG8_BAR; PG8_SCHED;
;             PG8_LDA(At, 1, 1); PG8_STAGE(PG8_SB(1, 0), b3, voffB); PG8_STAGE(PG8_SB(1, 1), b3 + hstep, voffB); PG8_STAGE(PG8_SA(1, 0), a3, voffA);
;             PG8_WAIT_V(8); PG8_WAIT_L(0); PG8_BAR; PG8_MMA(1, 0, At, B0); PG8_MMA(1, 1, At, B1); PG8_BAR; PG8_SCHED;
	s_setprio 1
	s_waitcnt lgkmcnt(0)
	v_mfma_f32_16x16x32_bf16 v[64:67], v[146:149], v[178:181], v[64:67]
	v_mfma_f32_16x16x32_bf16 v[64:67], v[150:153], v[182:185], v[64:67]
	v_mfma_f32_16x16x32_bf16 v[48:51], v[150:153], v[204:207], v[48:51]
	v_mfma_f32_16x16x32_bf16 v[48:51], v[146:149], v[186:189], v[48:51]
	v_mfma_f32_16x16x32_bf16 v[32:35], v[146:149], v[208:211], v[32:35]
	v_mfma_f32_16x16x32_bf16 v[32:35], v[150:153], v[212:215], v[32:35]
	v_mfma_f32_16x16x32_bf16 v[16:19], v[150:153], v[220:223], v[16:19]
	v_mfma_f32_16x16x32_bf16 v[16:19], v[146:149], v[216:219], v[16:19]
	v_mfma_f32_16x16x32_bf16 v[60:63], v[154:157], v[178:181], v[60:63]
	v_mfma_f32_16x16x32_bf16 v[60:63], v[158:161], v[182:185], v[60:63]
	v_mfma_f32_16x16x32_bf16 v[44:47], v[158:161], v[204:207], v[44:47]
	v_mfma_f32_16x16x32_bf16 v[44:47], v[154:157], v[186:189], v[44:47]
	v_mfma_f32_16x16x32_bf16 v[28:31], v[154:157], v[208:211], v[28:31]
	v_mfma_f32_16x16x32_bf16 v[28:31], v[158:161], v[212:215], v[28:31]
	v_mfma_f32_16x16x32_bf16 v[12:15], v[158:161], v[220:223], v[12:15]
	v_mfma_f32_16x16x32_bf16 v[12:15], v[154:157], v[216:219], v[12:15]
	s_setprio 0
	s_setprio 1
	v_mfma_f32_16x16x32_bf16 v[56:59], v[162:165], v[178:181], v[56:59]
	v_mfma_f32_16x16x32_bf16 v[56:59], v[166:169], v[182:185], v[56:59]
	v_mfma_f32_16x16x32_bf16 v[40:43], v[166:169], v[204:207], v[40:43]
	v_mfma_f32_16x16x32_bf16 v[40:43], v[162:165], v[186:189], v[40:43]
	v_mfma_f32_16x16x32_bf16 v[24:27], v[162:165], v[208:211], v[24:27]
	v_mfma_f32_16x16x32_bf16 v[24:27], v[166:169], v[212:215], v[24:27]
	v_mfma_f32_16x16x32_bf16 v[8:11], v[166:169], v[220:223], v[8:11]
	v_mfma_f32_16x16x32_bf16 v[8:11], v[162:165], v[216:219], v[8:11]
	v_mfma_f32_16x16x32_bf16 v[52:55], v[170:173], v[178:181], v[52:55]
	v_mfma_f32_16x16x32_bf16 v[52:55], v[174:177], v[182:185], v[52:55]
	v_mfma_f32_16x16x32_bf16 v[36:39], v[174:177], v[204:207], v[36:39]
	v_mfma_f32_16x16x32_bf16 v[36:39], v[170:173], v[186:189], v[36:39]
	v_mfma_f32_16x16x32_bf16 v[20:23], v[170:173], v[208:211], v[20:23]
	v_mfma_f32_16x16x32_bf16 v[20:23], v[174:177], v[212:215], v[20:23]
	v_mfma_f32_16x16x32_bf16 v[4:7], v[174:177], v[220:223], v[4:7]
	v_mfma_f32_16x16x32_bf16 v[4:7], v[170:173], v[216:219], v[4:7]
	s_setprio 0
	s_barrier
	s_add_u32 s44, s44, 0x100
	s_addc_u32 s45, s45, 0
	s_add_u32 s65, s65, 0x100
	s_addc_u32 s67, s67, 0
	s_cmp_ge_i32 s72, s53
	s_mov_b32 s48, s72
	s_cbranch_scc1 .Lkloop_exit_4
.LBB0_1623:
	s_add_i32 s72, s48, 2
	s_add_u32 s73, s44, 0x80
	s_addc_u32 s49, s45, 0
	s_add_i32 s86, 0, 0x10000
	s_cmp_eq_u32 s57, s48
	s_cselect_b32 s49, s13, s49
	s_cselect_b32 s48, s12, s73
	s_cselect_b32 s77, s41, s67
	s_cselect_b32 s76, s40, s65
	s_add_i32 s73, 0, 0x14000
	v_add_u32_e32 v158, s86, v143
	v_add_u32_e32 v174, s73, v143
	ds_read_b128 v[146:149], v158
	ds_read_b128 v[150:153], v158 offset:1024
	ds_read_b128 v[154:157], v158 offset:2048
	ds_read_b128 v[158:161], v158 offset:3072
	ds_read_b128 v[162:165], v174
	ds_read_b128 v[166:169], v174 offset:1024
	ds_read_b128 v[170:173], v174 offset:2048
	ds_read_b128 v[174:177], v174 offset:3072
	v_lshl_add_u64 v[190:191], s[44:45], 0, v[138:139]
	s_add_i32 m0, s47, 0xc000
	ds_read_b128 v[178:181], v145
	ds_read_b128 v[182:185], v145 offset:1024
	ds_read_b128 v[186:189], v145 offset:2048
	ds_read_b128 v[204:207], v145 offset:3072
	ds_read_b128 v[208:211], v145 offset:4096
	ds_read_b128 v[212:215], v145 offset:5120
	ds_read_b128 v[216:219], v145 offset:6144
	ds_read_b128 v[220:223], v145 offset:7168
	global_load_lds_dwordx4 v[190:191], off
	v_lshl_add_u64 v[190:191], s[44:45], 0, v[140:141]
	s_add_i32 m0, s47, 0xe000
	s_nop 0
	global_load_lds_dwordx4 v[190:191], off
	s_waitcnt vmcnt(8)
	s_waitcnt lgkmcnt(0)
	s_barrier
	s_setprio 1
	s_waitcnt lgkmcnt(0)
	v_mfma_f32_16x16x32_bf16 v[124:127], v[146:149], v[178:181], v[124:127]
	v_mfma_f32_16x16x32_bf16 v[124:127], v[150:153], v[182:185], v[124:127]
	v_mfma_f32_16x16x32_bf16 v[112:115], v[150:153], v[204:207], v[112:115]
	v_mfma_f32_16x16x32_bf16 v[112:115], v[146:149], v[186:189], v[112:115]
	v_mfma_f32_16x16x32_bf16 v[96:99], v[146:149], v[208:211], v[96:99]
	v_mfma_f32_16x16x32_bf16 v[96:99], v[150:153], v[212:215], v[96:99]
	v_mfma_f32_16x16x32_bf16 v[80:83], v[150:153], v[220:223], v[80:83]
	v_mfma_f32_16x16x32_bf16 v[80:83], v[146:149], v[216:219], v[80:83]
	v_mfma_f32_16x16x32_bf16 v[128:131], v[154:157], v[178:181], v[128:131]
	v_mfma_f32_16x16x32_bf16 v[128:131], v[158:161], v[182:185], v[128:131]
	v_mfma_f32_16x16x32_bf16 v[108:111], v[158:161], v[204:207], v[108:111]
	v_mfma_f32_16x16x32_bf16 v[108:111], v[154:157], v[186:189], v[108:111]
	v_mfma_f32_16x16x32_bf16 v[92:95], v[154:157], v[208:211], v[92:95]
	v_mfma_f32_16x16x32_bf16 v[92:95], v[158:161], v[212:215], v[92:95]
	v_mfma_f32_16x16x32_bf16 v[76:79], v[158:161], v[220:223], v[76:79]
	v_mfma_f32_16x16x32_bf16 v[76:79], v[154:157], v[216:219], v[76:79]
	s_setprio 0
	s_setprio 1
	v_mfma_f32_16x16x32_bf16 v[120:123], v[162:165], v[178:181], v[120:123]
	v_mfma_f32_16x16x32_bf16 v[120:123], v[166:169], v[182:185], v[120:123]
	v_mfma_f32_16x16x32_bf16 v[104:107], v[166:169], v[204:207], v[104:107]
	v_mfma_f32_16x16x32_bf16 v[104:107], v[162:165], v[186:189], v[104:107]
	v_mfma_f32_16x16x32_bf16 v[88:91], v[162:165], v[208:211], v[88:91]
	v_mfma_f32_16x16x32_bf16 v[88:91], v[166:169], v[212:215], v[88:91]
	v_mfma_f32_16x16x32_bf16 v[72:75], v[166:169], v[220:223], v[72:75]
	v_mfma_f32_16x16x32_bf16 v[72:75], v[162:165], v[216:219], v[72:75]
	v_mfma_f32_16x16x32_bf16 v[116:119], v[170:173], v[178:181], v[116:119]
	v_mfma_f32_16x16x32_bf16 v[116:119], v[174:177], v[182:185], v[116:119]
	v_mfma_f32_16x16x32_bf16 v[100:103], v[174:177], v[204:207], v[100:103]
	v_mfma_f32_16x16x32_bf16 v[100:103], v[170:173], v[186:189], v[100:103]
	v_mfma_f32_16x16x32_bf16 v[84:87], v[170:173], v[208:211], v[84:87]
	v_mfma_f32_16x16x32_bf16 v[84:87], v[174:177], v[212:215], v[84:87]
	v_mfma_f32_16x16x32_bf16 v[68:71], v[174:177], v[220:223], v[68:71]
	v_mfma_f32_16x16x32_bf16 v[68:71], v[170:173], v[216:219], v[68:71]
	s_setprio 0
	s_barrier
; #define PG8_STAGE(bufoff, gbase, voff) do { _Pragma("unroll") for (int _i = 0; _i < 2; ++_i) \
;         __builtin_amdgcn_global_load_lds((const unsigned*)((const char*)(gbase) + (voff)[_i]), (PG8_LAS unsigned*)(lds + (bufoff) + ldsw + _i * 8192), 16, 0, 0); } while (0)
; #define PG8_LDA(dst, b, h) do { _Pragma("unroll") for (int m = 0; m < 4; ++m) _Pragma("unroll") for (int k = 0; k < 2; ++k) dst[m][k] = *(const PG8_LAS bf16x8*)(lds + PG8_SA(b, h) + aoff + m * 2048 + k * 1024); } while (0)
; #define PG8_LDB(dst, b, h) do { _Pragma("unroll") for (int n = 0; n < 2; ++n) _Pragma("unroll") for (int k = 0; k < 2; ++k) dst[n][k] = *(const PG8_LAS bf16x8*)(lds + PG8_SB(b, h) + boff + n * 2048 + k * 1024); } while (0)
; #define PG8_WAIT_V(n) asm volatile("s_waitcnt vmcnt(" #n ")" ::: "memory")
; #define PG8_WAIT_L(n) asm volatile("s_waitcnt lgkmcnt(" #n ")" ::: "memory")
; #define PG8_BAR __builtin_amdgcn_s_barrier()
; #define PG8_SCHED __builtin_amdgcn_sched_barrier(0)
; template <class Epi, class Sched, bool ALIGN_EPI = false, bool SP2 = false, bool I8 = false>
; __device__ __forceinline__ void gemm_phase(PG8_LAS unsigned char* lds, const Gemm g, const Sched& S, const Epi& E) {
;     ...
;             PG8_WAIT_V(8); PG8_WAIT_L(0); PG8_BAR; PG8_MMA(0, 0, At, B0); PG8_MMA(0, 1, At, B1); PG8_BAR; PG8_SCHED;
;             PG8_LDA(At, 0, 1); PG8_STAGE(PG8_SB(0, 0), b2, voffB); PG8_STAGE(PG8_SB(0, 1), b2 + hstep, voffB); PG8_STAGE(PG8_SA(0, 0), a2, voffA);
;             PG8_WAIT_V(8); PG8_WAIT_L(0); PG8_BAR; PG8_MMA(1, 0, At, B0); PG8_MMA(1, 1, At, B1); PG8_BAR; PG8_SCHED;
;             PG8_LDB(B0, 1, 0); PG8_LDB(B1, 1, 1); PG8_SCHED; PG8_LDA(At, 1, 0); PG8_STAGE(PG8_SA(0, 1), a2 + hstep, voffA);
;             PG8_WAIT_V(8); PG8_WAIT_L(0); PG8_BAR; PG8_MMA(0, 0, At, B0); PG8_MMA(0, 1, At, B1); PG8_BAR; PG8_SCHED;
	s_add_i32 s86, s86, s28
	v_lshl_add_u64 v[190:191], s[76:77], 0, v[2:3]
	s_mov_b32 m0, s86
	ds_read_b128 v[178:181], v145 offset:16384
	ds_read_b128 v[182:185], v145 offset:17408
	ds_read_b128 v[186:189], v145 offset:18432
	ds_read_b128 v[204:207], v145 offset:19456
	ds_read_b128 v[208:211], v145 offset:20480
	ds_read_b128 v[212:215], v145 offset:21504
	ds_read_b128 v[216:219], v145 offset:22528
	ds_read_b128 v[220:223], v145 offset:23552
	global_load_lds_dwordx4 v[190:191], off
	s_add_i32 m0, s86, 0x2000
	v_lshl_add_u64 v[224:225], s[76:77], 0, v[136:137]
	s_add_u32 s76, s76, s18
	s_addc_u32 s77, s77, s19
	s_add_i32 s73, s73, s28
	global_load_lds_dwordx4 v[224:225], off
	v_lshl_add_u64 v[226:227], s[76:77], 0, v[2:3]
	s_mov_b32 m0, s73
	v_lshl_add_u64 v[228:229], s[76:77], 0, v[136:137]
	global_load_lds_dwordx4 v[226:227], off
	s_add_i32 m0, s73, 0x2000
	v_lshl_add_u64 v[240:241], s[48:49], 0, v[132:133]
	global_load_lds_dwordx4 v[228:229], off
	s_mov_b32 m0, s47
	v_lshl_add_u64 v[242:243], s[48:49], 0, v[134:135]
	global_load_lds_dwordx4 v[240:241], off
	s_mov_b32 m0, s50
	s_nop 0
	global_load_lds_dwordx4 v[242:243], off
	s_waitcnt vmcnt(8)
	s_waitcnt lgkmcnt(0)
	s_barrier
	s_setprio 1
	s_waitcnt lgkmcnt(0)
	v_mfma_f32_16x16x32_bf16 v[64:67], v[146:149], v[178:181], v[64:67]
	v_mfma_f32_16x16x32_bf16 v[64:67], v[150:153], v[182:185], v[64:67]
	v_mfma_f32_16x16x32_bf16 v[48:51], v[150:153], v[204:207], v[48:51]
	v_mfma_f32_16x16x32_bf16 v[48:51], v[146:149], v[186:189], v[48:51]
	v_mfma_f32_16x16x32_bf16 v[32:35], v[146:149], v[208:211], v[32:35]
	v_mfma_f32_16x16x32_bf16 v[32:35], v[150:153], v[212:215], v[32:35]
	v_mfma_f32_16x16x32_bf16 v[16:19], v[150:153], v[220:223], v[16:19]
	v_mfma_f32_16x16x32_bf16 v[16:19], v[146:149], v[216:219], v[16:19]
	v_mfma_f32_16x16x32_bf16 v[60:63], v[154:157], v[178:181], v[60:63]
	v_mfma_f32_16x16x32_bf16 v[60:63], v[158:161], v[182:185], v[60:63]
	v_mfma_f32_16x16x32_bf16 v[44:47], v[158:161], v[204:207], v[44:47]
	v_mfma_f32_16x16x32_bf16 v[44:47], v[154:157], v[186:189], v[44:47]
	v_mfma_f32_16x16x32_bf16 v[28:31], v[154:157], v[208:211], v[28:31]
	v_mfma_f32_16x16x32_bf16 v[28:31], v[158:161], v[212:215], v[28:31]
	v_mfma_f32_16x16x32_bf16 v[12:15], v[158:161], v[220:223], v[12:15]
	v_mfma_f32_16x16x32_bf16 v[12:15], v[154:157], v[216:219], v[12:15]
	s_setprio 0
	s_setprio 1
	v_mfma_f32_16x16x32_bf16 v[56:59], v[162:165], v[178:181], v[56:59]
	v_mfma_f32_16x16x32_bf16 v[56:59], v[166:169], v[182:185], v[56:59]
	v_mfma_f32_16x16x32_bf16 v[40:43], v[166:169], v[204:207], v[40:43]
	v_mfma_f32_16x16x32_bf16 v[40:43], v[162:165], v[186:189], v[40:43]
	v_mfma_f32_16x16x32_bf16 v[24:27], v[162:165], v[208:211], v[24:27]
	v_mfma_f32_16x16x32_bf16 v[24:27], v[166:169], v[212:215], v[24:27]
	v_mfma_f32_16x16x32_bf16 v[8:11], v[166:169], v[220:223], v[8:11]
	v_mfma_f32_16x16x32_bf16 v[8:11], v[162:165], v[216:219], v[8:11]
	v_mfma_f32_16x16x32_bf16 v[52:55], v[170:173], v[178:181], v[52:55]
	v_mfma_f32_16x16x32_bf16 v[52:55], v[174:177], v[182:185], v[52:55]
	v_mfma_f32_16x16x32_bf16 v[36:39], v[174:177], v[204:207], v[36:39]
	v_mfma_f32_16x16x32_bf16 v[36:39], v[170:173], v[186:189], v[36:39]
	v_mfma_f32_16x16x32_bf16 v[20:23], v[170:173], v[208:211], v[20:23]
	v_mfma_f32_16x16x32_bf16 v[20:23], v[174:177], v[212:215], v[20:23]
	v_mfma_f32_16x16x32_bf16 v[4:7], v[174:177], v[220:223], v[4:7]
	v_mfma_f32_16x16x32_bf16 v[4:7], v[170:173], v[216:219], v[4:7]
	s_setprio 0
	s_barrier
	s_add_i32 s73, 0, 0x18000
	s_add_i32 s76, 0, 0x1c000
	v_add_u32_e32 v158, s73, v143
	v_add_u32_e32 v174, s76, v143
	ds_read_b128 v[146:149], v158
	ds_read_b128 v[150:153], v158 offset:1024
	ds_read_b128 v[154:157], v158 offset:2048
	ds_read_b128 v[158:161], v158 offset:3072
	ds_read_b128 v[162:165], v174
	ds_read_b128 v[166:169], v174 offset:1024
	ds_read_b128 v[170:173], v174 offset:2048
	ds_read_b128 v[174:177], v174 offset:3072
	s_add_u32 s48, s48, s18
	s_addc_u32 s49, s49, s19
	s_mov_b32 m0, s51
	v_lshl_add_u64 v[244:245], s[48:49], 0, v[132:133]
	ds_read_b128 v[178:181], v145 offset:32768
	ds_read_b128 v[182:185], v145 offset:33792
	ds_read_b128 v[186:189], v145 offset:34816
	ds_read_b128 v[204:207], v145 offset:35840
	ds_read_b128 v[208:211], v145 offset:36864
	ds_read_b128 v[212:215], v145 offset:37888
	ds_read_b128 v[216:219], v145 offset:38912
	ds_read_b128 v[220:223], v145 offset:39936
	global_load_lds_dwordx4 v[244:245], off
	v_lshl_add_u64 v[244:245], s[48:49], 0, v[134:135]
	s_mov_b32 m0, s52
	s_nop 0
	global_load_lds_dwordx4 v[244:245], off
	s_waitcnt vmcnt(8)
	s_waitcnt lgkmcnt(0)
	s_barrier
; #define PG8_STAGE(bufoff, gbase, voff) do { _Pragma("unroll") for (int _i = 0; _i < 2; ++_i) \
;         __builtin_amdgcn_global_load_lds((const unsigned*)((const char*)(gbase) + (voff)[_i]), (PG8_LAS unsigned*)(lds + (bufoff) + ldsw + _i * 8192), 16, 0, 0); } while (0)
; #define PG8_LDA(dst, b, h) do { _Pragma("unroll") for (int m = 0; m < 4; ++m) _Pragma("unroll") for (int k = 0; k < 2; ++k) dst[m][k] = *(const PG8_LAS bf16x8*)(lds + PG8_SA(b, h) + aoff + m * 2048 + k * 1024); } while (0)
; #define PG8_WAIT_V(n) asm volatile("s_waitcnt vmcnt(" #n ")" ::: "memory")
; #define PG8_WAIT_L(n) asm volatile("s_waitcnt lgkmcnt(" #n ")" ::: "memory")
; #define PG8_BAR __builtin_amdgcn_s_barrier()
; #define PG8_SCHED __builtin_amdgcn_sched_barrier(0)
; template <class Epi, class Sched, bool ALIGN_EPI = false, bool SP2 = false, bool I8 = false>
; __device__ __forceinline__ void gemm_phase(PG8_LAS unsigned char* lds, const Gemm g, const Sched& S, const Epi& E) {
;     ...
;         for (int t = 0; t < nt; t += 2) {
;             const bool last = (t == nt - 2);
;             const char* a1 = cA + (size_t)(t + 1) * kstep;
;             const char* a2 = last ? nA : cA + (size_t)(t + 2) * kstep; const char* b2 = last ? nB : cB + (size_t)(t + 2) * kstep;
;     ...
;             PG8_WAIT_V(8); PG8_WAIT_L(0); PG8_BAR; PG8_MMA(0, 0, At, B0); PG8_MMA(0, 1, At, B1); PG8_BAR; PG8_SCHED;
;             PG8_LDA(At, 1, 1); PG8_STAGE(PG8_SB(1, 0), b3, voffB); PG8_STAGE(PG8_SB(1, 1), b3 + hstep, voffB); PG8_STAGE(PG8_SA(1, 0), a3, voffA);
;             PG8_WAIT_V(8); PG8_WAIT_L(0); PG8_BAR; PG8_MMA(1, 0, At, B0); PG8_MMA(1, 1, At, B1); PG8_BAR; PG8_SCHED;
	s_setprio 1
	s_waitcnt lgkmcnt(0)
	v_mfma_f32_16x16x32_bf16 v[124:127], v[146:149], v[178:181], v[124:127]
	v_mfma_f32_16x16x32_bf16 v[124:127], v[150:153], v[182:185], v[124:127]
	v_mfma_f32_16x16x32_bf16 v[112:115], v[150:153], v[204:207], v[112:115]
	v_mfma_f32_16x16x32_bf16 v[112:115], v[146:149], v[186:189], v[112:115]
	v_mfma_f32_16x16x32_bf16 v[96:99], v[146:149], v[208:211], v[96:99]
	v_mfma_f32_16x16x32_bf16 v[96:99], v[150:153], v[212:215], v[96:99]
	v_mfma_f32_16x16x32_bf16 v[80:83], v[150:153], v[220:223], v[80:83]
	v_mfma_f32_16x16x32_bf16 v[80:83], v[146:149], v[216:219], v[80:83]
	v_mfma_f32_16x16x32_bf16 v[128:131], v[154:157], v[178:181], v[128:131]
	v_mfma_f32_16x16x32_bf16 v[128:131], v[158:161], v[182:185], v[128:131]
	v_mfma_f32_16x16x32_bf16 v[108:111], v[158:161], v[204:207], v[108:111]
	v_mfma_f32_16x16x32_bf16 v[108:111], v[154:157], v[186:189], v[108:111]
	v_mfma_f32_16x16x32_bf16 v[92:95], v[154:157], v[208:211], v[92:95]
	v_mfma_f32_16x16x32_bf16 v[92:95], v[158:161], v[212:215], v[92:95]
	v_mfma_f32_16x16x32_bf16 v[76:79], v[158:161], v[220:223], v[76:79]
	v_mfma_f32_16x16x32_bf16 v[76:79], v[154:157], v[216:219], v[76:79]
	s_setprio 0
	s_setprio 1
	v_mfma_f32_16x16x32_bf16 v[120:123], v[162:165], v[178:181], v[120:123]
	v_mfma_f32_16x16x32_bf16 v[120:123], v[166:169], v[182:185], v[120:123]
	v_mfma_f32_16x16x32_bf16 v[104:107], v[166:169], v[204:207], v[104:107]
	v_mfma_f32_16x16x32_bf16 v[104:107], v[162:165], v[186:189], v[104:107]
	v_mfma_f32_16x16x32_bf16 v[88:91], v[162:165], v[208:211], v[88:91]
	v_mfma_f32_16x16x32_bf16 v[88:91], v[166:169], v[212:215], v[88:91]
	v_mfma_f32_16x16x32_bf16 v[72:75], v[166:169], v[220:223], v[72:75]
	v_mfma_f32_16x16x32_bf16 v[72:75], v[162:165], v[216:219], v[72:75]
	v_mfma_f32_16x16x32_bf16 v[116:119], v[170:173], v[178:181], v[116:119]
	v_mfma_f32_16x16x32_bf16 v[116:119], v[174:177], v[182:185], v[116:119]
	v_mfma_f32_16x16x32_bf16 v[100:103], v[174:177], v[204:207], v[100:103]
	v_mfma_f32_16x16x32_bf16 v[100:103], v[170:173], v[186:189], v[100:103]
	v_mfma_f32_16x16x32_bf16 v[84:87], v[170:173], v[208:211], v[84:87]
	v_mfma_f32_16x16x32_bf16 v[84:87], v[174:177], v[212:215], v[84:87]
	v_mfma_f32_16x16x32_bf16 v[68:71], v[174:177], v[220:223], v[68:71]
	v_mfma_f32_16x16x32_bf16 v[68:71], v[170:173], v[216:219], v[68:71]
	s_setprio 0
	s_barrier
	s_add_i32 s48, s73, s28
	v_lshl_add_u64 v[190:191], v[190:191], 0, s[84:85]
	s_mov_b32 m0, s48
	ds_read_b128 v[178:181], v145 offset:49152
	ds_read_b128 v[182:185], v145 offset:50176
	ds_read_b128 v[186:189], v145 offset:51200
	ds_read_b128 v[204:207], v145 offset:52224
	ds_read_b128 v[208:211], v145 offset:53248
	ds_read_b128 v[212:215], v145 offset:54272
	ds_read_b128 v[216:219], v145 offset:55296
	ds_read_b128 v[220:223], v145 offset:56320
	global_load_lds_dwordx4 v[190:191], off
	v_lshl_add_u64 v[190:191], v[224:225], 0, s[84:85]
	s_add_i32 m0, s48, 0x2000
	s_add_i32 s48, s76, s28
	global_load_lds_dwordx4 v[190:191], off
	v_lshl_add_u64 v[190:191], v[226:227], 0, s[84:85]
	s_mov_b32 m0, s48
	s_nop 0
	global_load_lds_dwordx4 v[190:191], off
	v_lshl_add_u64 v[190:191], v[228:229], 0, s[84:85]
	s_add_i32 m0, s48, 0x2000
	s_nop 0
	global_load_lds_dwordx4 v[190:191], off
	v_lshl_add_u64 v[190:191], v[240:241], 0, s[84:85]
	s_mov_b32 m0, s55
	s_nop 0
	global_load_lds_dwordx4 v[190:191], off
	v_lshl_add_u64 v[190:191], v[242:243], 0, s[84:85]
	s_mov_b32 m0, s56
	s_nop 0
	global_load_lds_dwordx4 v[190:191], off
	s_waitcnt vmcnt(8)
	s_waitcnt lgkmcnt(0)
	s_barrier
	s_setprio 1
	s_waitcnt lgkmcnt(0)
	v_mfma_f32_16x16x32_bf16 v[64:67], v[146:149], v[178:181], v[64:67]
	v_mfma_f32_16x16x32_bf16 v[64:67], v[150:153], v[182:185], v[64:67]
	v_mfma_f32_16x16x32_bf16 v[48:51], v[150:153], v[204:207], v[48:51]
	v_mfma_f32_16x16x32_bf16 v[48:51], v[146:149], v[186:189], v[48:51]
	v_mfma_f32_16x16x32_bf16 v[32:35], v[146:149], v[208:211], v[32:35]
	v_mfma_f32_16x16x32_bf16 v[32:35], v[150:153], v[212:215], v[32:35]
	v_mfma_f32_16x16x32_bf16 v[16:19], v[150:153], v[220:223], v[16:19]
	v_mfma_f32_16x16x32_bf16 v[16:19], v[146:149], v[216:219], v[16:19]
	v_mfma_f32_16x16x32_bf16 v[60:63], v[154:157], v[178:181], v[60:63]
	v_mfma_f32_16x16x32_bf16 v[60:63], v[158:161], v[182:185], v[60:63]
	v_mfma_f32_16x16x32_bf16 v[44:47], v[158:161], v[204:207], v[44:47]
	v_mfma_f32_16x16x32_bf16 v[44:47], v[154:157], v[186:189], v[44:47]
	v_mfma_f32_16x16x32_bf16 v[28:31], v[154:157], v[208:211], v[28:31]
	v_mfma_f32_16x16x32_bf16 v[28:31], v[158:161], v[212:215], v[28:31]
	v_mfma_f32_16x16x32_bf16 v[12:15], v[158:161], v[220:223], v[12:15]
	v_mfma_f32_16x16x32_bf16 v[12:15], v[154:157], v[216:219], v[12:15]
	s_setprio 0
	s_setprio 1
	v_mfma_f32_16x16x32_bf16 v[56:59], v[162:165], v[178:181], v[56:59]
	v_mfma_f32_16x16x32_bf16 v[56:59], v[166:169], v[182:185], v[56:59]
	v_mfma_f32_16x16x32_bf16 v[40:43], v[166:169], v[204:207], v[40:43]
	v_mfma_f32_16x16x32_bf16 v[40:43], v[162:165], v[186:189], v[40:43]
	v_mfma_f32_16x16x32_bf16 v[24:27], v[162:165], v[208:211], v[24:27]
	v_mfma_f32_16x16x32_bf16 v[24:27], v[166:169], v[212:215], v[24:27]
	v_mfma_f32_16x16x32_bf16 v[8:11], v[166:169], v[220:223], v[8:11]
	v_mfma_f32_16x16x32_bf16 v[8:11], v[162:165], v[216:219], v[8:11]
	v_mfma_f32_16x16x32_bf16 v[52:55], v[170:173], v[178:181], v[52:55]
	v_mfma_f32_16x16x32_bf16 v[52:55], v[174:177], v[182:185], v[52:55]
	v_mfma_f32_16x16x32_bf16 v[36:39], v[174:177], v[204:207], v[36:39]
	v_mfma_f32_16x16x32_bf16 v[36:39], v[170:173], v[186:189], v[36:39]
	v_mfma_f32_16x16x32_bf16 v[20:23], v[170:173], v[208:211], v[20:23]
	v_mfma_f32_16x16x32_bf16 v[20:23], v[174:177], v[212:215], v[20:23]
	v_mfma_f32_16x16x32_bf16 v[4:7], v[174:177], v[220:223], v[4:7]
	v_mfma_f32_16x16x32_bf16 v[4:7], v[170:173], v[216:219], v[4:7]
	s_setprio 0
	s_barrier
	s_add_u32 s44, s44, 0x100
	s_addc_u32 s45, s45, 0
	s_add_u32 s65, s65, 0x100
	s_addc_u32 s67, s67, 0
	s_cmp_ge_i32 s72, s53
	s_mov_b32 s48, s72
	s_cbranch_scc0 .LBB0_1623

; #define PG8_STAGE(bufoff, gbase, voff) do { _Pragma("unroll") for (int _i = 0; _i < 2; ++_i) \
;         __builtin_amdgcn_global_load_lds((const unsigned*)((const char*)(gbase) + (voff)[_i]), (PG8_LAS unsigned*)(lds + (bufoff) + ldsw + _i * 8192), 16, 0, 0); } while (0)
; #define PG8_LDA(dst, b, h) do { _Pragma("unroll") for (int m = 0; m < 4; ++m) _Pragma("unroll") for (int k = 0; k < 2; ++k) dst[m][k] = *(const PG8_LAS bf16x8*)(lds + PG8_SA(b, h) + aoff + m * 2048 + k * 1024); } while (0)
; #define PG8_LDB(dst, b, h) do { _Pragma("unroll") for (int n = 0; n < 2; ++n) _Pragma("unroll") for (int k = 0; k < 2; ++k) dst[n][k] = *(const PG8_LAS bf16x8*)(lds + PG8_SB(b, h) + boff + n * 2048 + k * 1024); } while (0)
; #define PG8_WAIT_V(n) asm volatile("s_waitcnt vmcnt(" #n ")" ::: "memory")
; #define PG8_WAIT_L(n) asm volatile("s_waitcnt lgkmcnt(" #n ")" ::: "memory")
; #define PG8_BAR __builtin_amdgcn_s_barrier()
; #define PG8_SCHED __builtin_amdgcn_sched_barrier(0)
; template <class Epi, class Sched, bool ALIGN_EPI = false, bool SP2 = false, bool I8 = false>
; __device__ __forceinline__ void gemm_phase(PG8_LAS unsigned char* lds, const Gemm g, const Sched& S, const Epi& E) {
;     ...
;         const bool has_next = S.next(ui + 1, nxt);
;         const char* nA = has_next ? (const char*)g.A + (size_t)nxt.pm * tstep : cA; const char* nB = has_next ? (const char*)g.Bt + (size_t)nxt.pn * tstep : cB;
;         for (int t = 0; t < nt; t += 2) {
;             const bool last = (t == nt - 2);
;             const char* a1 = cA + (size_t)(t + 1) * kstep;
;             const char* a2 = last ? nA : cA + (size_t)(t + 2) * kstep; const char* b2 = last ? nB : cB + (size_t)(t + 2) * kstep;
;             const char* a3 = a2 + kstep; const char* b3 = b2 + kstep;
;             if (last && has_next) S.a_ready(nxt);
;             if constexpr (SP2) {
;             PG8_LDB(B0, 0, 0); PG8_LDB(B1, 0, 1); PG8_SCHED; PG8_LDA(At, 0, 0); PG8_STAGE(PG8_SA(1, 1), a1 + hstep, voffA);
;             PG8_WAIT_V(8); PG8_WAIT_L(0); PG8_BAR; PG8_MMA(0, 0, At, B0); PG8_MMA(0, 1, At, B1); PG8_BAR; PG8_SCHED;
;             PG8_LDA(At, 0, 1); PG8_STAGE(PG8_SB(0, 0), b2, voffB); PG8_STAGE(PG8_SB(0, 1), b2 + hstep, voffB); PG8_STAGE(PG8_SA(0, 0), a2, voffA);
;             PG8_WAIT_V(8); PG8_WAIT_L(0); PG8_BAR; PG8_MMA(1, 0, At, B0); PG8_MMA(1, 1, At, B1); PG8_BAR; PG8_SCHED;
.LBB0_1699:
	s_add_u32 s53, s24, 0x100
	s_addc_u32 s54, s25, 0
	s_mov_b32 s55, -2
	s_add_u32 s24, s22, 0x100
	s_addc_u32 s25, s23, 0
	s_add_i32 s56, 0, 0x10000
	s_cmpk_eq_i32 s55, 0xa8
	s_cselect_b32 s37, s13, s25
	s_cselect_b32 s36, s12, s24
	s_cselect_b32 s27, s21, s54
	s_cselect_b32 s26, s20, s53
	s_add_i32 s57, 0, 0x14000
	v_add_u32_e32 v144, s56, v240
	v_add_u32_e32 v160, s57, v240
	ds_read_b128 v[124:127], v144
	ds_read_b128 v[128:131], v144 offset:1024
	ds_read_b128 v[132:135], v144 offset:2048
	ds_read_b128 v[144:147], v144 offset:3072
	ds_read_b128 v[148:151], v160
	ds_read_b128 v[152:155], v160 offset:1024
	ds_read_b128 v[156:159], v160 offset:2048
	ds_read_b128 v[160:163], v160 offset:3072
	v_lshl_add_u64 v[218:219], s[22:23], 0, v[210:211]
	s_add_i32 m0, s42, 0xc000
	ds_read_b128 v[164:167], v242
	ds_read_b128 v[168:171], v242 offset:1024
	ds_read_b128 v[172:175], v242 offset:2048
	ds_read_b128 v[176:179], v242 offset:3072
	ds_read_b128 v[180:183], v242 offset:4096
	ds_read_b128 v[184:187], v242 offset:5120
	ds_read_b128 v[188:191], v242 offset:6144
	ds_read_b128 v[214:217], v242 offset:7168
	global_load_lds_dwordx4 v[218:219], off
	v_lshl_add_u64 v[218:219], s[22:23], 0, v[212:213]
	s_add_i32 m0, s42, 0xe000
	s_nop 0
	global_load_lds_dwordx4 v[218:219], off
	s_waitcnt vmcnt(8)
	s_waitcnt lgkmcnt(0)
	s_barrier
	s_setprio 1
	s_waitcnt lgkmcnt(0)
	v_mfma_f32_16x16x32_bf16 v[140:143], v[124:127], v[164:167], 0
	v_mfma_f32_16x16x32_bf16 v[140:143], v[128:131], v[168:171], v[140:143]
	v_mfma_f32_16x16x32_bf16 v[112:115], v[128:131], v[176:179], 0
	v_mfma_f32_16x16x32_bf16 v[112:115], v[124:127], v[172:175], v[112:115]
	v_mfma_f32_16x16x32_bf16 v[96:99], v[124:127], v[180:183], 0
	v_mfma_f32_16x16x32_bf16 v[96:99], v[128:131], v[184:187], v[96:99]
	v_mfma_f32_16x16x32_bf16 v[80:83], v[128:131], v[214:217], 0
	v_mfma_f32_16x16x32_bf16 v[80:83], v[124:127], v[188:191], v[80:83]
	v_mfma_f32_16x16x32_bf16 v[136:139], v[132:135], v[164:167], 0
	v_mfma_f32_16x16x32_bf16 v[136:139], v[144:147], v[168:171], v[136:139]
	v_mfma_f32_16x16x32_bf16 v[108:111], v[144:147], v[176:179], 0
	v_mfma_f32_16x16x32_bf16 v[108:111], v[132:135], v[172:175], v[108:111]
	v_mfma_f32_16x16x32_bf16 v[92:95], v[132:135], v[180:183], 0
	v_mfma_f32_16x16x32_bf16 v[92:95], v[144:147], v[184:187], v[92:95]
	v_mfma_f32_16x16x32_bf16 v[76:79], v[144:147], v[214:217], 0
	v_mfma_f32_16x16x32_bf16 v[76:79], v[132:135], v[188:191], v[76:79]
	s_setprio 0
	s_setprio 1
	v_mfma_f32_16x16x32_bf16 v[120:123], v[148:151], v[164:167], 0
	v_mfma_f32_16x16x32_bf16 v[120:123], v[152:155], v[168:171], v[120:123]
	v_mfma_f32_16x16x32_bf16 v[104:107], v[152:155], v[176:179], 0
	v_mfma_f32_16x16x32_bf16 v[104:107], v[148:151], v[172:175], v[104:107]
	v_mfma_f32_16x16x32_bf16 v[88:91], v[148:151], v[180:183], 0
	v_mfma_f32_16x16x32_bf16 v[88:91], v[152:155], v[184:187], v[88:91]
	v_mfma_f32_16x16x32_bf16 v[72:75], v[152:155], v[214:217], 0
	v_mfma_f32_16x16x32_bf16 v[72:75], v[148:151], v[188:191], v[72:75]
	v_mfma_f32_16x16x32_bf16 v[116:119], v[156:159], v[164:167], 0
	v_mfma_f32_16x16x32_bf16 v[116:119], v[160:163], v[168:171], v[116:119]
	v_mfma_f32_16x16x32_bf16 v[100:103], v[160:163], v[176:179], 0
	v_mfma_f32_16x16x32_bf16 v[100:103], v[156:159], v[172:175], v[100:103]
	v_mfma_f32_16x16x32_bf16 v[84:87], v[156:159], v[180:183], 0
	v_mfma_f32_16x16x32_bf16 v[84:87], v[160:163], v[184:187], v[84:87]
	v_mfma_f32_16x16x32_bf16 v[68:71], v[160:163], v[214:217], 0
	v_mfma_f32_16x16x32_bf16 v[68:71], v[156:159], v[188:191], v[68:71]
	s_setprio 0
	s_barrier
	s_add_i32 s22, s56, s41
	v_lshl_add_u64 v[218:219], s[26:27], 0, v[2:3]
	s_mov_b32 m0, s22
	ds_read_b128 v[164:167], v242 offset:16384
	ds_read_b128 v[168:171], v242 offset:17408
	ds_read_b128 v[172:175], v242 offset:18432
	ds_read_b128 v[176:179], v242 offset:19456
	ds_read_b128 v[180:183], v242 offset:20480
	ds_read_b128 v[184:187], v242 offset:21504
	ds_read_b128 v[188:191], v242 offset:22528
	ds_read_b128 v[214:217], v242 offset:23552
	global_load_lds_dwordx4 v[218:219], off
	s_add_i32 m0, s22, 0x2000
	s_add_u32 s22, s26, 0x2b0000
	v_lshl_add_u64 v[220:221], s[26:27], 0, v[204:205]
	s_addc_u32 s23, s27, 0
	s_add_i32 s56, s57, s41
	global_load_lds_dwordx4 v[220:221], off
	v_lshl_add_u64 v[222:223], s[22:23], 0, v[2:3]
	s_mov_b32 m0, s56
	v_lshl_add_u64 v[224:225], s[36:37], 0, v[206:207]
	global_load_lds_dwordx4 v[222:223], off
	v_lshl_add_u64 v[222:223], s[22:23], 0, v[204:205]
	s_add_i32 m0, s56, 0x2000
	s_nop 0
	global_load_lds_dwordx4 v[222:223], off
	v_lshl_add_u64 v[222:223], s[36:37], 0, v[208:209]
	s_mov_b32 m0, s42
	s_nop 0
	global_load_lds_dwordx4 v[222:223], off
	s_mov_b32 m0, s43
	s_nop 0
	global_load_lds_dwordx4 v[224:225], off
	s_waitcnt vmcnt(8)
	s_waitcnt lgkmcnt(0)
	s_barrier
; #define PG8_STAGE(bufoff, gbase, voff) do { _Pragma("unroll") for (int _i = 0; _i < 2; ++_i) \
;         __builtin_amdgcn_global_load_lds((const unsigned*)((const char*)(gbase) + (voff)[_i]), (PG8_LAS unsigned*)(lds + (bufoff) + ldsw + _i * 8192), 16, 0, 0); } while (0)
; #define PG8_LDA(dst, b, h) do { _Pragma("unroll") for (int m = 0; m < 4; ++m) _Pragma("unroll") for (int k = 0; k < 2; ++k) dst[m][k] = *(const PG8_LAS bf16x8*)(lds + PG8_SA(b, h) + aoff + m * 2048 + k * 1024); } while (0)
; #define PG8_LDB(dst, b, h) do { _Pragma("unroll") for (int n = 0; n < 2; ++n) _Pragma("unroll") for (int k = 0; k < 2; ++k) dst[n][k] = *(const PG8_LAS bf16x8*)(lds + PG8_SB(b, h) + boff + n * 2048 + k * 1024); } while (0)
; #define PG8_WAIT_V(n) asm volatile("s_waitcnt vmcnt(" #n ")" ::: "memory")
; #define PG8_WAIT_L(n) asm volatile("s_waitcnt lgkmcnt(" #n ")" ::: "memory")
; #define PG8_BAR __builtin_amdgcn_s_barrier()
; #define PG8_SCHED __builtin_amdgcn_sched_barrier(0)
; template <class Epi, class Sched, bool ALIGN_EPI = false, bool SP2 = false, bool I8 = false>
; __device__ __forceinline__ void gemm_phase(PG8_LAS unsigned char* lds, const Gemm g, const Sched& S, const Epi& E) {
;     ...
;             PG8_WAIT_V(8); PG8_WAIT_L(0); PG8_BAR; PG8_MMA(1, 0, At, B0); PG8_MMA(1, 1, At, B1); PG8_BAR; PG8_SCHED;
;             PG8_LDB(B0, 1, 0); PG8_LDB(B1, 1, 1); PG8_SCHED; PG8_LDA(At, 1, 0); PG8_STAGE(PG8_SA(0, 1), a2 + hstep, voffA);
;             PG8_WAIT_V(8); PG8_WAIT_L(0); PG8_BAR; PG8_MMA(0, 0, At, B0); PG8_MMA(0, 1, At, B1); PG8_BAR; PG8_SCHED;
	s_setprio 1
	s_waitcnt lgkmcnt(0)
	v_mfma_f32_16x16x32_bf16 v[64:67], v[124:127], v[164:167], 0
	v_mfma_f32_16x16x32_bf16 v[64:67], v[128:131], v[168:171], v[64:67]
	v_mfma_f32_16x16x32_bf16 v[48:51], v[128:131], v[176:179], 0
	v_mfma_f32_16x16x32_bf16 v[48:51], v[124:127], v[172:175], v[48:51]
	v_mfma_f32_16x16x32_bf16 v[32:35], v[124:127], v[180:183], 0
	v_mfma_f32_16x16x32_bf16 v[32:35], v[128:131], v[184:187], v[32:35]
	v_mfma_f32_16x16x32_bf16 v[16:19], v[128:131], v[214:217], 0
	v_mfma_f32_16x16x32_bf16 v[16:19], v[124:127], v[188:191], v[16:19]
	v_mfma_f32_16x16x32_bf16 v[60:63], v[132:135], v[164:167], 0
	v_mfma_f32_16x16x32_bf16 v[60:63], v[144:147], v[168:171], v[60:63]
	v_mfma_f32_16x16x32_bf16 v[44:47], v[144:147], v[176:179], 0
	v_mfma_f32_16x16x32_bf16 v[44:47], v[132:135], v[172:175], v[44:47]
	v_mfma_f32_16x16x32_bf16 v[28:31], v[132:135], v[180:183], 0
	v_mfma_f32_16x16x32_bf16 v[28:31], v[144:147], v[184:187], v[28:31]
	v_mfma_f32_16x16x32_bf16 v[12:15], v[144:147], v[214:217], 0
	v_mfma_f32_16x16x32_bf16 v[12:15], v[132:135], v[188:191], v[12:15]
	s_setprio 0
	s_setprio 1
	v_mfma_f32_16x16x32_bf16 v[56:59], v[148:151], v[164:167], 0
	v_mfma_f32_16x16x32_bf16 v[56:59], v[152:155], v[168:171], v[56:59]
	v_mfma_f32_16x16x32_bf16 v[40:43], v[152:155], v[176:179], 0
	v_mfma_f32_16x16x32_bf16 v[40:43], v[148:151], v[172:175], v[40:43]
	v_mfma_f32_16x16x32_bf16 v[24:27], v[148:151], v[180:183], 0
	v_mfma_f32_16x16x32_bf16 v[24:27], v[152:155], v[184:187], v[24:27]
	v_mfma_f32_16x16x32_bf16 v[8:11], v[152:155], v[214:217], 0
	v_mfma_f32_16x16x32_bf16 v[8:11], v[148:151], v[188:191], v[8:11]
	v_mfma_f32_16x16x32_bf16 v[52:55], v[156:159], v[164:167], 0
	v_mfma_f32_16x16x32_bf16 v[52:55], v[160:163], v[168:171], v[52:55]
	v_mfma_f32_16x16x32_bf16 v[36:39], v[160:163], v[176:179], 0
	v_mfma_f32_16x16x32_bf16 v[36:39], v[156:159], v[172:175], v[36:39]
	v_mfma_f32_16x16x32_bf16 v[20:23], v[156:159], v[180:183], 0
	v_mfma_f32_16x16x32_bf16 v[20:23], v[160:163], v[184:187], v[20:23]
	v_mfma_f32_16x16x32_bf16 v[4:7], v[160:163], v[214:217], 0
	v_mfma_f32_16x16x32_bf16 v[4:7], v[156:159], v[188:191], v[4:7]
	s_setprio 0
	s_barrier
	s_add_i32 s56, 0, 0x18000
	s_add_i32 s57, 0, 0x1c000
	v_add_u32_e32 v144, s56, v240
	v_add_u32_e32 v160, s57, v240
	ds_read_b128 v[124:127], v144
	ds_read_b128 v[128:131], v144 offset:1024
	ds_read_b128 v[132:135], v144 offset:2048
	ds_read_b128 v[144:147], v144 offset:3072
	ds_read_b128 v[148:151], v160
	ds_read_b128 v[152:155], v160 offset:1024
	ds_read_b128 v[156:159], v160 offset:2048
	ds_read_b128 v[160:163], v160 offset:3072
	s_add_u32 s22, s36, 0x2b0000
	s_addc_u32 s23, s37, 0
	s_mov_b32 m0, s44
	v_lshl_add_u64 v[226:227], s[22:23], 0, v[208:209]
	ds_read_b128 v[164:167], v242 offset:32768
	ds_read_b128 v[168:171], v242 offset:33792
	ds_read_b128 v[172:175], v242 offset:34816
	ds_read_b128 v[176:179], v242 offset:35840
	ds_read_b128 v[180:183], v242 offset:36864
	ds_read_b128 v[184:187], v242 offset:37888
	ds_read_b128 v[188:191], v242 offset:38912
	ds_read_b128 v[214:217], v242 offset:39936
	global_load_lds_dwordx4 v[226:227], off
	v_lshl_add_u64 v[226:227], s[22:23], 0, v[206:207]
	s_mov_b32 m0, s45
	s_nop 0
	global_load_lds_dwordx4 v[226:227], off
	s_waitcnt vmcnt(8)
	s_waitcnt lgkmcnt(0)
	s_barrier
	s_setprio 1
	s_waitcnt lgkmcnt(0)
	v_mfma_f32_16x16x32_bf16 v[140:143], v[124:127], v[164:167], v[140:143]
	v_mfma_f32_16x16x32_bf16 v[140:143], v[128:131], v[168:171], v[140:143]
	v_mfma_f32_16x16x32_bf16 v[112:115], v[128:131], v[176:179], v[112:115]
	v_mfma_f32_16x16x32_bf16 v[112:115], v[124:127], v[172:175], v[112:115]
	v_mfma_f32_16x16x32_bf16 v[96:99], v[124:127], v[180:183], v[96:99]
	v_mfma_f32_16x16x32_bf16 v[96:99], v[128:131], v[184:187], v[96:99]
	v_mfma_f32_16x16x32_bf16 v[80:83], v[128:131], v[214:217], v[80:83]
	v_mfma_f32_16x16x32_bf16 v[80:83], v[124:127], v[188:191], v[80:83]
	v_mfma_f32_16x16x32_bf16 v[136:139], v[132:135], v[164:167], v[136:139]
	v_mfma_f32_16x16x32_bf16 v[136:139], v[144:147], v[168:171], v[136:139]
	v_mfma_f32_16x16x32_bf16 v[108:111], v[144:147], v[176:179], v[108:111]
	v_mfma_f32_16x16x32_bf16 v[108:111], v[132:135], v[172:175], v[108:111]
	v_mfma_f32_16x16x32_bf16 v[92:95], v[132:135], v[180:183], v[92:95]
	v_mfma_f32_16x16x32_bf16 v[92:95], v[144:147], v[184:187], v[92:95]
	v_mfma_f32_16x16x32_bf16 v[76:79], v[144:147], v[214:217], v[76:79]
	v_mfma_f32_16x16x32_bf16 v[76:79], v[132:135], v[188:191], v[76:79]
	s_setprio 0
	s_setprio 1
	v_mfma_f32_16x16x32_bf16 v[120:123], v[148:151], v[164:167], v[120:123]
	v_mfma_f32_16x16x32_bf16 v[120:123], v[152:155], v[168:171], v[120:123]
	v_mfma_f32_16x16x32_bf16 v[104:107], v[152:155], v[176:179], v[104:107]
	v_mfma_f32_16x16x32_bf16 v[104:107], v[148:151], v[172:175], v[104:107]
	v_mfma_f32_16x16x32_bf16 v[88:91], v[148:151], v[180:183], v[88:91]
	v_mfma_f32_16x16x32_bf16 v[88:91], v[152:155], v[184:187], v[88:91]
	v_mfma_f32_16x16x32_bf16 v[72:75], v[152:155], v[214:217], v[72:75]
	v_mfma_f32_16x16x32_bf16 v[72:75], v[148:151], v[188:191], v[72:75]
	v_mfma_f32_16x16x32_bf16 v[116:119], v[156:159], v[164:167], v[116:119]
	v_mfma_f32_16x16x32_bf16 v[116:119], v[160:163], v[168:171], v[116:119]
	v_mfma_f32_16x16x32_bf16 v[100:103], v[160:163], v[176:179], v[100:103]
	v_mfma_f32_16x16x32_bf16 v[100:103], v[156:159], v[172:175], v[100:103]
	v_mfma_f32_16x16x32_bf16 v[84:87], v[156:159], v[180:183], v[84:87]
	v_mfma_f32_16x16x32_bf16 v[84:87], v[160:163], v[184:187], v[84:87]
	v_mfma_f32_16x16x32_bf16 v[68:71], v[160:163], v[214:217], v[68:71]
	v_mfma_f32_16x16x32_bf16 v[68:71], v[156:159], v[188:191], v[68:71]
	s_setprio 0
	s_barrier
; #define PG8_STAGE(bufoff, gbase, voff) do { _Pragma("unroll") for (int _i = 0; _i < 2; ++_i) \
;         __builtin_amdgcn_global_load_lds((const unsigned*)((const char*)(gbase) + (voff)[_i]), (PG8_LAS unsigned*)(lds + (bufoff) + ldsw + _i * 8192), 16, 0, 0); } while (0)
; #define PG8_LDA(dst, b, h) do { _Pragma("unroll") for (int m = 0; m < 4; ++m) _Pragma("unroll") for (int k = 0; k < 2; ++k) dst[m][k] = *(const PG8_LAS bf16x8*)(lds + PG8_SA(b, h) + aoff + m * 2048 + k * 1024); } while (0)
; #define PG8_LDB(dst, b, h) do { _Pragma("unroll") for (int n = 0; n < 2; ++n) _Pragma("unroll") for (int k = 0; k < 2; ++k) dst[n][k] = *(const PG8_LAS bf16x8*)(lds + PG8_SB(b, h) + boff + n * 2048 + k * 1024); } while (0)
; #define PG8_WAIT_V(n) asm volatile("s_waitcnt vmcnt(" #n ")" ::: "memory")
; template <class Epi, class Sched, bool ALIGN_EPI = false, bool SP2 = false, bool I8 = false>
; __device__ __forceinline__ void gemm_phase(PG8_LAS unsigned char* lds, const Gemm g, const Sched& S, const Epi& E) {
;     ...
;             const char* a1 = cA + (size_t)(t + 1) * kstep;
;             const char* a2 = last ? nA : cA + (size_t)(t + 2) * kstep; const char* b2 = last ? nB : cB + (size_t)(t + 2) * kstep;
;             const char* a3 = a2 + kstep; const char* b3 = b2 + kstep;
;             if (last && has_next) S.a_ready(nxt);
;             if constexpr (SP2) {
;             PG8_LDB(B0, 0, 0); PG8_LDB(B1, 0, 1); PG8_SCHED; PG8_LDA(At, 0, 0); PG8_STAGE(PG8_SA(1, 1), a1 + hstep, voffA);
;             PG8_WAIT_V(8); PG8_WAIT_L(0); PG8_BAR; PG8_MMA(0, 0, At, B0); PG8_MMA(0, 1, At, B1); PG8_BAR; PG8_SCHED;
;             PG8_LDA(At, 0, 1); PG8_STAGE(PG8_SB(0, 0), b2, voffB); PG8_STAGE(PG8_SB(0, 1), b2 + hstep, voffB); PG8_STAGE(PG8_SA(0, 0), a2, voffA);
;             PG8_WAIT_V(8); PG8_WAIT_L(0); PG8_BAR; PG8_MMA(1, 0, At, B0); PG8_MMA(1, 1, At, B1); PG8_BAR; PG8_SCHED;
;             PG8_LDB(B0, 1, 0); PG8_LDB(B1, 1, 1); PG8_SCHED; PG8_LDA(At, 1, 0); PG8_STAGE(PG8_SA(0, 1), a2 + hstep, voffA);
;             PG8_WAIT_V(8); PG8_WAIT_L(0); PG8_BAR; PG8_MMA(0, 0, At, B0); PG8_MMA(0, 1, At, B1); PG8_BAR; PG8_SCHED;
;             PG8_LDA(At, 1, 1); PG8_STAGE(PG8_SB(1, 0), b3, voffB); PG8_STAGE(PG8_SB(1, 1), b3 + hstep, voffB); PG8_STAGE(PG8_SA(1, 0), a3, voffA);
;             PG8_WAIT_V(8); PG8_WAIT_L(0); PG8_BAR; PG8_MMA(1, 0, At, B0); PG8_MMA(1, 1, At, B1); PG8_BAR; PG8_SCHED;
	s_add_i32 s22, s56, s41
	v_lshl_add_u64 v[218:219], v[218:219], 0, s[84:85]
	s_mov_b32 m0, s22
	ds_read_b128 v[164:167], v242 offset:49152
	ds_read_b128 v[168:171], v242 offset:50176
	ds_read_b128 v[172:175], v242 offset:51200
	ds_read_b128 v[176:179], v242 offset:52224
	ds_read_b128 v[180:183], v242 offset:53248
	ds_read_b128 v[184:187], v242 offset:54272
	ds_read_b128 v[188:191], v242 offset:55296
	ds_read_b128 v[214:217], v242 offset:56320
	global_load_lds_dwordx4 v[218:219], off
	s_add_i32 m0, s22, 0x2000
	s_add_u32 s22, s26, 0x2b0080
	v_lshl_add_u64 v[218:219], v[220:221], 0, s[84:85]
	s_addc_u32 s23, s27, 0
	s_add_i32 s26, s57, s41
	global_load_lds_dwordx4 v[218:219], off
	v_lshl_add_u64 v[218:219], s[22:23], 0, v[2:3]
	s_mov_b32 m0, s26
	s_nop 0
	global_load_lds_dwordx4 v[218:219], off
	v_lshl_add_u64 v[218:219], s[22:23], 0, v[204:205]
	s_add_i32 m0, s26, 0x2000
	s_nop 0
	global_load_lds_dwordx4 v[218:219], off
	v_lshl_add_u64 v[218:219], v[222:223], 0, s[84:85]
	s_mov_b32 m0, s46
	s_nop 0
	global_load_lds_dwordx4 v[218:219], off
	v_lshl_add_u64 v[218:219], v[224:225], 0, s[84:85]
	s_mov_b32 m0, s47
	s_nop 0
	global_load_lds_dwordx4 v[218:219], off
	s_waitcnt vmcnt(8)
	s_waitcnt lgkmcnt(0)
	s_barrier
	s_setprio 1
	s_waitcnt lgkmcnt(0)
	v_mfma_f32_16x16x32_bf16 v[64:67], v[124:127], v[164:167], v[64:67]
	v_mfma_f32_16x16x32_bf16 v[64:67], v[128:131], v[168:171], v[64:67]
	v_mfma_f32_16x16x32_bf16 v[48:51], v[128:131], v[176:179], v[48:51]
	v_mfma_f32_16x16x32_bf16 v[48:51], v[124:127], v[172:175], v[48:51]
	v_mfma_f32_16x16x32_bf16 v[32:35], v[124:127], v[180:183], v[32:35]
	v_mfma_f32_16x16x32_bf16 v[32:35], v[128:131], v[184:187], v[32:35]
	v_mfma_f32_16x16x32_bf16 v[16:19], v[128:131], v[214:217], v[16:19]
	v_mfma_f32_16x16x32_bf16 v[16:19], v[124:127], v[188:191], v[16:19]
	v_mfma_f32_16x16x32_bf16 v[60:63], v[132:135], v[164:167], v[60:63]
	v_mfma_f32_16x16x32_bf16 v[60:63], v[144:147], v[168:171], v[60:63]
	v_mfma_f32_16x16x32_bf16 v[44:47], v[144:147], v[176:179], v[44:47]
	v_mfma_f32_16x16x32_bf16 v[44:47], v[132:135], v[172:175], v[44:47]
	v_mfma_f32_16x16x32_bf16 v[28:31], v[132:135], v[180:183], v[28:31]
	v_mfma_f32_16x16x32_bf16 v[28:31], v[144:147], v[184:187], v[28:31]
	v_mfma_f32_16x16x32_bf16 v[12:15], v[144:147], v[214:217], v[12:15]
	v_mfma_f32_16x16x32_bf16 v[12:15], v[132:135], v[188:191], v[12:15]
	s_setprio 0
	s_setprio 1
	v_mfma_f32_16x16x32_bf16 v[56:59], v[148:151], v[164:167], v[56:59]
	v_mfma_f32_16x16x32_bf16 v[56:59], v[152:155], v[168:171], v[56:59]
	v_mfma_f32_16x16x32_bf16 v[40:43], v[152:155], v[176:179], v[40:43]
	v_mfma_f32_16x16x32_bf16 v[40:43], v[148:151], v[172:175], v[40:43]
	v_mfma_f32_16x16x32_bf16 v[24:27], v[148:151], v[180:183], v[24:27]
	v_mfma_f32_16x16x32_bf16 v[24:27], v[152:155], v[184:187], v[24:27]
	v_mfma_f32_16x16x32_bf16 v[8:11], v[152:155], v[214:217], v[8:11]
	v_mfma_f32_16x16x32_bf16 v[8:11], v[148:151], v[188:191], v[8:11]
	v_mfma_f32_16x16x32_bf16 v[52:55], v[156:159], v[164:167], v[52:55]
	v_mfma_f32_16x16x32_bf16 v[52:55], v[160:163], v[168:171], v[52:55]
	v_mfma_f32_16x16x32_bf16 v[36:39], v[160:163], v[176:179], v[36:39]
	v_mfma_f32_16x16x32_bf16 v[36:39], v[156:159], v[172:175], v[36:39]
	v_mfma_f32_16x16x32_bf16 v[20:23], v[156:159], v[180:183], v[20:23]
	v_mfma_f32_16x16x32_bf16 v[20:23], v[160:163], v[184:187], v[20:23]
	v_mfma_f32_16x16x32_bf16 v[4:7], v[160:163], v[214:217], v[4:7]
	v_mfma_f32_16x16x32_bf16 v[4:7], v[156:159], v[188:191], v[4:7]
	s_setprio 0
	s_barrier
	s_add_i32 s55, s55, 2
	s_add_u32 s53, s53, 0x100
	s_addc_u32 s54, s54, 0
	s_cmpk_gt_u32 s55, 0xa9
	s_mov_b64 s[22:23], s[24:25]
	s_cbranch_scc1 .Lkloop_exit_5
.LBB0_1700:
	s_add_u32 s24, s22, 0x100
	s_addc_u32 s25, s23, 0
	s_add_i32 s56, 0, 0x10000
	s_cmpk_eq_i32 s55, 0xa8
	s_cselect_b32 s37, s13, s25
	s_cselect_b32 s36, s12, s24
	s_cselect_b32 s27, s21, s54
	s_cselect_b32 s26, s20, s53
	s_add_i32 s57, 0, 0x14000
	v_add_u32_e32 v144, s56, v240
	v_add_u32_e32 v160, s57, v240
	ds_read_b128 v[124:127], v144
	ds_read_b128 v[128:131], v144 offset:1024
	ds_read_b128 v[132:135], v144 offset:2048
	ds_read_b128 v[144:147], v144 offset:3072
	ds_read_b128 v[148:151], v160
	ds_read_b128 v[152:155], v160 offset:1024
	ds_read_b128 v[156:159], v160 offset:2048
	ds_read_b128 v[160:163], v160 offset:3072
	v_lshl_add_u64 v[218:219], s[22:23], 0, v[210:211]
	s_add_i32 m0, s42, 0xc000
	ds_read_b128 v[164:167], v242
	ds_read_b128 v[168:171], v242 offset:1024
	ds_read_b128 v[172:175], v242 offset:2048
	ds_read_b128 v[176:179], v242 offset:3072
	ds_read_b128 v[180:183], v242 offset:4096
	ds_read_b128 v[184:187], v242 offset:5120
	ds_read_b128 v[188:191], v242 offset:6144
	ds_read_b128 v[214:217], v242 offset:7168
	global_load_lds_dwordx4 v[218:219], off
	v_lshl_add_u64 v[218:219], s[22:23], 0, v[212:213]
	s_add_i32 m0, s42, 0xe000
	s_nop 0
	global_load_lds_dwordx4 v[218:219], off
	s_waitcnt vmcnt(8)
	s_waitcnt lgkmcnt(0)
	s_barrier
; #define PG8_STAGE(bufoff, gbase, voff) do { _Pragma("unroll") for (int _i = 0; _i < 2; ++_i) \
;         __builtin_amdgcn_global_load_lds((const unsigned*)((const char*)(gbase) + (voff)[_i]), (PG8_LAS unsigned*)(lds + (bufoff) + ldsw + _i * 8192), 16, 0, 0); } while (0)
; #define PG8_LDA(dst, b, h) do { _Pragma("unroll") for (int m = 0; m < 4; ++m) _Pragma("unroll") for (int k = 0; k < 2; ++k) dst[m][k] = *(const PG8_LAS bf16x8*)(lds + PG8_SA(b, h) + aoff + m * 2048 + k * 1024); } while (0)
; #define PG8_LDB(dst, b, h) do { _Pragma("unroll") for (int n = 0; n < 2; ++n) _Pragma("unroll") for (int k = 0; k < 2; ++k) dst[n][k] = *(const PG8_LAS bf16x8*)(lds + PG8_SB(b, h) + boff + n * 2048 + k * 1024); } while (0)
; #define PG8_WAIT_V(n) asm volatile("s_waitcnt vmcnt(" #n ")" ::: "memory")
; #define PG8_WAIT_L(n) asm volatile("s_waitcnt lgkmcnt(" #n ")" ::: "memory")
; #define PG8_BAR __builtin_amdgcn_s_barrier()
; #define PG8_SCHED __builtin_amdgcn_sched_barrier(0)
; template <class Epi, class Sched, bool ALIGN_EPI = false, bool SP2 = false, bool I8 = false>
; __device__ __forceinline__ void gemm_phase(PG8_LAS unsigned char* lds, const Gemm g, const Sched& S, const Epi& E) {
;     ...
;             PG8_LDB(B0, 0, 0); PG8_LDB(B1, 0, 1); PG8_SCHED; PG8_LDA(At, 0, 0); PG8_STAGE(PG8_SA(1, 1), a1 + hstep, voffA);
;             PG8_WAIT_V(8); PG8_WAIT_L(0); PG8_BAR; PG8_MMA(0, 0, At, B0); PG8_MMA(0, 1, At, B1); PG8_BAR; PG8_SCHED;
;             PG8_LDA(At, 0, 1); PG8_STAGE(PG8_SB(0, 0), b2, voffB); PG8_STAGE(PG8_SB(0, 1), b2 + hstep, voffB); PG8_STAGE(PG8_SA(0, 0), a2, voffA);
;             PG8_WAIT_V(8); PG8_WAIT_L(0); PG8_BAR; PG8_MMA(1, 0, At, B0); PG8_MMA(1, 1, At, B1); PG8_BAR; PG8_SCHED;
	s_setprio 1
	s_waitcnt lgkmcnt(0)
	v_mfma_f32_16x16x32_bf16 v[140:143], v[124:127], v[164:167], v[140:143]
	v_mfma_f32_16x16x32_bf16 v[140:143], v[128:131], v[168:171], v[140:143]
	v_mfma_f32_16x16x32_bf16 v[112:115], v[128:131], v[176:179], v[112:115]
	v_mfma_f32_16x16x32_bf16 v[112:115], v[124:127], v[172:175], v[112:115]
	v_mfma_f32_16x16x32_bf16 v[96:99], v[124:127], v[180:183], v[96:99]
	v_mfma_f32_16x16x32_bf16 v[96:99], v[128:131], v[184:187], v[96:99]
	v_mfma_f32_16x16x32_bf16 v[80:83], v[128:131], v[214:217], v[80:83]
	v_mfma_f32_16x16x32_bf16 v[80:83], v[124:127], v[188:191], v[80:83]
	v_mfma_f32_16x16x32_bf16 v[136:139], v[132:135], v[164:167], v[136:139]
	v_mfma_f32_16x16x32_bf16 v[136:139], v[144:147], v[168:171], v[136:139]
	v_mfma_f32_16x16x32_bf16 v[108:111], v[144:147], v[176:179], v[108:111]
	v_mfma_f32_16x16x32_bf16 v[108:111], v[132:135], v[172:175], v[108:111]
	v_mfma_f32_16x16x32_bf16 v[92:95], v[132:135], v[180:183], v[92:95]
	v_mfma_f32_16x16x32_bf16 v[92:95], v[144:147], v[184:187], v[92:95]
	v_mfma_f32_16x16x32_bf16 v[76:79], v[144:147], v[214:217], v[76:79]
	v_mfma_f32_16x16x32_bf16 v[76:79], v[132:135], v[188:191], v[76:79]
	s_setprio 0
	s_setprio 1
	v_mfma_f32_16x16x32_bf16 v[120:123], v[148:151], v[164:167], v[120:123]
	v_mfma_f32_16x16x32_bf16 v[120:123], v[152:155], v[168:171], v[120:123]
	v_mfma_f32_16x16x32_bf16 v[104:107], v[152:155], v[176:179], v[104:107]
	v_mfma_f32_16x16x32_bf16 v[104:107], v[148:151], v[172:175], v[104:107]
	v_mfma_f32_16x16x32_bf16 v[88:91], v[148:151], v[180:183], v[88:91]
	v_mfma_f32_16x16x32_bf16 v[88:91], v[152:155], v[184:187], v[88:91]
	v_mfma_f32_16x16x32_bf16 v[72:75], v[152:155], v[214:217], v[72:75]
	v_mfma_f32_16x16x32_bf16 v[72:75], v[148:151], v[188:191], v[72:75]
	v_mfma_f32_16x16x32_bf16 v[116:119], v[156:159], v[164:167], v[116:119]
	v_mfma_f32_16x16x32_bf16 v[116:119], v[160:163], v[168:171], v[116:119]
	v_mfma_f32_16x16x32_bf16 v[100:103], v[160:163], v[176:179], v[100:103]
	v_mfma_f32_16x16x32_bf16 v[100:103], v[156:159], v[172:175], v[100:103]
	v_mfma_f32_16x16x32_bf16 v[84:87], v[156:159], v[180:183], v[84:87]
	v_mfma_f32_16x16x32_bf16 v[84:87], v[160:163], v[184:187], v[84:87]
	v_mfma_f32_16x16x32_bf16 v[68:71], v[160:163], v[214:217], v[68:71]
	v_mfma_f32_16x16x32_bf16 v[68:71], v[156:159], v[188:191], v[68:71]
	s_setprio 0
	s_barrier
	s_add_i32 s22, s56, s41
	v_lshl_add_u64 v[218:219], s[26:27], 0, v[2:3]
	s_mov_b32 m0, s22
	ds_read_b128 v[164:167], v242 offset:16384
	ds_read_b128 v[168:171], v242 offset:17408
	ds_read_b128 v[172:175], v242 offset:18432
	ds_read_b128 v[176:179], v242 offset:19456
	ds_read_b128 v[180:183], v242 offset:20480
	ds_read_b128 v[184:187], v242 offset:21504
	ds_read_b128 v[188:191], v242 offset:22528
	ds_read_b128 v[214:217], v242 offset:23552
	global_load_lds_dwordx4 v[218:219], off
	s_add_i32 m0, s22, 0x2000
	s_add_u32 s22, s26, 0x2b0000
	v_lshl_add_u64 v[220:221], s[26:27], 0, v[204:205]
	s_addc_u32 s23, s27, 0
	s_add_i32 s56, s57, s41
	global_load_lds_dwordx4 v[220:221], off
	v_lshl_add_u64 v[222:223], s[22:23], 0, v[2:3]
	s_mov_b32 m0, s56
	v_lshl_add_u64 v[224:225], s[36:37], 0, v[206:207]
	global_load_lds_dwordx4 v[222:223], off
	v_lshl_add_u64 v[222:223], s[22:23], 0, v[204:205]
	s_add_i32 m0, s56, 0x2000
	s_nop 0
	global_load_lds_dwordx4 v[222:223], off
	v_lshl_add_u64 v[222:223], s[36:37], 0, v[208:209]
	s_mov_b32 m0, s42
	s_nop 0
	global_load_lds_dwordx4 v[222:223], off
	s_mov_b32 m0, s43
	s_nop 0
	global_load_lds_dwordx4 v[224:225], off
	s_waitcnt vmcnt(8)
	s_waitcnt lgkmcnt(0)
	s_barrier
	s_setprio 1
	s_waitcnt lgkmcnt(0)
	v_mfma_f32_16x16x32_bf16 v[64:67], v[124:127], v[164:167], v[64:67]
	v_mfma_f32_16x16x32_bf16 v[64:67], v[128:131], v[168:171], v[64:67]
	v_mfma_f32_16x16x32_bf16 v[48:51], v[128:131], v[176:179], v[48:51]
	v_mfma_f32_16x16x32_bf16 v[48:51], v[124:127], v[172:175], v[48:51]
	v_mfma_f32_16x16x32_bf16 v[32:35], v[124:127], v[180:183], v[32:35]
	v_mfma_f32_16x16x32_bf16 v[32:35], v[128:131], v[184:187], v[32:35]
	v_mfma_f32_16x16x32_bf16 v[16:19], v[128:131], v[214:217], v[16:19]
	v_mfma_f32_16x16x32_bf16 v[16:19], v[124:127], v[188:191], v[16:19]
	v_mfma_f32_16x16x32_bf16 v[60:63], v[132:135], v[164:167], v[60:63]
	v_mfma_f32_16x16x32_bf16 v[60:63], v[144:147], v[168:171], v[60:63]
	v_mfma_f32_16x16x32_bf16 v[44:47], v[144:147], v[176:179], v[44:47]
	v_mfma_f32_16x16x32_bf16 v[44:47], v[132:135], v[172:175], v[44:47]
	v_mfma_f32_16x16x32_bf16 v[28:31], v[132:135], v[180:183], v[28:31]
	v_mfma_f32_16x16x32_bf16 v[28:31], v[144:147], v[184:187], v[28:31]
	v_mfma_f32_16x16x32_bf16 v[12:15], v[144:147], v[214:217], v[12:15]
	v_mfma_f32_16x16x32_bf16 v[12:15], v[132:135], v[188:191], v[12:15]
	s_setprio 0
	s_setprio 1
	v_mfma_f32_16x16x32_bf16 v[56:59], v[148:151], v[164:167], v[56:59]
	v_mfma_f32_16x16x32_bf16 v[56:59], v[152:155], v[168:171], v[56:59]
	v_mfma_f32_16x16x32_bf16 v[40:43], v[152:155], v[176:179], v[40:43]
	v_mfma_f32_16x16x32_bf16 v[40:43], v[148:151], v[172:175], v[40:43]
	v_mfma_f32_16x16x32_bf16 v[24:27], v[148:151], v[180:183], v[24:27]
	v_mfma_f32_16x16x32_bf16 v[24:27], v[152:155], v[184:187], v[24:27]
	v_mfma_f32_16x16x32_bf16 v[8:11], v[152:155], v[214:217], v[8:11]
	v_mfma_f32_16x16x32_bf16 v[8:11], v[148:151], v[188:191], v[8:11]
	v_mfma_f32_16x16x32_bf16 v[52:55], v[156:159], v[164:167], v[52:55]
	v_mfma_f32_16x16x32_bf16 v[52:55], v[160:163], v[168:171], v[52:55]
	v_mfma_f32_16x16x32_bf16 v[36:39], v[160:163], v[176:179], v[36:39]
	v_mfma_f32_16x16x32_bf16 v[36:39], v[156:159], v[172:175], v[36:39]
	v_mfma_f32_16x16x32_bf16 v[20:23], v[156:159], v[180:183], v[20:23]
	v_mfma_f32_16x16x32_bf16 v[20:23], v[160:163], v[184:187], v[20:23]
	v_mfma_f32_16x16x32_bf16 v[4:7], v[160:163], v[214:217], v[4:7]
	v_mfma_f32_16x16x32_bf16 v[4:7], v[156:159], v[188:191], v[4:7]
	s_setprio 0
	s_barrier
; #define PG8_STAGE(bufoff, gbase, voff) do { _Pragma("unroll") for (int _i = 0; _i < 2; ++_i) \
;         __builtin_amdgcn_global_load_lds((const unsigned*)((const char*)(gbase) + (voff)[_i]), (PG8_LAS unsigned*)(lds + (bufoff) + ldsw + _i * 8192), 16, 0, 0); } while (0)
; #define PG8_LDA(dst, b, h) do { _Pragma("unroll") for (int m = 0; m < 4; ++m) _Pragma("unroll") for (int k = 0; k < 2; ++k) dst[m][k] = *(const PG8_LAS bf16x8*)(lds + PG8_SA(b, h) + aoff + m * 2048 + k * 1024); } while (0)
; #define PG8_LDB(dst, b, h) do { _Pragma("unroll") for (int n = 0; n < 2; ++n) _Pragma("unroll") for (int k = 0; k < 2; ++k) dst[n][k] = *(const PG8_LAS bf16x8*)(lds + PG8_SB(b, h) + boff + n * 2048 + k * 1024); } while (0)
; #define PG8_WAIT_V(n) asm volatile("s_waitcnt vmcnt(" #n ")" ::: "memory")
; #define PG8_WAIT_L(n) asm volatile("s_waitcnt lgkmcnt(" #n ")" ::: "memory")
; #define PG8_BAR __builtin_amdgcn_s_barrier()
; #define PG8_SCHED __builtin_amdgcn_sched_barrier(0)
; template <class Epi, class Sched, bool ALIGN_EPI = false, bool SP2 = false, bool I8 = false>
; __device__ __forceinline__ void gemm_phase(PG8_LAS unsigned char* lds, const Gemm g, const Sched& S, const Epi& E) {
;     ...
;             PG8_LDB(B0, 1, 0); PG8_LDB(B1, 1, 1); PG8_SCHED; PG8_LDA(At, 1, 0); PG8_STAGE(PG8_SA(0, 1), a2 + hstep, voffA);
;             PG8_WAIT_V(8); PG8_WAIT_L(0); PG8_BAR; PG8_MMA(0, 0, At, B0); PG8_MMA(0, 1, At, B1); PG8_BAR; PG8_SCHED;
	s_add_i32 s56, 0, 0x18000
	s_add_i32 s57, 0, 0x1c000
	v_add_u32_e32 v144, s56, v240
	v_add_u32_e32 v160, s57, v240
	ds_read_b128 v[124:127], v144
	ds_read_b128 v[128:131], v144 offset:1024
	ds_read_b128 v[132:135], v144 offset:2048
	ds_read_b128 v[144:147], v144 offset:3072
	ds_read_b128 v[148:151], v160
	ds_read_b128 v[152:155], v160 offset:1024
	ds_read_b128 v[156:159], v160 offset:2048
	ds_read_b128 v[160:163], v160 offset:3072
	s_add_u32 s22, s36, 0x2b0000
	s_addc_u32 s23, s37, 0
	s_mov_b32 m0, s44
	v_lshl_add_u64 v[226:227], s[22:23], 0, v[208:209]
	ds_read_b128 v[164:167], v242 offset:32768
	ds_read_b128 v[168:171], v242 offset:33792
	ds_read_b128 v[172:175], v242 offset:34816
	ds_read_b128 v[176:179], v242 offset:35840
	ds_read_b128 v[180:183], v242 offset:36864
	ds_read_b128 v[184:187], v242 offset:37888
	ds_read_b128 v[188:191], v242 offset:38912
	ds_read_b128 v[214:217], v242 offset:39936
	global_load_lds_dwordx4 v[226:227], off
	v_lshl_add_u64 v[226:227], s[22:23], 0, v[206:207]
	s_mov_b32 m0, s45
	s_nop 0
	global_load_lds_dwordx4 v[226:227], off
	s_waitcnt vmcnt(8)
	s_waitcnt lgkmcnt(0)
	s_barrier
	s_setprio 1
	s_waitcnt lgkmcnt(0)
	v_mfma_f32_16x16x32_bf16 v[140:143], v[124:127], v[164:167], v[140:143]
	v_mfma_f32_16x16x32_bf16 v[140:143], v[128:131], v[168:171], v[140:143]
	v_mfma_f32_16x16x32_bf16 v[112:115], v[128:131], v[176:179], v[112:115]
	v_mfma_f32_16x16x32_bf16 v[112:115], v[124:127], v[172:175], v[112:115]
	v_mfma_f32_16x16x32_bf16 v[96:99], v[124:127], v[180:183], v[96:99]
	v_mfma_f32_16x16x32_bf16 v[96:99], v[128:131], v[184:187], v[96:99]
	v_mfma_f32_16x16x32_bf16 v[80:83], v[128:131], v[214:217], v[80:83]
	v_mfma_f32_16x16x32_bf16 v[80:83], v[124:127], v[188:191], v[80:83]
	v_mfma_f32_16x16x32_bf16 v[136:139], v[132:135], v[164:167], v[136:139]
	v_mfma_f32_16x16x32_bf16 v[136:139], v[144:147], v[168:171], v[136:139]
	v_mfma_f32_16x16x32_bf16 v[108:111], v[144:147], v[176:179], v[108:111]
	v_mfma_f32_16x16x32_bf16 v[108:111], v[132:135], v[172:175], v[108:111]
	v_mfma_f32_16x16x32_bf16 v[92:95], v[132:135], v[180:183], v[92:95]
	v_mfma_f32_16x16x32_bf16 v[92:95], v[144:147], v[184:187], v[92:95]
	v_mfma_f32_16x16x32_bf16 v[76:79], v[144:147], v[214:217], v[76:79]
	v_mfma_f32_16x16x32_bf16 v[76:79], v[132:135], v[188:191], v[76:79]
	s_setprio 0
	s_setprio 1
	v_mfma_f32_16x16x32_bf16 v[120:123], v[148:151], v[164:167], v[120:123]
	v_mfma_f32_16x16x32_bf16 v[120:123], v[152:155], v[168:171], v[120:123]
	v_mfma_f32_16x16x32_bf16 v[104:107], v[152:155], v[176:179], v[104:107]
	v_mfma_f32_16x16x32_bf16 v[104:107], v[148:151], v[172:175], v[104:107]
	v_mfma_f32_16x16x32_bf16 v[88:91], v[148:151], v[180:183], v[88:91]
	v_mfma_f32_16x16x32_bf16 v[88:91], v[152:155], v[184:187], v[88:91]
	v_mfma_f32_16x16x32_bf16 v[72:75], v[152:155], v[214:217], v[72:75]
	v_mfma_f32_16x16x32_bf16 v[72:75], v[148:151], v[188:191], v[72:75]
	v_mfma_f32_16x16x32_bf16 v[116:119], v[156:159], v[164:167], v[116:119]
	v_mfma_f32_16x16x32_bf16 v[116:119], v[160:163], v[168:171], v[116:119]
	v_mfma_f32_16x16x32_bf16 v[100:103], v[160:163], v[176:179], v[100:103]
	v_mfma_f32_16x16x32_bf16 v[100:103], v[156:159], v[172:175], v[100:103]
	v_mfma_f32_16x16x32_bf16 v[84:87], v[156:159], v[180:183], v[84:87]
	v_mfma_f32_16x16x32_bf16 v[84:87], v[160:163], v[184:187], v[84:87]
	v_mfma_f32_16x16x32_bf16 v[68:71], v[160:163], v[214:217], v[68:71]
	v_mfma_f32_16x16x32_bf16 v[68:71], v[156:159], v[188:191], v[68:71]
	s_setprio 0
	s_barrier
; #define PG8_STAGE(bufoff, gbase, voff) do { _Pragma("unroll") for (int _i = 0; _i < 2; ++_i) \
;         __builtin_amdgcn_global_load_lds((const unsigned*)((const char*)(gbase) + (voff)[_i]), (PG8_LAS unsigned*)(lds + (bufoff) + ldsw + _i * 8192), 16, 0, 0); } while (0)
; #define PG8_LDA(dst, b, h) do { _Pragma("unroll") for (int m = 0; m < 4; ++m) _Pragma("unroll") for (int k = 0; k < 2; ++k) dst[m][k] = *(const PG8_LAS bf16x8*)(lds + PG8_SA(b, h) + aoff + m * 2048 + k * 1024); } while (0)
; #define PG8_WAIT_V(n) asm volatile("s_waitcnt vmcnt(" #n ")" ::: "memory")
; #define PG8_WAIT_L(n) asm volatile("s_waitcnt lgkmcnt(" #n ")" ::: "memory")
; #define PG8_BAR __builtin_amdgcn_s_barrier()
; #define PG8_SCHED __builtin_amdgcn_sched_barrier(0)
; template <class Epi, class Sched, bool ALIGN_EPI = false, bool SP2 = false, bool I8 = false>
; __device__ __forceinline__ void gemm_phase(PG8_LAS unsigned char* lds, const Gemm g, const Sched& S, const Epi& E) {
;     ...
;             PG8_LDA(At, 1, 1); PG8_STAGE(PG8_SB(1, 0), b3, voffB); PG8_STAGE(PG8_SB(1, 1), b3 + hstep, voffB); PG8_STAGE(PG8_SA(1, 0), a3, voffA);
;             PG8_WAIT_V(8); PG8_WAIT_L(0); PG8_BAR; PG8_MMA(1, 0, At, B0); PG8_MMA(1, 1, At, B1); PG8_BAR; PG8_SCHED;
	s_add_i32 s22, s56, s41
	v_lshl_add_u64 v[218:219], v[218:219], 0, s[84:85]
	s_mov_b32 m0, s22
	ds_read_b128 v[164:167], v242 offset:49152
	ds_read_b128 v[168:171], v242 offset:50176
	ds_read_b128 v[172:175], v242 offset:51200
	ds_read_b128 v[176:179], v242 offset:52224
	ds_read_b128 v[180:183], v242 offset:53248
	ds_read_b128 v[184:187], v242 offset:54272
	ds_read_b128 v[188:191], v242 offset:55296
	ds_read_b128 v[214:217], v242 offset:56320
	global_load_lds_dwordx4 v[218:219], off
	s_add_i32 m0, s22, 0x2000
	s_add_u32 s22, s26, 0x2b0080
	v_lshl_add_u64 v[218:219], v[220:221], 0, s[84:85]
	s_addc_u32 s23, s27, 0
	s_add_i32 s26, s57, s41
	global_load_lds_dwordx4 v[218:219], off
	v_lshl_add_u64 v[218:219], s[22:23], 0, v[2:3]
	s_mov_b32 m0, s26
	s_nop 0
	global_load_lds_dwordx4 v[218:219], off
	v_lshl_add_u64 v[218:219], s[22:23], 0, v[204:205]
	s_add_i32 m0, s26, 0x2000
	s_nop 0
	global_load_lds_dwordx4 v[218:219], off
	v_lshl_add_u64 v[218:219], v[222:223], 0, s[84:85]
	s_mov_b32 m0, s46
	s_nop 0
	global_load_lds_dwordx4 v[218:219], off
	v_lshl_add_u64 v[218:219], v[224:225], 0, s[84:85]
	s_mov_b32 m0, s47
	s_nop 0
	global_load_lds_dwordx4 v[218:219], off
	s_waitcnt vmcnt(8)
	s_waitcnt lgkmcnt(0)
	s_barrier
	s_setprio 1
	s_waitcnt lgkmcnt(0)
	v_mfma_f32_16x16x32_bf16 v[64:67], v[124:127], v[164:167], v[64:67]
	v_mfma_f32_16x16x32_bf16 v[64:67], v[128:131], v[168:171], v[64:67]
	v_mfma_f32_16x16x32_bf16 v[48:51], v[128:131], v[176:179], v[48:51]
	v_mfma_f32_16x16x32_bf16 v[48:51], v[124:127], v[172:175], v[48:51]
	v_mfma_f32_16x16x32_bf16 v[32:35], v[124:127], v[180:183], v[32:35]
	v_mfma_f32_16x16x32_bf16 v[32:35], v[128:131], v[184:187], v[32:35]
	v_mfma_f32_16x16x32_bf16 v[16:19], v[128:131], v[214:217], v[16:19]
	v_mfma_f32_16x16x32_bf16 v[16:19], v[124:127], v[188:191], v[16:19]
	v_mfma_f32_16x16x32_bf16 v[60:63], v[132:135], v[164:167], v[60:63]
	v_mfma_f32_16x16x32_bf16 v[60:63], v[144:147], v[168:171], v[60:63]
	v_mfma_f32_16x16x32_bf16 v[44:47], v[144:147], v[176:179], v[44:47]
	v_mfma_f32_16x16x32_bf16 v[44:47], v[132:135], v[172:175], v[44:47]
	v_mfma_f32_16x16x32_bf16 v[28:31], v[132:135], v[180:183], v[28:31]
	v_mfma_f32_16x16x32_bf16 v[28:31], v[144:147], v[184:187], v[28:31]
	v_mfma_f32_16x16x32_bf16 v[12:15], v[144:147], v[214:217], v[12:15]
	v_mfma_f32_16x16x32_bf16 v[12:15], v[132:135], v[188:191], v[12:15]
	s_setprio 0
	s_setprio 1
	v_mfma_f32_16x16x32_bf16 v[56:59], v[148:151], v[164:167], v[56:59]
	v_mfma_f32_16x16x32_bf16 v[56:59], v[152:155], v[168:171], v[56:59]
	v_mfma_f32_16x16x32_bf16 v[40:43], v[152:155], v[176:179], v[40:43]
	v_mfma_f32_16x16x32_bf16 v[40:43], v[148:151], v[172:175], v[40:43]
	v_mfma_f32_16x16x32_bf16 v[24:27], v[148:151], v[180:183], v[24:27]
	v_mfma_f32_16x16x32_bf16 v[24:27], v[152:155], v[184:187], v[24:27]
	v_mfma_f32_16x16x32_bf16 v[8:11], v[152:155], v[214:217], v[8:11]
	v_mfma_f32_16x16x32_bf16 v[8:11], v[148:151], v[188:191], v[8:11]
	v_mfma_f32_16x16x32_bf16 v[52:55], v[156:159], v[164:167], v[52:55]
	v_mfma_f32_16x16x32_bf16 v[52:55], v[160:163], v[168:171], v[52:55]
	v_mfma_f32_16x16x32_bf16 v[36:39], v[160:163], v[176:179], v[36:39]
	v_mfma_f32_16x16x32_bf16 v[36:39], v[156:159], v[172:175], v[36:39]
	v_mfma_f32_16x16x32_bf16 v[20:23], v[156:159], v[180:183], v[20:23]
	v_mfma_f32_16x16x32_bf16 v[20:23], v[160:163], v[184:187], v[20:23]
	v_mfma_f32_16x16x32_bf16 v[4:7], v[160:163], v[214:217], v[4:7]
	v_mfma_f32_16x16x32_bf16 v[4:7], v[156:159], v[188:191], v[4:7]
	s_setprio 0
	s_barrier
	s_add_i32 s55, s55, 2
	s_add_u32 s53, s53, 0x100
	s_addc_u32 s54, s54, 0
	s_cmpk_gt_u32 s55, 0xa9
	s_mov_b64 s[22:23], s[24:25]
	s_cbranch_scc0 .LBB0_1700
